# GEMM k-step: barrier after the first four MFMAs, LDS-DMA issues at MFMA 5,10,..,30
# speedup vs baseline: 1.0161x; 1.0007x over previous
.Lgy_nn_a:
	s_waitcnt vmcnt(6) lgkmcnt(0)
	v_add_u32_e32 v240, s61, v238
	v_add_u32_e32 v241, s61, v239
	s_setprio 1
	v_mfma_f32_16x16x32_bf16 v[2:5], v[162:165], v[130:133], 0
	v_mfma_f32_16x16x32_bf16 v[6:9], v[166:169], v[130:133], 0
	v_mfma_f32_16x16x32_bf16 v[10:13], v[170:173], v[130:133], 0
	v_mfma_f32_16x16x32_bf16 v[14:17], v[174:177], v[130:133], 0
	s_barrier
	v_mfma_f32_16x16x32_bf16 v[18:21], v[162:165], v[134:137], 0
	s_add_i32 m0, s60, s62
	v_mfma_f32_16x16x32_bf16 v[22:25], v[166:169], v[134:137], 0
	global_load_lds_dwordx4 v226, s[54:55]
	v_mfma_f32_16x16x32_bf16 v[26:29], v[170:173], v[134:137], 0
	v_mfma_f32_16x16x32_bf16 v[30:33], v[174:177], v[134:137], 0
	v_mfma_f32_16x16x32_bf16 v[34:37], v[162:165], v[138:141], 0
	ds_read_b128 v[210:213], v241 offset:0
	v_mfma_f32_16x16x32_bf16 v[38:41], v[166:169], v[138:141], 0
	ds_read_b128 v[214:217], v241 offset:256
	v_mfma_f32_16x16x32_bf16 v[42:45], v[170:173], v[138:141], 0
	ds_read_b128 v[218:221], v241 offset:512
	global_load_lds_dwordx4 v226, s[54:55] offset:1024
	v_mfma_f32_16x16x32_bf16 v[46:49], v[174:177], v[138:141], 0
	ds_read_b128 v[222:225], v241 offset:768
	v_mfma_f32_16x16x32_bf16 v[50:53], v[162:165], v[142:145], 0
	ds_read_b128 v[178:181], v240 offset:0
	v_mfma_f32_16x16x32_bf16 v[54:57], v[166:169], v[142:145], 0
	ds_read_b128 v[182:185], v240 offset:1024
	v_mfma_f32_16x16x32_bf16 v[58:61], v[170:173], v[142:145], 0
	ds_read_b128 v[186:189], v240 offset:2048
	v_mfma_f32_16x16x32_bf16 v[62:65], v[174:177], v[142:145], 0
	ds_read_b128 v[190:193], v240 offset:3072
	global_load_lds_dwordx4 v226, s[54:55] offset:2048
	v_mfma_f32_16x16x32_bf16 v[66:69], v[162:165], v[146:149], 0
	ds_read_b128 v[194:197], v240 offset:4096
	v_mfma_f32_16x16x32_bf16 v[70:73], v[166:169], v[146:149], 0
	ds_read_b128 v[198:201], v240 offset:5120
	v_mfma_f32_16x16x32_bf16 v[74:77], v[170:173], v[146:149], 0
	ds_read_b128 v[202:205], v240 offset:6144
	v_mfma_f32_16x16x32_bf16 v[78:81], v[174:177], v[146:149], 0
	ds_read_b128 v[206:209], v240 offset:7168
	v_mfma_f32_16x16x32_bf16 v[82:85], v[162:165], v[150:153], 0
	global_load_lds_dwordx4 v226, s[54:55] offset:3072
	v_mfma_f32_16x16x32_bf16 v[86:89], v[166:169], v[150:153], 0
	v_mfma_f32_16x16x32_bf16 v[90:93], v[170:173], v[150:153], 0
	v_mfma_f32_16x16x32_bf16 v[94:97], v[174:177], v[150:153], 0
	v_mfma_f32_16x16x32_bf16 v[98:101], v[162:165], v[154:157], 0
	s_add_i32 m0, s60, s63
	v_mfma_f32_16x16x32_bf16 v[102:105], v[166:169], v[154:157], 0
	global_load_lds_dwordx4 v230, s[56:57]
	v_mfma_f32_16x16x32_bf16 v[106:109], v[170:173], v[154:157], 0
	v_mfma_f32_16x16x32_bf16 v[110:113], v[174:177], v[154:157], 0
	v_mfma_f32_16x16x32_bf16 v[114:117], v[162:165], v[158:161], 0
	v_mfma_f32_16x16x32_bf16 v[118:121], v[166:169], v[158:161], 0
	v_mfma_f32_16x16x32_bf16 v[122:125], v[170:173], v[158:161], 0
	global_load_lds_dwordx4 v231, s[56:57] offset:1024
	v_mfma_f32_16x16x32_bf16 v[126:129], v[174:177], v[158:161], 0
	s_setprio 0
	s_add_i32 s60, s60, 0x6000
	s_cmp_eq_u32 s60, 0x12000
	s_cselect_b32 s60, 0, s60
	s_add_u32 s54, s54, s72
	s_addc_u32 s55, s55, 0
	s_add_u32 s56, s56, s73
	s_addc_u32 s57, s57, 0
	s_add_i32 s61, s61, 0x6000
	s_cmp_eq_u32 s61, 0x12000
	s_cselect_b32 s61, 0, s61
	s_waitcnt vmcnt(6) lgkmcnt(0)
	v_add_u32_e32 v240, s61, v238
	v_add_u32_e32 v241, s61, v239
	s_setprio 1
	v_mfma_f32_16x16x32_bf16 v[2:5], v[210:213], v[178:181], v[2:5]
	v_mfma_f32_16x16x32_bf16 v[6:9], v[214:217], v[178:181], v[6:9]
	v_mfma_f32_16x16x32_bf16 v[10:13], v[218:221], v[178:181], v[10:13]
	v_mfma_f32_16x16x32_bf16 v[14:17], v[222:225], v[178:181], v[14:17]
	s_barrier
	v_mfma_f32_16x16x32_bf16 v[18:21], v[210:213], v[182:185], v[18:21]
	s_add_i32 m0, s60, s62
	v_mfma_f32_16x16x32_bf16 v[22:25], v[214:217], v[182:185], v[22:25]
	global_load_lds_dwordx4 v226, s[54:55]
	v_mfma_f32_16x16x32_bf16 v[26:29], v[218:221], v[182:185], v[26:29]
	v_mfma_f32_16x16x32_bf16 v[30:33], v[222:225], v[182:185], v[30:33]
	v_mfma_f32_16x16x32_bf16 v[34:37], v[210:213], v[186:189], v[34:37]
	ds_read_b128 v[162:165], v241 offset:0
	v_mfma_f32_16x16x32_bf16 v[38:41], v[214:217], v[186:189], v[38:41]
	ds_read_b128 v[166:169], v241 offset:256
	v_mfma_f32_16x16x32_bf16 v[42:45], v[218:221], v[186:189], v[42:45]
	ds_read_b128 v[170:173], v241 offset:512
	global_load_lds_dwordx4 v226, s[54:55] offset:1024
	v_mfma_f32_16x16x32_bf16 v[46:49], v[222:225], v[186:189], v[46:49]
	ds_read_b128 v[174:177], v241 offset:768
	v_mfma_f32_16x16x32_bf16 v[50:53], v[210:213], v[190:193], v[50:53]
	ds_read_b128 v[130:133], v240 offset:0
	v_mfma_f32_16x16x32_bf16 v[54:57], v[214:217], v[190:193], v[54:57]
	ds_read_b128 v[134:137], v240 offset:1024
	v_mfma_f32_16x16x32_bf16 v[58:61], v[218:221], v[190:193], v[58:61]
	ds_read_b128 v[138:141], v240 offset:2048
	v_mfma_f32_16x16x32_bf16 v[62:65], v[222:225], v[190:193], v[62:65]
	ds_read_b128 v[142:145], v240 offset:3072
	global_load_lds_dwordx4 v226, s[54:55] offset:2048
	v_mfma_f32_16x16x32_bf16 v[66:69], v[210:213], v[194:197], v[66:69]
	ds_read_b128 v[146:149], v240 offset:4096
	v_mfma_f32_16x16x32_bf16 v[70:73], v[214:217], v[194:197], v[70:73]
	ds_read_b128 v[150:153], v240 offset:5120
	v_mfma_f32_16x16x32_bf16 v[74:77], v[218:221], v[194:197], v[74:77]
	ds_read_b128 v[154:157], v240 offset:6144
	v_mfma_f32_16x16x32_bf16 v[78:81], v[222:225], v[194:197], v[78:81]
	ds_read_b128 v[158:161], v240 offset:7168
	v_mfma_f32_16x16x32_bf16 v[82:85], v[210:213], v[198:201], v[82:85]
	global_load_lds_dwordx4 v226, s[54:55] offset:3072
	v_mfma_f32_16x16x32_bf16 v[86:89], v[214:217], v[198:201], v[86:89]
	v_mfma_f32_16x16x32_bf16 v[90:93], v[218:221], v[198:201], v[90:93]
	v_mfma_f32_16x16x32_bf16 v[94:97], v[222:225], v[198:201], v[94:97]
	v_mfma_f32_16x16x32_bf16 v[98:101], v[210:213], v[202:205], v[98:101]
	s_add_i32 m0, s60, s63
	v_mfma_f32_16x16x32_bf16 v[102:105], v[214:217], v[202:205], v[102:105]
	global_load_lds_dwordx4 v230, s[56:57]
	v_mfma_f32_16x16x32_bf16 v[106:109], v[218:221], v[202:205], v[106:109]
	v_mfma_f32_16x16x32_bf16 v[110:113], v[222:225], v[202:205], v[110:113]
	v_mfma_f32_16x16x32_bf16 v[114:117], v[210:213], v[206:209], v[114:117]
	v_mfma_f32_16x16x32_bf16 v[118:121], v[214:217], v[206:209], v[118:121]
	v_mfma_f32_16x16x32_bf16 v[122:125], v[218:221], v[206:209], v[122:125]
	global_load_lds_dwordx4 v231, s[56:57] offset:1024
	v_mfma_f32_16x16x32_bf16 v[126:129], v[222:225], v[206:209], v[126:129]
	s_setprio 0
	s_add_i32 s60, s60, 0x6000
	s_cmp_eq_u32 s60, 0x12000
	s_cselect_b32 s60, 0, s60
	s_add_u32 s54, s54, s72
	s_addc_u32 s55, s55, 0
	s_add_u32 s56, s56, s73
	s_addc_u32 s57, s57, 0
	s_add_i32 s61, s61, 0x6000
	s_cmp_eq_u32 s61, 0x12000
	s_cselect_b32 s61, 0, s61
	s_branch .Lgy_main

.Lgy_nn_b:
	s_waitcnt vmcnt(22) lgkmcnt(0)
	v_add_u32_e32 v240, s61, v238
	v_add_u32_e32 v241, s61, v239
	s_setprio 1
	v_mfma_f32_16x16x32_bf16 v[2:5], v[162:165], v[130:133], 0
	v_mfma_f32_16x16x32_bf16 v[6:9], v[166:169], v[130:133], 0
	v_mfma_f32_16x16x32_bf16 v[10:13], v[170:173], v[130:133], 0
	v_mfma_f32_16x16x32_bf16 v[14:17], v[174:177], v[130:133], 0
	s_barrier
	v_mfma_f32_16x16x32_bf16 v[18:21], v[162:165], v[134:137], 0
	s_add_i32 m0, s60, s62
	v_mfma_f32_16x16x32_bf16 v[22:25], v[166:169], v[134:137], 0
	global_load_lds_dwordx4 v226, s[54:55]
	v_mfma_f32_16x16x32_bf16 v[26:29], v[170:173], v[134:137], 0
	v_mfma_f32_16x16x32_bf16 v[30:33], v[174:177], v[134:137], 0
	v_mfma_f32_16x16x32_bf16 v[34:37], v[162:165], v[138:141], 0
	ds_read_b128 v[210:213], v241 offset:0
	v_mfma_f32_16x16x32_bf16 v[38:41], v[166:169], v[138:141], 0
	ds_read_b128 v[214:217], v241 offset:256
	v_mfma_f32_16x16x32_bf16 v[42:45], v[170:173], v[138:141], 0
	ds_read_b128 v[218:221], v241 offset:512
	global_load_lds_dwordx4 v226, s[54:55] offset:1024
	v_mfma_f32_16x16x32_bf16 v[46:49], v[174:177], v[138:141], 0
	ds_read_b128 v[222:225], v241 offset:768
	v_mfma_f32_16x16x32_bf16 v[50:53], v[162:165], v[142:145], 0
	ds_read_b128 v[178:181], v240 offset:0
	v_mfma_f32_16x16x32_bf16 v[54:57], v[166:169], v[142:145], 0
	ds_read_b128 v[182:185], v240 offset:1024
	v_mfma_f32_16x16x32_bf16 v[58:61], v[170:173], v[142:145], 0
	ds_read_b128 v[186:189], v240 offset:2048
	v_mfma_f32_16x16x32_bf16 v[62:65], v[174:177], v[142:145], 0
	ds_read_b128 v[190:193], v240 offset:3072
	global_load_lds_dwordx4 v226, s[54:55] offset:2048
	v_mfma_f32_16x16x32_bf16 v[66:69], v[162:165], v[146:149], 0
	ds_read_b128 v[194:197], v240 offset:4096
	v_mfma_f32_16x16x32_bf16 v[70:73], v[166:169], v[146:149], 0
	ds_read_b128 v[198:201], v240 offset:5120
	v_mfma_f32_16x16x32_bf16 v[74:77], v[170:173], v[146:149], 0
	ds_read_b128 v[202:205], v240 offset:6144
	v_mfma_f32_16x16x32_bf16 v[78:81], v[174:177], v[146:149], 0
	ds_read_b128 v[206:209], v240 offset:7168
	v_mfma_f32_16x16x32_bf16 v[82:85], v[162:165], v[150:153], 0
	global_load_lds_dwordx4 v226, s[54:55] offset:3072
	v_mfma_f32_16x16x32_bf16 v[86:89], v[166:169], v[150:153], 0
	v_mfma_f32_16x16x32_bf16 v[90:93], v[170:173], v[150:153], 0
	v_mfma_f32_16x16x32_bf16 v[94:97], v[174:177], v[150:153], 0
	v_mfma_f32_16x16x32_bf16 v[98:101], v[162:165], v[154:157], 0
	s_add_i32 m0, s60, s63
	v_mfma_f32_16x16x32_bf16 v[102:105], v[166:169], v[154:157], 0
	global_load_lds_dwordx4 v230, s[56:57]
	v_mfma_f32_16x16x32_bf16 v[106:109], v[170:173], v[154:157], 0
	v_mfma_f32_16x16x32_bf16 v[110:113], v[174:177], v[154:157], 0
	v_mfma_f32_16x16x32_bf16 v[114:117], v[162:165], v[158:161], 0
	v_mfma_f32_16x16x32_bf16 v[118:121], v[166:169], v[158:161], 0
	v_mfma_f32_16x16x32_bf16 v[122:125], v[170:173], v[158:161], 0
	global_load_lds_dwordx4 v231, s[56:57] offset:1024
	v_mfma_f32_16x16x32_bf16 v[126:129], v[174:177], v[158:161], 0
	s_setprio 0
	s_add_i32 s60, s60, 0x6000
	s_cmp_eq_u32 s60, 0x12000
	s_cselect_b32 s60, 0, s60
	s_add_u32 s54, s54, s72
	s_addc_u32 s55, s55, 0
	s_add_u32 s56, s56, s73
	s_addc_u32 s57, s57, 0
	s_add_i32 s61, s61, 0x6000
	s_cmp_eq_u32 s61, 0x12000
	s_cselect_b32 s61, 0, s61
	s_waitcnt vmcnt(22) lgkmcnt(0)
	v_add_u32_e32 v240, s61, v238
	v_add_u32_e32 v241, s61, v239
	s_setprio 1
	v_mfma_f32_16x16x32_bf16 v[2:5], v[210:213], v[178:181], v[2:5]
	v_mfma_f32_16x16x32_bf16 v[6:9], v[214:217], v[178:181], v[6:9]
	v_mfma_f32_16x16x32_bf16 v[10:13], v[218:221], v[178:181], v[10:13]
	v_mfma_f32_16x16x32_bf16 v[14:17], v[222:225], v[178:181], v[14:17]
	s_barrier
	v_mfma_f32_16x16x32_bf16 v[18:21], v[210:213], v[182:185], v[18:21]
	s_add_i32 m0, s60, s62
	v_mfma_f32_16x16x32_bf16 v[22:25], v[214:217], v[182:185], v[22:25]
	global_load_lds_dwordx4 v226, s[54:55]
	v_mfma_f32_16x16x32_bf16 v[26:29], v[218:221], v[182:185], v[26:29]
	v_mfma_f32_16x16x32_bf16 v[30:33], v[222:225], v[182:185], v[30:33]
	v_mfma_f32_16x16x32_bf16 v[34:37], v[210:213], v[186:189], v[34:37]
	ds_read_b128 v[162:165], v241 offset:0
	v_mfma_f32_16x16x32_bf16 v[38:41], v[214:217], v[186:189], v[38:41]
	ds_read_b128 v[166:169], v241 offset:256
	v_mfma_f32_16x16x32_bf16 v[42:45], v[218:221], v[186:189], v[42:45]
	ds_read_b128 v[170:173], v241 offset:512
	global_load_lds_dwordx4 v226, s[54:55] offset:1024
	v_mfma_f32_16x16x32_bf16 v[46:49], v[222:225], v[186:189], v[46:49]
	ds_read_b128 v[174:177], v241 offset:768
	v_mfma_f32_16x16x32_bf16 v[50:53], v[210:213], v[190:193], v[50:53]
	ds_read_b128 v[130:133], v240 offset:0
	v_mfma_f32_16x16x32_bf16 v[54:57], v[214:217], v[190:193], v[54:57]
	ds_read_b128 v[134:137], v240 offset:1024
	v_mfma_f32_16x16x32_bf16 v[58:61], v[218:221], v[190:193], v[58:61]
	ds_read_b128 v[138:141], v240 offset:2048
	v_mfma_f32_16x16x32_bf16 v[62:65], v[222:225], v[190:193], v[62:65]
	ds_read_b128 v[142:145], v240 offset:3072
	global_load_lds_dwordx4 v226, s[54:55] offset:2048
	v_mfma_f32_16x16x32_bf16 v[66:69], v[210:213], v[194:197], v[66:69]
	ds_read_b128 v[146:149], v240 offset:4096
	v_mfma_f32_16x16x32_bf16 v[70:73], v[214:217], v[194:197], v[70:73]
	ds_read_b128 v[150:153], v240 offset:5120
	v_mfma_f32_16x16x32_bf16 v[74:77], v[218:221], v[194:197], v[74:77]
	ds_read_b128 v[154:157], v240 offset:6144
	v_mfma_f32_16x16x32_bf16 v[78:81], v[222:225], v[194:197], v[78:81]
	ds_read_b128 v[158:161], v240 offset:7168
	v_mfma_f32_16x16x32_bf16 v[82:85], v[210:213], v[198:201], v[82:85]
	global_load_lds_dwordx4 v226, s[54:55] offset:3072
	v_mfma_f32_16x16x32_bf16 v[86:89], v[214:217], v[198:201], v[86:89]
	v_mfma_f32_16x16x32_bf16 v[90:93], v[218:221], v[198:201], v[90:93]
	v_mfma_f32_16x16x32_bf16 v[94:97], v[222:225], v[198:201], v[94:97]
	v_mfma_f32_16x16x32_bf16 v[98:101], v[210:213], v[202:205], v[98:101]
	s_add_i32 m0, s60, s63
	v_mfma_f32_16x16x32_bf16 v[102:105], v[214:217], v[202:205], v[102:105]
	global_load_lds_dwordx4 v230, s[56:57]
	v_mfma_f32_16x16x32_bf16 v[106:109], v[218:221], v[202:205], v[106:109]
	v_mfma_f32_16x16x32_bf16 v[110:113], v[222:225], v[202:205], v[110:113]
	v_mfma_f32_16x16x32_bf16 v[114:117], v[210:213], v[206:209], v[114:117]
	v_mfma_f32_16x16x32_bf16 v[118:121], v[214:217], v[206:209], v[118:121]
	v_mfma_f32_16x16x32_bf16 v[122:125], v[218:221], v[206:209], v[122:125]
	global_load_lds_dwordx4 v231, s[56:57] offset:1024
	v_mfma_f32_16x16x32_bf16 v[126:129], v[222:225], v[206:209], v[126:129]
	s_setprio 0
	s_add_i32 s60, s60, 0x6000
	s_cmp_eq_u32 s60, 0x12000
	s_cselect_b32 s60, 0, s60
	s_add_u32 s54, s54, s72
	s_addc_u32 s55, s55, 0
	s_add_u32 s56, s56, s73
	s_addc_u32 s57, s57, 0
	s_add_i32 s61, s61, 0x6000
	s_cmp_eq_u32 s61, 0x12000
	s_cselect_b32 s61, 0, s61

.Lgy_kloop:
	s_waitcnt vmcnt(6) lgkmcnt(0)
	v_add_u32_e32 v240, s61, v238
	v_add_u32_e32 v241, s61, v239
	s_setprio 1
	v_mfma_f32_16x16x32_bf16 v[2:5], v[162:165], v[130:133], v[2:5]
	v_mfma_f32_16x16x32_bf16 v[6:9], v[166:169], v[130:133], v[6:9]
	v_mfma_f32_16x16x32_bf16 v[10:13], v[170:173], v[130:133], v[10:13]
	v_mfma_f32_16x16x32_bf16 v[14:17], v[174:177], v[130:133], v[14:17]
	s_barrier
	v_mfma_f32_16x16x32_bf16 v[18:21], v[162:165], v[134:137], v[18:21]
	s_add_i32 m0, s60, s62
	v_mfma_f32_16x16x32_bf16 v[22:25], v[166:169], v[134:137], v[22:25]
	global_load_lds_dwordx4 v226, s[54:55]
	v_mfma_f32_16x16x32_bf16 v[26:29], v[170:173], v[134:137], v[26:29]
	v_mfma_f32_16x16x32_bf16 v[30:33], v[174:177], v[134:137], v[30:33]
	v_mfma_f32_16x16x32_bf16 v[34:37], v[162:165], v[138:141], v[34:37]
	ds_read_b128 v[210:213], v241 offset:0
	v_mfma_f32_16x16x32_bf16 v[38:41], v[166:169], v[138:141], v[38:41]
	ds_read_b128 v[214:217], v241 offset:256
	v_mfma_f32_16x16x32_bf16 v[42:45], v[170:173], v[138:141], v[42:45]
	ds_read_b128 v[218:221], v241 offset:512
	global_load_lds_dwordx4 v226, s[54:55] offset:1024
	v_mfma_f32_16x16x32_bf16 v[46:49], v[174:177], v[138:141], v[46:49]
	ds_read_b128 v[222:225], v241 offset:768
	v_mfma_f32_16x16x32_bf16 v[50:53], v[162:165], v[142:145], v[50:53]
	ds_read_b128 v[178:181], v240 offset:0
	v_mfma_f32_16x16x32_bf16 v[54:57], v[166:169], v[142:145], v[54:57]
	ds_read_b128 v[182:185], v240 offset:1024
	v_mfma_f32_16x16x32_bf16 v[58:61], v[170:173], v[142:145], v[58:61]
	ds_read_b128 v[186:189], v240 offset:2048
	v_mfma_f32_16x16x32_bf16 v[62:65], v[174:177], v[142:145], v[62:65]
	ds_read_b128 v[190:193], v240 offset:3072
	global_load_lds_dwordx4 v226, s[54:55] offset:2048
	v_mfma_f32_16x16x32_bf16 v[66:69], v[162:165], v[146:149], v[66:69]
	ds_read_b128 v[194:197], v240 offset:4096
	v_mfma_f32_16x16x32_bf16 v[70:73], v[166:169], v[146:149], v[70:73]
	ds_read_b128 v[198:201], v240 offset:5120
	v_mfma_f32_16x16x32_bf16 v[74:77], v[170:173], v[146:149], v[74:77]
	ds_read_b128 v[202:205], v240 offset:6144
	v_mfma_f32_16x16x32_bf16 v[78:81], v[174:177], v[146:149], v[78:81]
	ds_read_b128 v[206:209], v240 offset:7168
	v_mfma_f32_16x16x32_bf16 v[82:85], v[162:165], v[150:153], v[82:85]
	global_load_lds_dwordx4 v226, s[54:55] offset:3072
	v_mfma_f32_16x16x32_bf16 v[86:89], v[166:169], v[150:153], v[86:89]
	v_mfma_f32_16x16x32_bf16 v[90:93], v[170:173], v[150:153], v[90:93]
	v_mfma_f32_16x16x32_bf16 v[94:97], v[174:177], v[150:153], v[94:97]
	v_mfma_f32_16x16x32_bf16 v[98:101], v[162:165], v[154:157], v[98:101]
	s_add_i32 m0, s60, s63
	v_mfma_f32_16x16x32_bf16 v[102:105], v[166:169], v[154:157], v[102:105]
	global_load_lds_dwordx4 v230, s[56:57]
	v_mfma_f32_16x16x32_bf16 v[106:109], v[170:173], v[154:157], v[106:109]
	v_mfma_f32_16x16x32_bf16 v[110:113], v[174:177], v[154:157], v[110:113]
	v_mfma_f32_16x16x32_bf16 v[114:117], v[162:165], v[158:161], v[114:117]
	v_mfma_f32_16x16x32_bf16 v[118:121], v[166:169], v[158:161], v[118:121]
	v_mfma_f32_16x16x32_bf16 v[122:125], v[170:173], v[158:161], v[122:125]
	global_load_lds_dwordx4 v231, s[56:57] offset:1024
	v_mfma_f32_16x16x32_bf16 v[126:129], v[174:177], v[158:161], v[126:129]
	s_setprio 0
	s_add_i32 s60, s60, 0x6000
	s_cmp_eq_u32 s60, 0x12000
	s_cselect_b32 s60, 0, s60
	s_add_u32 s54, s54, s72
	s_addc_u32 s55, s55, 0
	s_add_u32 s56, s56, s73
	s_addc_u32 s57, s57, 0
	s_add_i32 s61, s61, 0x6000
	s_cmp_eq_u32 s61, 0x12000
	s_cselect_b32 s61, 0, s61
	s_waitcnt vmcnt(6) lgkmcnt(0)
	v_add_u32_e32 v240, s61, v238
	v_add_u32_e32 v241, s61, v239
	s_setprio 1
	v_mfma_f32_16x16x32_bf16 v[2:5], v[210:213], v[178:181], v[2:5]
	v_mfma_f32_16x16x32_bf16 v[6:9], v[214:217], v[178:181], v[6:9]
	v_mfma_f32_16x16x32_bf16 v[10:13], v[218:221], v[178:181], v[10:13]
	v_mfma_f32_16x16x32_bf16 v[14:17], v[222:225], v[178:181], v[14:17]
	s_barrier
	v_mfma_f32_16x16x32_bf16 v[18:21], v[210:213], v[182:185], v[18:21]
	s_add_i32 m0, s60, s62
	v_mfma_f32_16x16x32_bf16 v[22:25], v[214:217], v[182:185], v[22:25]
	global_load_lds_dwordx4 v226, s[54:55]
	v_mfma_f32_16x16x32_bf16 v[26:29], v[218:221], v[182:185], v[26:29]
	v_mfma_f32_16x16x32_bf16 v[30:33], v[222:225], v[182:185], v[30:33]
	v_mfma_f32_16x16x32_bf16 v[34:37], v[210:213], v[186:189], v[34:37]
	ds_read_b128 v[162:165], v241 offset:0
	v_mfma_f32_16x16x32_bf16 v[38:41], v[214:217], v[186:189], v[38:41]
	ds_read_b128 v[166:169], v241 offset:256
	v_mfma_f32_16x16x32_bf16 v[42:45], v[218:221], v[186:189], v[42:45]
	ds_read_b128 v[170:173], v241 offset:512
	global_load_lds_dwordx4 v226, s[54:55] offset:1024
	v_mfma_f32_16x16x32_bf16 v[46:49], v[222:225], v[186:189], v[46:49]
	ds_read_b128 v[174:177], v241 offset:768
	v_mfma_f32_16x16x32_bf16 v[50:53], v[210:213], v[190:193], v[50:53]
	ds_read_b128 v[130:133], v240 offset:0
	v_mfma_f32_16x16x32_bf16 v[54:57], v[214:217], v[190:193], v[54:57]
	ds_read_b128 v[134:137], v240 offset:1024
	v_mfma_f32_16x16x32_bf16 v[58:61], v[218:221], v[190:193], v[58:61]
	ds_read_b128 v[138:141], v240 offset:2048
	v_mfma_f32_16x16x32_bf16 v[62:65], v[222:225], v[190:193], v[62:65]
	ds_read_b128 v[142:145], v240 offset:3072
	global_load_lds_dwordx4 v226, s[54:55] offset:2048
	v_mfma_f32_16x16x32_bf16 v[66:69], v[210:213], v[194:197], v[66:69]
	ds_read_b128 v[146:149], v240 offset:4096
	v_mfma_f32_16x16x32_bf16 v[70:73], v[214:217], v[194:197], v[70:73]
	ds_read_b128 v[150:153], v240 offset:5120
	v_mfma_f32_16x16x32_bf16 v[74:77], v[218:221], v[194:197], v[74:77]
	ds_read_b128 v[154:157], v240 offset:6144
	v_mfma_f32_16x16x32_bf16 v[78:81], v[222:225], v[194:197], v[78:81]
	ds_read_b128 v[158:161], v240 offset:7168
	v_mfma_f32_16x16x32_bf16 v[82:85], v[210:213], v[198:201], v[82:85]
	global_load_lds_dwordx4 v226, s[54:55] offset:3072
	v_mfma_f32_16x16x32_bf16 v[86:89], v[214:217], v[198:201], v[86:89]
	v_mfma_f32_16x16x32_bf16 v[90:93], v[218:221], v[198:201], v[90:93]
	v_mfma_f32_16x16x32_bf16 v[94:97], v[222:225], v[198:201], v[94:97]
	v_mfma_f32_16x16x32_bf16 v[98:101], v[210:213], v[202:205], v[98:101]
	s_add_i32 m0, s60, s63
	v_mfma_f32_16x16x32_bf16 v[102:105], v[214:217], v[202:205], v[102:105]
	global_load_lds_dwordx4 v230, s[56:57]
	v_mfma_f32_16x16x32_bf16 v[106:109], v[218:221], v[202:205], v[106:109]
	v_mfma_f32_16x16x32_bf16 v[110:113], v[222:225], v[202:205], v[110:113]
	v_mfma_f32_16x16x32_bf16 v[114:117], v[210:213], v[206:209], v[114:117]
	v_mfma_f32_16x16x32_bf16 v[118:121], v[214:217], v[206:209], v[118:121]
	v_mfma_f32_16x16x32_bf16 v[122:125], v[218:221], v[206:209], v[122:125]
	global_load_lds_dwordx4 v231, s[56:57] offset:1024
	v_mfma_f32_16x16x32_bf16 v[126:129], v[222:225], v[206:209], v[126:129]
	s_setprio 0
	s_add_i32 s60, s60, 0x6000
	s_cmp_eq_u32 s60, 0x12000
	s_cselect_b32 s60, 0, s60
	s_add_u32 s54, s54, s72
	s_addc_u32 s55, s55, 0
	s_add_u32 s56, s56, s73
	s_addc_u32 s57, s57, 0
	s_add_i32 s61, s61, 0x6000
	s_cmp_eq_u32 s61, 0x12000
	s_cselect_b32 s61, 0, s61
	s_add_i32 s40, s40, -1
	s_cmp_lg_u32 s40, 0
	s_cbranch_scc1 .Lgy_kloop
.Lgy_kdone:
	s_cmp_eq_u32 s37, 0
	s_cbranch_scc1 .Lgy_tail_last
	s_waitcnt vmcnt(6) lgkmcnt(0)
	v_add_u32_e32 v240, s61, v238
	v_add_u32_e32 v241, s61, v239
	s_setprio 1
	v_mfma_f32_16x16x32_bf16 v[2:5], v[162:165], v[130:133], v[2:5]
	v_mfma_f32_16x16x32_bf16 v[6:9], v[166:169], v[130:133], v[6:9]
	v_mfma_f32_16x16x32_bf16 v[10:13], v[170:173], v[130:133], v[10:13]
	v_mfma_f32_16x16x32_bf16 v[14:17], v[174:177], v[130:133], v[14:17]
	s_barrier
	v_mfma_f32_16x16x32_bf16 v[18:21], v[162:165], v[134:137], v[18:21]
	s_add_i32 m0, s60, s62
	v_mfma_f32_16x16x32_bf16 v[22:25], v[166:169], v[134:137], v[22:25]
	global_load_lds_dwordx4 v226, s[54:55]
	v_mfma_f32_16x16x32_bf16 v[26:29], v[170:173], v[134:137], v[26:29]
	v_mfma_f32_16x16x32_bf16 v[30:33], v[174:177], v[134:137], v[30:33]
	v_mfma_f32_16x16x32_bf16 v[34:37], v[162:165], v[138:141], v[34:37]
	ds_read_b128 v[210:213], v241 offset:0
	v_mfma_f32_16x16x32_bf16 v[38:41], v[166:169], v[138:141], v[38:41]
	ds_read_b128 v[214:217], v241 offset:256
	v_mfma_f32_16x16x32_bf16 v[42:45], v[170:173], v[138:141], v[42:45]
	ds_read_b128 v[218:221], v241 offset:512
	global_load_lds_dwordx4 v226, s[54:55] offset:1024
	v_mfma_f32_16x16x32_bf16 v[46:49], v[174:177], v[138:141], v[46:49]
	ds_read_b128 v[222:225], v241 offset:768
	v_mfma_f32_16x16x32_bf16 v[50:53], v[162:165], v[142:145], v[50:53]
	ds_read_b128 v[178:181], v240 offset:0
	v_mfma_f32_16x16x32_bf16 v[54:57], v[166:169], v[142:145], v[54:57]
	ds_read_b128 v[182:185], v240 offset:1024
	v_mfma_f32_16x16x32_bf16 v[58:61], v[170:173], v[142:145], v[58:61]
	ds_read_b128 v[186:189], v240 offset:2048
	v_mfma_f32_16x16x32_bf16 v[62:65], v[174:177], v[142:145], v[62:65]
	ds_read_b128 v[190:193], v240 offset:3072
	global_load_lds_dwordx4 v226, s[54:55] offset:2048
	v_mfma_f32_16x16x32_bf16 v[66:69], v[162:165], v[146:149], v[66:69]
	ds_read_b128 v[194:197], v240 offset:4096
	v_mfma_f32_16x16x32_bf16 v[70:73], v[166:169], v[146:149], v[70:73]
	ds_read_b128 v[198:201], v240 offset:5120
	v_mfma_f32_16x16x32_bf16 v[74:77], v[170:173], v[146:149], v[74:77]
	ds_read_b128 v[202:205], v240 offset:6144
	v_mfma_f32_16x16x32_bf16 v[78:81], v[174:177], v[146:149], v[78:81]
	ds_read_b128 v[206:209], v240 offset:7168
	v_mfma_f32_16x16x32_bf16 v[82:85], v[162:165], v[150:153], v[82:85]
	global_load_lds_dwordx4 v226, s[54:55] offset:3072
	v_mfma_f32_16x16x32_bf16 v[86:89], v[166:169], v[150:153], v[86:89]
	v_mfma_f32_16x16x32_bf16 v[90:93], v[170:173], v[150:153], v[90:93]
	v_mfma_f32_16x16x32_bf16 v[94:97], v[174:177], v[150:153], v[94:97]
	v_mfma_f32_16x16x32_bf16 v[98:101], v[162:165], v[154:157], v[98:101]
	s_add_i32 m0, s60, s63
	v_mfma_f32_16x16x32_bf16 v[102:105], v[166:169], v[154:157], v[102:105]
	global_load_lds_dwordx4 v230, s[56:57]
	v_mfma_f32_16x16x32_bf16 v[106:109], v[170:173], v[154:157], v[106:109]
	v_mfma_f32_16x16x32_bf16 v[110:113], v[174:177], v[154:157], v[110:113]
	v_mfma_f32_16x16x32_bf16 v[114:117], v[162:165], v[158:161], v[114:117]
	v_mfma_f32_16x16x32_bf16 v[118:121], v[166:169], v[158:161], v[118:121]
	v_mfma_f32_16x16x32_bf16 v[122:125], v[170:173], v[158:161], v[122:125]
	global_load_lds_dwordx4 v231, s[56:57] offset:1024
	v_mfma_f32_16x16x32_bf16 v[126:129], v[174:177], v[158:161], v[126:129]
	s_setprio 0
	s_add_i32 s60, s60, 0x6000
	s_cmp_eq_u32 s60, 0x12000
	s_cselect_b32 s60, 0, s60
	s_add_u32 s54, s54, s72
	s_addc_u32 s55, s55, 0
	s_add_u32 s56, s56, s73
	s_addc_u32 s57, s57, 0
	s_add_i32 s61, s61, 0x6000
	s_cmp_eq_u32 s61, 0x12000
	s_cselect_b32 s61, 0, s61
	v_mov_b32_e32 v226, v232
	v_mov_b32_e32 v230, v236
	v_mov_b32_e32 v231, v237
	s_mov_b64 s[54:55], s[48:49]
	s_mov_b64 s[56:57], s[50:51]
	s_waitcnt vmcnt(6) lgkmcnt(0)
	v_add_u32_e32 v240, s61, v238
	v_add_u32_e32 v241, s61, v239
	s_setprio 1
	v_mfma_f32_16x16x32_bf16 v[2:5], v[210:213], v[178:181], v[2:5]
	v_mfma_f32_16x16x32_bf16 v[6:9], v[214:217], v[178:181], v[6:9]
	v_mfma_f32_16x16x32_bf16 v[10:13], v[218:221], v[178:181], v[10:13]
	v_mfma_f32_16x16x32_bf16 v[14:17], v[222:225], v[178:181], v[14:17]
	s_barrier
	v_mfma_f32_16x16x32_bf16 v[18:21], v[210:213], v[182:185], v[18:21]
	s_add_i32 m0, s60, s62
	v_mfma_f32_16x16x32_bf16 v[22:25], v[214:217], v[182:185], v[22:25]
	global_load_lds_dwordx4 v226, s[54:55]
	v_mfma_f32_16x16x32_bf16 v[26:29], v[218:221], v[182:185], v[26:29]
	v_mfma_f32_16x16x32_bf16 v[30:33], v[222:225], v[182:185], v[30:33]
	v_mfma_f32_16x16x32_bf16 v[34:37], v[210:213], v[186:189], v[34:37]
	ds_read_b128 v[162:165], v241 offset:0
	v_mfma_f32_16x16x32_bf16 v[38:41], v[214:217], v[186:189], v[38:41]
	ds_read_b128 v[166:169], v241 offset:256
	v_mfma_f32_16x16x32_bf16 v[42:45], v[218:221], v[186:189], v[42:45]
	ds_read_b128 v[170:173], v241 offset:512
	global_load_lds_dwordx4 v226, s[54:55] offset:1024
	v_mfma_f32_16x16x32_bf16 v[46:49], v[222:225], v[186:189], v[46:49]
	ds_read_b128 v[174:177], v241 offset:768
	v_mfma_f32_16x16x32_bf16 v[50:53], v[210:213], v[190:193], v[50:53]
	ds_read_b128 v[130:133], v240 offset:0
	v_mfma_f32_16x16x32_bf16 v[54:57], v[214:217], v[190:193], v[54:57]
	ds_read_b128 v[134:137], v240 offset:1024
	v_mfma_f32_16x16x32_bf16 v[58:61], v[218:221], v[190:193], v[58:61]
	ds_read_b128 v[138:141], v240 offset:2048
	v_mfma_f32_16x16x32_bf16 v[62:65], v[222:225], v[190:193], v[62:65]
	ds_read_b128 v[142:145], v240 offset:3072
	global_load_lds_dwordx4 v226, s[54:55] offset:2048
	v_mfma_f32_16x16x32_bf16 v[66:69], v[210:213], v[194:197], v[66:69]
	ds_read_b128 v[146:149], v240 offset:4096
	v_mfma_f32_16x16x32_bf16 v[70:73], v[214:217], v[194:197], v[70:73]
	ds_read_b128 v[150:153], v240 offset:5120
	v_mfma_f32_16x16x32_bf16 v[74:77], v[218:221], v[194:197], v[74:77]
	ds_read_b128 v[154:157], v240 offset:6144
	v_mfma_f32_16x16x32_bf16 v[78:81], v[222:225], v[194:197], v[78:81]
	ds_read_b128 v[158:161], v240 offset:7168
	v_mfma_f32_16x16x32_bf16 v[82:85], v[210:213], v[198:201], v[82:85]
	global_load_lds_dwordx4 v226, s[54:55] offset:3072
	v_mfma_f32_16x16x32_bf16 v[86:89], v[214:217], v[198:201], v[86:89]
	v_mfma_f32_16x16x32_bf16 v[90:93], v[218:221], v[198:201], v[90:93]
	v_mfma_f32_16x16x32_bf16 v[94:97], v[222:225], v[198:201], v[94:97]
	v_mfma_f32_16x16x32_bf16 v[98:101], v[210:213], v[202:205], v[98:101]
	s_add_i32 m0, s60, s63
	v_mfma_f32_16x16x32_bf16 v[102:105], v[214:217], v[202:205], v[102:105]
	global_load_lds_dwordx4 v230, s[56:57]
	v_mfma_f32_16x16x32_bf16 v[106:109], v[218:221], v[202:205], v[106:109]
	v_mfma_f32_16x16x32_bf16 v[110:113], v[222:225], v[202:205], v[110:113]
	v_mfma_f32_16x16x32_bf16 v[114:117], v[210:213], v[206:209], v[114:117]
	v_mfma_f32_16x16x32_bf16 v[118:121], v[214:217], v[206:209], v[118:121]
	v_mfma_f32_16x16x32_bf16 v[122:125], v[218:221], v[206:209], v[122:125]
	global_load_lds_dwordx4 v231, s[56:57] offset:1024
	v_mfma_f32_16x16x32_bf16 v[126:129], v[222:225], v[206:209], v[126:129]
	s_setprio 0
	s_add_i32 s60, s60, 0x6000
	s_cmp_eq_u32 s60, 0x12000
	s_cselect_b32 s60, 0, s60
	s_add_u32 s54, s54, s72
	s_addc_u32 s55, s55, 0
	s_add_u32 s56, s56, s73
	s_addc_u32 s57, s57, 0
	s_add_i32 s61, s61, 0x6000
	s_cmp_eq_u32 s61, 0x12000
	s_cselect_b32 s61, 0, s61
	s_waitcnt vmcnt(6) lgkmcnt(0)
	v_add_u32_e32 v240, s61, v238
	v_add_u32_e32 v241, s61, v239
	s_setprio 1
	v_mfma_f32_16x16x32_bf16 v[2:5], v[162:165], v[130:133], v[2:5]
	v_mfma_f32_16x16x32_bf16 v[6:9], v[166:169], v[130:133], v[6:9]
	v_mfma_f32_16x16x32_bf16 v[10:13], v[170:173], v[130:133], v[10:13]
	v_mfma_f32_16x16x32_bf16 v[14:17], v[174:177], v[130:133], v[14:17]
	s_barrier
	v_mfma_f32_16x16x32_bf16 v[18:21], v[162:165], v[134:137], v[18:21]
	s_add_i32 m0, s60, s62
	v_mfma_f32_16x16x32_bf16 v[22:25], v[166:169], v[134:137], v[22:25]
	global_load_lds_dwordx4 v226, s[54:55]
	v_mfma_f32_16x16x32_bf16 v[26:29], v[170:173], v[134:137], v[26:29]
	v_mfma_f32_16x16x32_bf16 v[30:33], v[174:177], v[134:137], v[30:33]
	v_mfma_f32_16x16x32_bf16 v[34:37], v[162:165], v[138:141], v[34:37]
	ds_read_b128 v[210:213], v241 offset:0
	v_mfma_f32_16x16x32_bf16 v[38:41], v[166:169], v[138:141], v[38:41]
	ds_read_b128 v[214:217], v241 offset:256
	v_mfma_f32_16x16x32_bf16 v[42:45], v[170:173], v[138:141], v[42:45]
	ds_read_b128 v[218:221], v241 offset:512
	global_load_lds_dwordx4 v226, s[54:55] offset:1024
	v_mfma_f32_16x16x32_bf16 v[46:49], v[174:177], v[138:141], v[46:49]
	ds_read_b128 v[222:225], v241 offset:768
	v_mfma_f32_16x16x32_bf16 v[50:53], v[162:165], v[142:145], v[50:53]
	ds_read_b128 v[178:181], v240 offset:0
	v_mfma_f32_16x16x32_bf16 v[54:57], v[166:169], v[142:145], v[54:57]
	ds_read_b128 v[182:185], v240 offset:1024
	v_mfma_f32_16x16x32_bf16 v[58:61], v[170:173], v[142:145], v[58:61]
	ds_read_b128 v[186:189], v240 offset:2048
	v_mfma_f32_16x16x32_bf16 v[62:65], v[174:177], v[142:145], v[62:65]
	ds_read_b128 v[190:193], v240 offset:3072
	global_load_lds_dwordx4 v226, s[54:55] offset:2048
	v_mfma_f32_16x16x32_bf16 v[66:69], v[162:165], v[146:149], v[66:69]
	ds_read_b128 v[194:197], v240 offset:4096
	v_mfma_f32_16x16x32_bf16 v[70:73], v[166:169], v[146:149], v[70:73]
	ds_read_b128 v[198:201], v240 offset:5120
	v_mfma_f32_16x16x32_bf16 v[74:77], v[170:173], v[146:149], v[74:77]
	ds_read_b128 v[202:205], v240 offset:6144
	v_mfma_f32_16x16x32_bf16 v[78:81], v[174:177], v[146:149], v[78:81]
	ds_read_b128 v[206:209], v240 offset:7168
	v_mfma_f32_16x16x32_bf16 v[82:85], v[162:165], v[150:153], v[82:85]
	global_load_lds_dwordx4 v226, s[54:55] offset:3072
	v_mfma_f32_16x16x32_bf16 v[86:89], v[166:169], v[150:153], v[86:89]
	v_mfma_f32_16x16x32_bf16 v[90:93], v[170:173], v[150:153], v[90:93]
	v_mfma_f32_16x16x32_bf16 v[94:97], v[174:177], v[150:153], v[94:97]
	v_mfma_f32_16x16x32_bf16 v[98:101], v[162:165], v[154:157], v[98:101]
	s_add_i32 m0, s60, s63
	v_mfma_f32_16x16x32_bf16 v[102:105], v[166:169], v[154:157], v[102:105]
	global_load_lds_dwordx4 v230, s[56:57]
	v_mfma_f32_16x16x32_bf16 v[106:109], v[170:173], v[154:157], v[106:109]
	v_mfma_f32_16x16x32_bf16 v[110:113], v[174:177], v[154:157], v[110:113]
	v_mfma_f32_16x16x32_bf16 v[114:117], v[162:165], v[158:161], v[114:117]
	v_mfma_f32_16x16x32_bf16 v[118:121], v[166:169], v[158:161], v[118:121]
	v_mfma_f32_16x16x32_bf16 v[122:125], v[170:173], v[158:161], v[122:125]
	global_load_lds_dwordx4 v231, s[56:57] offset:1024
	v_mfma_f32_16x16x32_bf16 v[126:129], v[174:177], v[158:161], v[126:129]
	s_setprio 0
	s_add_i32 s60, s60, 0x6000
	s_cmp_eq_u32 s60, 0x12000
	s_cselect_b32 s60, 0, s60
	s_add_u32 s54, s54, s72
	s_addc_u32 s55, s55, 0
	s_add_u32 s56, s56, s73
	s_addc_u32 s57, s57, 0
	s_add_i32 s61, s61, 0x6000
	s_cmp_eq_u32 s61, 0x12000
	s_cselect_b32 s61, 0, s61
	s_waitcnt vmcnt(6) lgkmcnt(0)
	v_add_u32_e32 v240, s61, v238
	v_add_u32_e32 v241, s61, v239
	s_setprio 1
	v_mfma_f32_16x16x32_bf16 v[2:5], v[210:213], v[178:181], v[2:5]
	v_mfma_f32_16x16x32_bf16 v[6:9], v[214:217], v[178:181], v[6:9]
	v_mfma_f32_16x16x32_bf16 v[10:13], v[218:221], v[178:181], v[10:13]
	v_mfma_f32_16x16x32_bf16 v[14:17], v[222:225], v[178:181], v[14:17]
	s_barrier
	v_mfma_f32_16x16x32_bf16 v[18:21], v[210:213], v[182:185], v[18:21]
	s_add_i32 m0, s60, s62
	v_mfma_f32_16x16x32_bf16 v[22:25], v[214:217], v[182:185], v[22:25]
	global_load_lds_dwordx4 v226, s[54:55]
	v_mfma_f32_16x16x32_bf16 v[26:29], v[218:221], v[182:185], v[26:29]
	v_mfma_f32_16x16x32_bf16 v[30:33], v[222:225], v[182:185], v[30:33]
	v_mfma_f32_16x16x32_bf16 v[34:37], v[210:213], v[186:189], v[34:37]
	ds_read_b128 v[162:165], v241 offset:0
	v_mfma_f32_16x16x32_bf16 v[38:41], v[214:217], v[186:189], v[38:41]
	ds_read_b128 v[166:169], v241 offset:256
	v_mfma_f32_16x16x32_bf16 v[42:45], v[218:221], v[186:189], v[42:45]
	ds_read_b128 v[170:173], v241 offset:512
	global_load_lds_dwordx4 v226, s[54:55] offset:1024
	v_mfma_f32_16x16x32_bf16 v[46:49], v[222:225], v[186:189], v[46:49]
	ds_read_b128 v[174:177], v241 offset:768
	v_mfma_f32_16x16x32_bf16 v[50:53], v[210:213], v[190:193], v[50:53]
	ds_read_b128 v[130:133], v240 offset:0
	v_mfma_f32_16x16x32_bf16 v[54:57], v[214:217], v[190:193], v[54:57]
	ds_read_b128 v[134:137], v240 offset:1024
	v_mfma_f32_16x16x32_bf16 v[58:61], v[218:221], v[190:193], v[58:61]
	ds_read_b128 v[138:141], v240 offset:2048
	v_mfma_f32_16x16x32_bf16 v[62:65], v[222:225], v[190:193], v[62:65]
	ds_read_b128 v[142:145], v240 offset:3072
	global_load_lds_dwordx4 v226, s[54:55] offset:2048
	v_mfma_f32_16x16x32_bf16 v[66:69], v[210:213], v[194:197], v[66:69]
	ds_read_b128 v[146:149], v240 offset:4096
	v_mfma_f32_16x16x32_bf16 v[70:73], v[214:217], v[194:197], v[70:73]
	ds_read_b128 v[150:153], v240 offset:5120
	v_mfma_f32_16x16x32_bf16 v[74:77], v[218:221], v[194:197], v[74:77]
	ds_read_b128 v[154:157], v240 offset:6144
	v_mfma_f32_16x16x32_bf16 v[78:81], v[222:225], v[194:197], v[78:81]
	ds_read_b128 v[158:161], v240 offset:7168
	v_mfma_f32_16x16x32_bf16 v[82:85], v[210:213], v[198:201], v[82:85]
	global_load_lds_dwordx4 v226, s[54:55] offset:3072
	v_mfma_f32_16x16x32_bf16 v[86:89], v[214:217], v[198:201], v[86:89]
	v_mfma_f32_16x16x32_bf16 v[90:93], v[218:221], v[198:201], v[90:93]
	v_mfma_f32_16x16x32_bf16 v[94:97], v[222:225], v[198:201], v[94:97]
	v_mfma_f32_16x16x32_bf16 v[98:101], v[210:213], v[202:205], v[98:101]
	s_add_i32 m0, s60, s63
	v_mfma_f32_16x16x32_bf16 v[102:105], v[214:217], v[202:205], v[102:105]
	global_load_lds_dwordx4 v230, s[56:57]
	v_mfma_f32_16x16x32_bf16 v[106:109], v[218:221], v[202:205], v[106:109]
	v_mfma_f32_16x16x32_bf16 v[110:113], v[222:225], v[202:205], v[110:113]
	v_mfma_f32_16x16x32_bf16 v[114:117], v[210:213], v[206:209], v[114:117]
	v_mfma_f32_16x16x32_bf16 v[118:121], v[214:217], v[206:209], v[118:121]
	v_mfma_f32_16x16x32_bf16 v[122:125], v[218:221], v[206:209], v[122:125]
	global_load_lds_dwordx4 v231, s[56:57] offset:1024
	v_mfma_f32_16x16x32_bf16 v[126:129], v[222:225], v[206:209], v[126:129]
	s_setprio 0
	s_add_i32 s60, s60, 0x6000
	s_cmp_eq_u32 s60, 0x12000
	s_cselect_b32 s60, 0, s60
	s_add_u32 s54, s54, s72
	s_addc_u32 s55, s55, 0
	s_add_u32 s56, s56, s73
	s_addc_u32 s57, s57, 0
	s_add_i32 s61, s61, 0x6000
	s_cmp_eq_u32 s61, 0x12000
	s_cselect_b32 s61, 0, s61
	s_nop 7
	s_nop 1
	s_lshl_b32 s26, s35, 11
	s_lshl_b32 s27, s36, 1
	s_add_i32 s26, s26, s27
	s_add_u32 s18, s52, s26
	s_addc_u32 s19, s53, 0
	v_cvt_pk_bf16_f32 v2, v2, v3
	v_cvt_pk_bf16_f32 v3, v4, v5
	v_cvt_pk_bf16_f32 v4, v6, v7
	v_cvt_pk_bf16_f32 v5, v8, v9
	v_cvt_pk_bf16_f32 v6, v10, v11
	v_cvt_pk_bf16_f32 v7, v12, v13
	v_cvt_pk_bf16_f32 v8, v14, v15
	v_cvt_pk_bf16_f32 v9, v16, v17
	global_store_dwordx4 v242, v[2:5], s[18:19]
	global_store_dwordx4 v242, v[6:9], s[18:19] offset:16
	s_add_u32 s18, s18, 0x8000
	s_addc_u32 s19, s19, 0
	v_cvt_pk_bf16_f32 v18, v18, v19
	v_cvt_pk_bf16_f32 v19, v20, v21
	v_cvt_pk_bf16_f32 v20, v22, v23
	v_cvt_pk_bf16_f32 v21, v24, v25
	v_cvt_pk_bf16_f32 v22, v26, v27
	v_cvt_pk_bf16_f32 v23, v28, v29
	v_cvt_pk_bf16_f32 v24, v30, v31
	v_cvt_pk_bf16_f32 v25, v32, v33
	global_store_dwordx4 v242, v[18:21], s[18:19]
	global_store_dwordx4 v242, v[22:25], s[18:19] offset:16
	s_add_u32 s18, s18, 0x8000
	s_addc_u32 s19, s19, 0
	v_cvt_pk_bf16_f32 v34, v34, v35
	v_cvt_pk_bf16_f32 v35, v36, v37
	v_cvt_pk_bf16_f32 v36, v38, v39
	v_cvt_pk_bf16_f32 v37, v40, v41
	v_cvt_pk_bf16_f32 v38, v42, v43
	v_cvt_pk_bf16_f32 v39, v44, v45
	v_cvt_pk_bf16_f32 v40, v46, v47
	v_cvt_pk_bf16_f32 v41, v48, v49
	global_store_dwordx4 v242, v[34:37], s[18:19]
	global_store_dwordx4 v242, v[38:41], s[18:19] offset:16
	s_add_u32 s18, s18, 0x8000
	s_addc_u32 s19, s19, 0
	v_cvt_pk_bf16_f32 v50, v50, v51
	v_cvt_pk_bf16_f32 v51, v52, v53
	v_cvt_pk_bf16_f32 v52, v54, v55
	v_cvt_pk_bf16_f32 v53, v56, v57
	v_cvt_pk_bf16_f32 v54, v58, v59
	v_cvt_pk_bf16_f32 v55, v60, v61
	v_cvt_pk_bf16_f32 v56, v62, v63
	v_cvt_pk_bf16_f32 v57, v64, v65
	global_store_dwordx4 v242, v[50:53], s[18:19]
	global_store_dwordx4 v242, v[54:57], s[18:19] offset:16
	s_add_u32 s18, s18, 0x8000
	s_addc_u32 s19, s19, 0
	v_cvt_pk_bf16_f32 v66, v66, v67
	v_cvt_pk_bf16_f32 v67, v68, v69
	v_cvt_pk_bf16_f32 v68, v70, v71
	v_cvt_pk_bf16_f32 v69, v72, v73
	v_cvt_pk_bf16_f32 v70, v74, v75
	v_cvt_pk_bf16_f32 v71, v76, v77
	v_cvt_pk_bf16_f32 v72, v78, v79
	v_cvt_pk_bf16_f32 v73, v80, v81
	global_store_dwordx4 v242, v[66:69], s[18:19]
	global_store_dwordx4 v242, v[70:73], s[18:19] offset:16
	s_add_u32 s18, s18, 0x8000
	s_addc_u32 s19, s19, 0
	v_cvt_pk_bf16_f32 v82, v82, v83
	v_cvt_pk_bf16_f32 v83, v84, v85
	v_cvt_pk_bf16_f32 v84, v86, v87
	v_cvt_pk_bf16_f32 v85, v88, v89
	v_cvt_pk_bf16_f32 v86, v90, v91
	v_cvt_pk_bf16_f32 v87, v92, v93
	v_cvt_pk_bf16_f32 v88, v94, v95
	v_cvt_pk_bf16_f32 v89, v96, v97
	global_store_dwordx4 v242, v[82:85], s[18:19]
	global_store_dwordx4 v242, v[86:89], s[18:19] offset:16
	s_add_u32 s18, s18, 0x8000
	s_addc_u32 s19, s19, 0
	v_cvt_pk_bf16_f32 v98, v98, v99
	v_cvt_pk_bf16_f32 v99, v100, v101
	v_cvt_pk_bf16_f32 v100, v102, v103
	v_cvt_pk_bf16_f32 v101, v104, v105
	v_cvt_pk_bf16_f32 v102, v106, v107
	v_cvt_pk_bf16_f32 v103, v108, v109
	v_cvt_pk_bf16_f32 v104, v110, v111
	v_cvt_pk_bf16_f32 v105, v112, v113
	global_store_dwordx4 v242, v[98:101], s[18:19]
	global_store_dwordx4 v242, v[102:105], s[18:19] offset:16
	s_add_u32 s18, s18, 0x8000
	s_addc_u32 s19, s19, 0
	v_cvt_pk_bf16_f32 v114, v114, v115
	v_cvt_pk_bf16_f32 v115, v116, v117
	v_cvt_pk_bf16_f32 v116, v118, v119
	v_cvt_pk_bf16_f32 v117, v120, v121
	v_cvt_pk_bf16_f32 v118, v122, v123
	v_cvt_pk_bf16_f32 v119, v124, v125
	v_cvt_pk_bf16_f32 v120, v126, v127
	v_cvt_pk_bf16_f32 v121, v128, v129
	global_store_dwordx4 v242, v[114:117], s[18:19]
	global_store_dwordx4 v242, v[118:121], s[18:19] offset:16
	s_mov_b32 s34, s38
	s_mov_b32 s35, s30
	s_mov_b32 s36, s31
	s_branch .Lgy_tile
.Lgy_tail_last:
	s_waitcnt vmcnt(6) lgkmcnt(0)
	v_add_u32_e32 v240, s61, v238
	v_add_u32_e32 v241, s61, v239
	s_setprio 1
	v_mfma_f32_16x16x32_bf16 v[2:5], v[162:165], v[130:133], v[2:5]
	v_mfma_f32_16x16x32_bf16 v[6:9], v[166:169], v[130:133], v[6:9]
	v_mfma_f32_16x16x32_bf16 v[10:13], v[170:173], v[130:133], v[10:13]
	v_mfma_f32_16x16x32_bf16 v[14:17], v[174:177], v[130:133], v[14:17]
	s_barrier
	v_mfma_f32_16x16x32_bf16 v[18:21], v[162:165], v[134:137], v[18:21]
	s_add_i32 m0, s60, s62
	v_mfma_f32_16x16x32_bf16 v[22:25], v[166:169], v[134:137], v[22:25]
	global_load_lds_dwordx4 v226, s[54:55]
	v_mfma_f32_16x16x32_bf16 v[26:29], v[170:173], v[134:137], v[26:29]
	v_mfma_f32_16x16x32_bf16 v[30:33], v[174:177], v[134:137], v[30:33]
	v_mfma_f32_16x16x32_bf16 v[34:37], v[162:165], v[138:141], v[34:37]
	ds_read_b128 v[210:213], v241 offset:0
	v_mfma_f32_16x16x32_bf16 v[38:41], v[166:169], v[138:141], v[38:41]
	ds_read_b128 v[214:217], v241 offset:256
	v_mfma_f32_16x16x32_bf16 v[42:45], v[170:173], v[138:141], v[42:45]
	ds_read_b128 v[218:221], v241 offset:512
	global_load_lds_dwordx4 v226, s[54:55] offset:1024
	v_mfma_f32_16x16x32_bf16 v[46:49], v[174:177], v[138:141], v[46:49]
	ds_read_b128 v[222:225], v241 offset:768
	v_mfma_f32_16x16x32_bf16 v[50:53], v[162:165], v[142:145], v[50:53]
	ds_read_b128 v[178:181], v240 offset:0
	v_mfma_f32_16x16x32_bf16 v[54:57], v[166:169], v[142:145], v[54:57]
	ds_read_b128 v[182:185], v240 offset:1024
	v_mfma_f32_16x16x32_bf16 v[58:61], v[170:173], v[142:145], v[58:61]
	ds_read_b128 v[186:189], v240 offset:2048
	v_mfma_f32_16x16x32_bf16 v[62:65], v[174:177], v[142:145], v[62:65]
	ds_read_b128 v[190:193], v240 offset:3072
	global_load_lds_dwordx4 v226, s[54:55] offset:2048
	v_mfma_f32_16x16x32_bf16 v[66:69], v[162:165], v[146:149], v[66:69]
	ds_read_b128 v[194:197], v240 offset:4096
	v_mfma_f32_16x16x32_bf16 v[70:73], v[166:169], v[146:149], v[70:73]
	ds_read_b128 v[198:201], v240 offset:5120
	v_mfma_f32_16x16x32_bf16 v[74:77], v[170:173], v[146:149], v[74:77]
	ds_read_b128 v[202:205], v240 offset:6144
	v_mfma_f32_16x16x32_bf16 v[78:81], v[174:177], v[146:149], v[78:81]
	ds_read_b128 v[206:209], v240 offset:7168
	v_mfma_f32_16x16x32_bf16 v[82:85], v[162:165], v[150:153], v[82:85]
	global_load_lds_dwordx4 v226, s[54:55] offset:3072
	v_mfma_f32_16x16x32_bf16 v[86:89], v[166:169], v[150:153], v[86:89]
	v_mfma_f32_16x16x32_bf16 v[90:93], v[170:173], v[150:153], v[90:93]
	v_mfma_f32_16x16x32_bf16 v[94:97], v[174:177], v[150:153], v[94:97]
	v_mfma_f32_16x16x32_bf16 v[98:101], v[162:165], v[154:157], v[98:101]
	s_add_i32 m0, s60, s63
	v_mfma_f32_16x16x32_bf16 v[102:105], v[166:169], v[154:157], v[102:105]
	global_load_lds_dwordx4 v230, s[56:57]
	v_mfma_f32_16x16x32_bf16 v[106:109], v[170:173], v[154:157], v[106:109]
	v_mfma_f32_16x16x32_bf16 v[110:113], v[174:177], v[154:157], v[110:113]
	v_mfma_f32_16x16x32_bf16 v[114:117], v[162:165], v[158:161], v[114:117]
	v_mfma_f32_16x16x32_bf16 v[118:121], v[166:169], v[158:161], v[118:121]
	v_mfma_f32_16x16x32_bf16 v[122:125], v[170:173], v[158:161], v[122:125]
	global_load_lds_dwordx4 v231, s[56:57] offset:1024
	v_mfma_f32_16x16x32_bf16 v[126:129], v[174:177], v[158:161], v[126:129]
	s_setprio 0
	s_add_i32 s60, s60, 0x6000
	s_cmp_eq_u32 s60, 0x12000
	s_cselect_b32 s60, 0, s60
	s_add_u32 s54, s54, s72
	s_addc_u32 s55, s55, 0
	s_add_u32 s56, s56, s73
	s_addc_u32 s57, s57, 0
	s_add_i32 s61, s61, 0x6000
	s_cmp_eq_u32 s61, 0x12000
	s_cselect_b32 s61, 0, s61
	s_waitcnt vmcnt(6) lgkmcnt(0)
	v_add_u32_e32 v240, s61, v238
	v_add_u32_e32 v241, s61, v239
	s_setprio 1
	v_mfma_f32_16x16x32_bf16 v[2:5], v[210:213], v[178:181], v[2:5]
	v_mfma_f32_16x16x32_bf16 v[6:9], v[214:217], v[178:181], v[6:9]
	v_mfma_f32_16x16x32_bf16 v[10:13], v[218:221], v[178:181], v[10:13]
	v_mfma_f32_16x16x32_bf16 v[14:17], v[222:225], v[178:181], v[14:17]
	s_barrier
	v_mfma_f32_16x16x32_bf16 v[18:21], v[210:213], v[182:185], v[18:21]
	v_mfma_f32_16x16x32_bf16 v[22:25], v[214:217], v[182:185], v[22:25]
	v_mfma_f32_16x16x32_bf16 v[26:29], v[218:221], v[182:185], v[26:29]
	v_mfma_f32_16x16x32_bf16 v[30:33], v[222:225], v[182:185], v[30:33]
	v_mfma_f32_16x16x32_bf16 v[34:37], v[210:213], v[186:189], v[34:37]
	ds_read_b128 v[162:165], v241 offset:0
	v_mfma_f32_16x16x32_bf16 v[38:41], v[214:217], v[186:189], v[38:41]
	ds_read_b128 v[166:169], v241 offset:256
	v_mfma_f32_16x16x32_bf16 v[42:45], v[218:221], v[186:189], v[42:45]
	ds_read_b128 v[170:173], v241 offset:512
	v_mfma_f32_16x16x32_bf16 v[46:49], v[222:225], v[186:189], v[46:49]
	ds_read_b128 v[174:177], v241 offset:768
	v_mfma_f32_16x16x32_bf16 v[50:53], v[210:213], v[190:193], v[50:53]
	ds_read_b128 v[130:133], v240 offset:0
	v_mfma_f32_16x16x32_bf16 v[54:57], v[214:217], v[190:193], v[54:57]
	ds_read_b128 v[134:137], v240 offset:1024
	v_mfma_f32_16x16x32_bf16 v[58:61], v[218:221], v[190:193], v[58:61]
	ds_read_b128 v[138:141], v240 offset:2048
	v_mfma_f32_16x16x32_bf16 v[62:65], v[222:225], v[190:193], v[62:65]
	ds_read_b128 v[142:145], v240 offset:3072
	v_mfma_f32_16x16x32_bf16 v[66:69], v[210:213], v[194:197], v[66:69]
	ds_read_b128 v[146:149], v240 offset:4096
	v_mfma_f32_16x16x32_bf16 v[70:73], v[214:217], v[194:197], v[70:73]
	ds_read_b128 v[150:153], v240 offset:5120
	v_mfma_f32_16x16x32_bf16 v[74:77], v[218:221], v[194:197], v[74:77]
	ds_read_b128 v[154:157], v240 offset:6144
	v_mfma_f32_16x16x32_bf16 v[78:81], v[222:225], v[194:197], v[78:81]
	ds_read_b128 v[158:161], v240 offset:7168
	v_mfma_f32_16x16x32_bf16 v[82:85], v[210:213], v[198:201], v[82:85]
	v_mfma_f32_16x16x32_bf16 v[86:89], v[214:217], v[198:201], v[86:89]
	v_mfma_f32_16x16x32_bf16 v[90:93], v[218:221], v[198:201], v[90:93]
	v_mfma_f32_16x16x32_bf16 v[94:97], v[222:225], v[198:201], v[94:97]
	v_mfma_f32_16x16x32_bf16 v[98:101], v[210:213], v[202:205], v[98:101]
	v_mfma_f32_16x16x32_bf16 v[102:105], v[214:217], v[202:205], v[102:105]
	v_mfma_f32_16x16x32_bf16 v[106:109], v[218:221], v[202:205], v[106:109]
	v_mfma_f32_16x16x32_bf16 v[110:113], v[222:225], v[202:205], v[110:113]
	v_mfma_f32_16x16x32_bf16 v[114:117], v[210:213], v[206:209], v[114:117]
	v_mfma_f32_16x16x32_bf16 v[118:121], v[214:217], v[206:209], v[118:121]
	v_mfma_f32_16x16x32_bf16 v[122:125], v[218:221], v[206:209], v[122:125]
	v_mfma_f32_16x16x32_bf16 v[126:129], v[222:225], v[206:209], v[126:129]
	s_setprio 0
	s_add_i32 s61, s61, 0x6000
	s_cmp_eq_u32 s61, 0x12000
	s_cselect_b32 s61, 0, s61
	s_waitcnt vmcnt(0) lgkmcnt(0)
	v_add_u32_e32 v240, s61, v238
	v_add_u32_e32 v241, s61, v239
	s_setprio 1
	v_mfma_f32_16x16x32_bf16 v[2:5], v[162:165], v[130:133], v[2:5]
	v_mfma_f32_16x16x32_bf16 v[6:9], v[166:169], v[130:133], v[6:9]
	v_mfma_f32_16x16x32_bf16 v[10:13], v[170:173], v[130:133], v[10:13]
	v_mfma_f32_16x16x32_bf16 v[14:17], v[174:177], v[130:133], v[14:17]
	s_barrier
	v_mfma_f32_16x16x32_bf16 v[18:21], v[162:165], v[134:137], v[18:21]
	v_mfma_f32_16x16x32_bf16 v[22:25], v[166:169], v[134:137], v[22:25]
	v_mfma_f32_16x16x32_bf16 v[26:29], v[170:173], v[134:137], v[26:29]
	v_mfma_f32_16x16x32_bf16 v[30:33], v[174:177], v[134:137], v[30:33]
	v_mfma_f32_16x16x32_bf16 v[34:37], v[162:165], v[138:141], v[34:37]
	ds_read_b128 v[210:213], v241 offset:0
	v_mfma_f32_16x16x32_bf16 v[38:41], v[166:169], v[138:141], v[38:41]
	ds_read_b128 v[214:217], v241 offset:256
	v_mfma_f32_16x16x32_bf16 v[42:45], v[170:173], v[138:141], v[42:45]
	ds_read_b128 v[218:221], v241 offset:512
	v_mfma_f32_16x16x32_bf16 v[46:49], v[174:177], v[138:141], v[46:49]
	ds_read_b128 v[222:225], v241 offset:768
	v_mfma_f32_16x16x32_bf16 v[50:53], v[162:165], v[142:145], v[50:53]
	ds_read_b128 v[178:181], v240 offset:0
	v_mfma_f32_16x16x32_bf16 v[54:57], v[166:169], v[142:145], v[54:57]
	ds_read_b128 v[182:185], v240 offset:1024
	v_mfma_f32_16x16x32_bf16 v[58:61], v[170:173], v[142:145], v[58:61]
	ds_read_b128 v[186:189], v240 offset:2048
	v_mfma_f32_16x16x32_bf16 v[62:65], v[174:177], v[142:145], v[62:65]
	ds_read_b128 v[190:193], v240 offset:3072
	v_mfma_f32_16x16x32_bf16 v[66:69], v[162:165], v[146:149], v[66:69]
	ds_read_b128 v[194:197], v240 offset:4096
	v_mfma_f32_16x16x32_bf16 v[70:73], v[166:169], v[146:149], v[70:73]
	ds_read_b128 v[198:201], v240 offset:5120
	v_mfma_f32_16x16x32_bf16 v[74:77], v[170:173], v[146:149], v[74:77]
	ds_read_b128 v[202:205], v240 offset:6144
	v_mfma_f32_16x16x32_bf16 v[78:81], v[174:177], v[146:149], v[78:81]
	ds_read_b128 v[206:209], v240 offset:7168
	v_mfma_f32_16x16x32_bf16 v[82:85], v[162:165], v[150:153], v[82:85]
	v_mfma_f32_16x16x32_bf16 v[86:89], v[166:169], v[150:153], v[86:89]
	v_mfma_f32_16x16x32_bf16 v[90:93], v[170:173], v[150:153], v[90:93]
	v_mfma_f32_16x16x32_bf16 v[94:97], v[174:177], v[150:153], v[94:97]
	v_mfma_f32_16x16x32_bf16 v[98:101], v[162:165], v[154:157], v[98:101]
	v_mfma_f32_16x16x32_bf16 v[102:105], v[166:169], v[154:157], v[102:105]
	v_mfma_f32_16x16x32_bf16 v[106:109], v[170:173], v[154:157], v[106:109]
	v_mfma_f32_16x16x32_bf16 v[110:113], v[174:177], v[154:157], v[110:113]
	v_mfma_f32_16x16x32_bf16 v[114:117], v[162:165], v[158:161], v[114:117]
	v_mfma_f32_16x16x32_bf16 v[118:121], v[166:169], v[158:161], v[118:121]
	v_mfma_f32_16x16x32_bf16 v[122:125], v[170:173], v[158:161], v[122:125]
	v_mfma_f32_16x16x32_bf16 v[126:129], v[174:177], v[158:161], v[126:129]
	s_setprio 0
	s_add_i32 s61, s61, 0x6000
	s_cmp_eq_u32 s61, 0x12000
	s_cselect_b32 s61, 0, s61
	s_waitcnt lgkmcnt(0)
	s_setprio 1
	v_mfma_f32_16x16x32_bf16 v[2:5], v[210:213], v[178:181], v[2:5]
	v_mfma_f32_16x16x32_bf16 v[6:9], v[214:217], v[178:181], v[6:9]
	v_mfma_f32_16x16x32_bf16 v[10:13], v[218:221], v[178:181], v[10:13]
	v_mfma_f32_16x16x32_bf16 v[14:17], v[222:225], v[178:181], v[14:17]
	s_barrier
	v_mfma_f32_16x16x32_bf16 v[18:21], v[210:213], v[182:185], v[18:21]
	v_mfma_f32_16x16x32_bf16 v[22:25], v[214:217], v[182:185], v[22:25]
	v_mfma_f32_16x16x32_bf16 v[26:29], v[218:221], v[182:185], v[26:29]
	v_mfma_f32_16x16x32_bf16 v[30:33], v[222:225], v[182:185], v[30:33]
	v_mfma_f32_16x16x32_bf16 v[34:37], v[210:213], v[186:189], v[34:37]
	v_mfma_f32_16x16x32_bf16 v[38:41], v[214:217], v[186:189], v[38:41]
	v_mfma_f32_16x16x32_bf16 v[42:45], v[218:221], v[186:189], v[42:45]
	v_mfma_f32_16x16x32_bf16 v[46:49], v[222:225], v[186:189], v[46:49]
	v_mfma_f32_16x16x32_bf16 v[50:53], v[210:213], v[190:193], v[50:53]
	v_mfma_f32_16x16x32_bf16 v[54:57], v[214:217], v[190:193], v[54:57]
	v_mfma_f32_16x16x32_bf16 v[58:61], v[218:221], v[190:193], v[58:61]
	v_mfma_f32_16x16x32_bf16 v[62:65], v[222:225], v[190:193], v[62:65]
	v_mfma_f32_16x16x32_bf16 v[66:69], v[210:213], v[194:197], v[66:69]
	v_mfma_f32_16x16x32_bf16 v[70:73], v[214:217], v[194:197], v[70:73]
	v_mfma_f32_16x16x32_bf16 v[74:77], v[218:221], v[194:197], v[74:77]
	v_mfma_f32_16x16x32_bf16 v[78:81], v[222:225], v[194:197], v[78:81]
	v_mfma_f32_16x16x32_bf16 v[82:85], v[210:213], v[198:201], v[82:85]
	v_mfma_f32_16x16x32_bf16 v[86:89], v[214:217], v[198:201], v[86:89]
	v_mfma_f32_16x16x32_bf16 v[90:93], v[218:221], v[198:201], v[90:93]
	v_mfma_f32_16x16x32_bf16 v[94:97], v[222:225], v[198:201], v[94:97]
	v_mfma_f32_16x16x32_bf16 v[98:101], v[210:213], v[202:205], v[98:101]
	v_mfma_f32_16x16x32_bf16 v[102:105], v[214:217], v[202:205], v[102:105]
	v_mfma_f32_16x16x32_bf16 v[106:109], v[218:221], v[202:205], v[106:109]
	v_mfma_f32_16x16x32_bf16 v[110:113], v[222:225], v[202:205], v[110:113]
	v_mfma_f32_16x16x32_bf16 v[114:117], v[210:213], v[206:209], v[114:117]
	v_mfma_f32_16x16x32_bf16 v[118:121], v[214:217], v[206:209], v[118:121]
	v_mfma_f32_16x16x32_bf16 v[122:125], v[218:221], v[206:209], v[122:125]
	v_mfma_f32_16x16x32_bf16 v[126:129], v[222:225], v[206:209], v[126:129]
	s_setprio 0
	s_nop 7
	s_nop 1
	s_lshl_b32 s26, s35, 11
	s_lshl_b32 s27, s36, 1
	s_add_i32 s26, s26, s27
	s_add_u32 s18, s52, s26
	s_addc_u32 s19, s53, 0
	v_cvt_pk_bf16_f32 v2, v2, v3
	v_cvt_pk_bf16_f32 v3, v4, v5
	v_cvt_pk_bf16_f32 v4, v6, v7
	v_cvt_pk_bf16_f32 v5, v8, v9
	v_cvt_pk_bf16_f32 v6, v10, v11
	v_cvt_pk_bf16_f32 v7, v12, v13
	v_cvt_pk_bf16_f32 v8, v14, v15
	v_cvt_pk_bf16_f32 v9, v16, v17
	global_store_dwordx4 v242, v[2:5], s[18:19]
	global_store_dwordx4 v242, v[6:9], s[18:19] offset:16
	s_add_u32 s18, s18, 0x8000
	s_addc_u32 s19, s19, 0
	v_cvt_pk_bf16_f32 v18, v18, v19
	v_cvt_pk_bf16_f32 v19, v20, v21
	v_cvt_pk_bf16_f32 v20, v22, v23
	v_cvt_pk_bf16_f32 v21, v24, v25
	v_cvt_pk_bf16_f32 v22, v26, v27
	v_cvt_pk_bf16_f32 v23, v28, v29
	v_cvt_pk_bf16_f32 v24, v30, v31
	v_cvt_pk_bf16_f32 v25, v32, v33
	global_store_dwordx4 v242, v[18:21], s[18:19]
	global_store_dwordx4 v242, v[22:25], s[18:19] offset:16
	s_add_u32 s18, s18, 0x8000
	s_addc_u32 s19, s19, 0
	v_cvt_pk_bf16_f32 v34, v34, v35
	v_cvt_pk_bf16_f32 v35, v36, v37
	v_cvt_pk_bf16_f32 v36, v38, v39
	v_cvt_pk_bf16_f32 v37, v40, v41
	v_cvt_pk_bf16_f32 v38, v42, v43
	v_cvt_pk_bf16_f32 v39, v44, v45
	v_cvt_pk_bf16_f32 v40, v46, v47
	v_cvt_pk_bf16_f32 v41, v48, v49
	global_store_dwordx4 v242, v[34:37], s[18:19]
	global_store_dwordx4 v242, v[38:41], s[18:19] offset:16
	s_add_u32 s18, s18, 0x8000
	s_addc_u32 s19, s19, 0
	v_cvt_pk_bf16_f32 v50, v50, v51
	v_cvt_pk_bf16_f32 v51, v52, v53
	v_cvt_pk_bf16_f32 v52, v54, v55
	v_cvt_pk_bf16_f32 v53, v56, v57
	v_cvt_pk_bf16_f32 v54, v58, v59
	v_cvt_pk_bf16_f32 v55, v60, v61
	v_cvt_pk_bf16_f32 v56, v62, v63
	v_cvt_pk_bf16_f32 v57, v64, v65
	global_store_dwordx4 v242, v[50:53], s[18:19]
	global_store_dwordx4 v242, v[54:57], s[18:19] offset:16
	s_add_u32 s18, s18, 0x8000
	s_addc_u32 s19, s19, 0
	v_cvt_pk_bf16_f32 v66, v66, v67
	v_cvt_pk_bf16_f32 v67, v68, v69
	v_cvt_pk_bf16_f32 v68, v70, v71
	v_cvt_pk_bf16_f32 v69, v72, v73
	v_cvt_pk_bf16_f32 v70, v74, v75
	v_cvt_pk_bf16_f32 v71, v76, v77
	v_cvt_pk_bf16_f32 v72, v78, v79
	v_cvt_pk_bf16_f32 v73, v80, v81
	global_store_dwordx4 v242, v[66:69], s[18:19]
	global_store_dwordx4 v242, v[70:73], s[18:19] offset:16
	s_add_u32 s18, s18, 0x8000
	s_addc_u32 s19, s19, 0
	v_cvt_pk_bf16_f32 v82, v82, v83
	v_cvt_pk_bf16_f32 v83, v84, v85
	v_cvt_pk_bf16_f32 v84, v86, v87
	v_cvt_pk_bf16_f32 v85, v88, v89
	v_cvt_pk_bf16_f32 v86, v90, v91
	v_cvt_pk_bf16_f32 v87, v92, v93
	v_cvt_pk_bf16_f32 v88, v94, v95
	v_cvt_pk_bf16_f32 v89, v96, v97
	global_store_dwordx4 v242, v[82:85], s[18:19]
	global_store_dwordx4 v242, v[86:89], s[18:19] offset:16
	s_add_u32 s18, s18, 0x8000
	s_addc_u32 s19, s19, 0
	v_cvt_pk_bf16_f32 v98, v98, v99
	v_cvt_pk_bf16_f32 v99, v100, v101
	v_cvt_pk_bf16_f32 v100, v102, v103
	v_cvt_pk_bf16_f32 v101, v104, v105
	v_cvt_pk_bf16_f32 v102, v106, v107
	v_cvt_pk_bf16_f32 v103, v108, v109
	v_cvt_pk_bf16_f32 v104, v110, v111
	v_cvt_pk_bf16_f32 v105, v112, v113
	global_store_dwordx4 v242, v[98:101], s[18:19]
	global_store_dwordx4 v242, v[102:105], s[18:19] offset:16
	s_add_u32 s18, s18, 0x8000
	s_addc_u32 s19, s19, 0
	v_cvt_pk_bf16_f32 v114, v114, v115
	v_cvt_pk_bf16_f32 v115, v116, v117
	v_cvt_pk_bf16_f32 v116, v118, v119
	v_cvt_pk_bf16_f32 v117, v120, v121
	v_cvt_pk_bf16_f32 v118, v122, v123
	v_cvt_pk_bf16_f32 v119, v124, v125
	v_cvt_pk_bf16_f32 v120, v126, v127
	v_cvt_pk_bf16_f32 v121, v128, v129
	global_store_dwordx4 v242, v[114:117], s[18:19]
	global_store_dwordx4 v242, v[118:121], s[18:19] offset:16

.Lup_nn_a:
	s_waitcnt vmcnt(6) lgkmcnt(0)
	v_add_u32_e32 v240, s61, v238
	v_add_u32_e32 v241, s61, v239
	s_setprio 1
	v_mfma_f32_16x16x32_bf16 v[2:5], v[162:165], v[130:133], 0
	v_mfma_f32_16x16x32_bf16 v[6:9], v[166:169], v[130:133], 0
	v_mfma_f32_16x16x32_bf16 v[10:13], v[170:173], v[130:133], 0
	v_mfma_f32_16x16x32_bf16 v[14:17], v[174:177], v[130:133], 0
	s_barrier
	v_mfma_f32_16x16x32_bf16 v[18:21], v[162:165], v[134:137], 0
	s_add_i32 m0, s60, s62
	v_mfma_f32_16x16x32_bf16 v[22:25], v[166:169], v[134:137], 0
	global_load_lds_dwordx4 v226, s[54:55]
	v_mfma_f32_16x16x32_bf16 v[26:29], v[170:173], v[134:137], 0
	v_mfma_f32_16x16x32_bf16 v[30:33], v[174:177], v[134:137], 0
	v_mfma_f32_16x16x32_bf16 v[34:37], v[162:165], v[138:141], 0
	ds_read_b128 v[210:213], v241 offset:0
	v_mfma_f32_16x16x32_bf16 v[38:41], v[166:169], v[138:141], 0
	ds_read_b128 v[214:217], v241 offset:256
	v_mfma_f32_16x16x32_bf16 v[42:45], v[170:173], v[138:141], 0
	ds_read_b128 v[218:221], v241 offset:2048
	global_load_lds_dwordx4 v226, s[54:55] offset:1024
	v_mfma_f32_16x16x32_bf16 v[46:49], v[174:177], v[138:141], 0
	ds_read_b128 v[222:225], v241 offset:2304
	v_mfma_f32_16x16x32_bf16 v[50:53], v[162:165], v[142:145], 0
	ds_read_b128 v[178:181], v240 offset:0
	v_mfma_f32_16x16x32_bf16 v[54:57], v[166:169], v[142:145], 0
	ds_read_b128 v[182:185], v240 offset:1024
	v_mfma_f32_16x16x32_bf16 v[58:61], v[170:173], v[142:145], 0
	ds_read_b128 v[186:189], v240 offset:2048
	v_mfma_f32_16x16x32_bf16 v[62:65], v[174:177], v[142:145], 0
	ds_read_b128 v[190:193], v240 offset:3072
	global_load_lds_dwordx4 v226, s[54:55] offset:2048
	v_mfma_f32_16x16x32_bf16 v[66:69], v[162:165], v[146:149], 0
	ds_read_b128 v[194:197], v240 offset:4096
	v_mfma_f32_16x16x32_bf16 v[70:73], v[166:169], v[146:149], 0
	ds_read_b128 v[198:201], v240 offset:5120
	v_mfma_f32_16x16x32_bf16 v[74:77], v[170:173], v[146:149], 0
	ds_read_b128 v[202:205], v240 offset:6144
	v_mfma_f32_16x16x32_bf16 v[78:81], v[174:177], v[146:149], 0
	ds_read_b128 v[206:209], v240 offset:7168
	v_mfma_f32_16x16x32_bf16 v[82:85], v[162:165], v[150:153], 0
	global_load_lds_dwordx4 v226, s[54:55] offset:3072
	v_mfma_f32_16x16x32_bf16 v[86:89], v[166:169], v[150:153], 0
	v_mfma_f32_16x16x32_bf16 v[90:93], v[170:173], v[150:153], 0
	v_mfma_f32_16x16x32_bf16 v[94:97], v[174:177], v[150:153], 0
	v_mfma_f32_16x16x32_bf16 v[98:101], v[162:165], v[154:157], 0
	s_add_i32 m0, s60, s63
	v_mfma_f32_16x16x32_bf16 v[102:105], v[166:169], v[154:157], 0
	global_load_lds_dwordx4 v230, s[56:57]
	v_mfma_f32_16x16x32_bf16 v[106:109], v[170:173], v[154:157], 0
	v_mfma_f32_16x16x32_bf16 v[110:113], v[174:177], v[154:157], 0
	v_mfma_f32_16x16x32_bf16 v[114:117], v[162:165], v[158:161], 0
	v_mfma_f32_16x16x32_bf16 v[118:121], v[166:169], v[158:161], 0
	v_mfma_f32_16x16x32_bf16 v[122:125], v[170:173], v[158:161], 0
	global_load_lds_dwordx4 v231, s[56:57] offset:1024
	v_mfma_f32_16x16x32_bf16 v[126:129], v[174:177], v[158:161], 0
	s_setprio 0
	s_add_i32 s60, s60, 0x6000
	s_cmp_eq_u32 s60, 0x12000
	s_cselect_b32 s60, 0, s60
	s_add_u32 s54, s54, s72
	s_addc_u32 s55, s55, 0
	s_add_u32 s56, s56, s73
	s_addc_u32 s57, s57, 0
	s_add_i32 s61, s61, 0x6000
	s_cmp_eq_u32 s61, 0x12000
	s_cselect_b32 s61, 0, s61
	v_mbcnt_lo_u32_b32 v0, -1, 0
	v_lshlrev_b32_e32 v0, 4, v0
	s_lshl_b32 s26, s36, 1
	v_add_u32_e32 v0, s26, v0
	s_lshl_b32 s26, s41, 8
	s_add_i32 m0, s26, 0x13010
	s_mov_b64 exec, 0xffff
	global_load_lds_dwordx4 v0, s[82:83]
	s_mov_b64 exec, -1
	s_waitcnt vmcnt(6) lgkmcnt(0)
	v_add_u32_e32 v240, s61, v238
	v_add_u32_e32 v241, s61, v239
	s_setprio 1
	v_mfma_f32_16x16x32_bf16 v[2:5], v[210:213], v[178:181], v[2:5]
	v_mfma_f32_16x16x32_bf16 v[6:9], v[214:217], v[178:181], v[6:9]
	v_mfma_f32_16x16x32_bf16 v[10:13], v[218:221], v[178:181], v[10:13]
	v_mfma_f32_16x16x32_bf16 v[14:17], v[222:225], v[178:181], v[14:17]
	s_barrier
	v_mfma_f32_16x16x32_bf16 v[18:21], v[210:213], v[182:185], v[18:21]
	s_add_i32 m0, s60, s62
	v_mfma_f32_16x16x32_bf16 v[22:25], v[214:217], v[182:185], v[22:25]
	global_load_lds_dwordx4 v226, s[54:55]
	v_mfma_f32_16x16x32_bf16 v[26:29], v[218:221], v[182:185], v[26:29]
	v_mfma_f32_16x16x32_bf16 v[30:33], v[222:225], v[182:185], v[30:33]
	v_mfma_f32_16x16x32_bf16 v[34:37], v[210:213], v[186:189], v[34:37]
	ds_read_b128 v[162:165], v241 offset:0
	v_mfma_f32_16x16x32_bf16 v[38:41], v[214:217], v[186:189], v[38:41]
	ds_read_b128 v[166:169], v241 offset:256
	v_mfma_f32_16x16x32_bf16 v[42:45], v[218:221], v[186:189], v[42:45]
	ds_read_b128 v[170:173], v241 offset:2048
	global_load_lds_dwordx4 v226, s[54:55] offset:1024
	v_mfma_f32_16x16x32_bf16 v[46:49], v[222:225], v[186:189], v[46:49]
	ds_read_b128 v[174:177], v241 offset:2304
	v_mfma_f32_16x16x32_bf16 v[50:53], v[210:213], v[190:193], v[50:53]
	ds_read_b128 v[130:133], v240 offset:0
	v_mfma_f32_16x16x32_bf16 v[54:57], v[214:217], v[190:193], v[54:57]
	ds_read_b128 v[134:137], v240 offset:1024
	v_mfma_f32_16x16x32_bf16 v[58:61], v[218:221], v[190:193], v[58:61]
	ds_read_b128 v[138:141], v240 offset:2048
	v_mfma_f32_16x16x32_bf16 v[62:65], v[222:225], v[190:193], v[62:65]
	ds_read_b128 v[142:145], v240 offset:3072
	global_load_lds_dwordx4 v226, s[54:55] offset:2048
	v_mfma_f32_16x16x32_bf16 v[66:69], v[210:213], v[194:197], v[66:69]
	ds_read_b128 v[146:149], v240 offset:4096
	v_mfma_f32_16x16x32_bf16 v[70:73], v[214:217], v[194:197], v[70:73]
	ds_read_b128 v[150:153], v240 offset:5120
	v_mfma_f32_16x16x32_bf16 v[74:77], v[218:221], v[194:197], v[74:77]
	ds_read_b128 v[154:157], v240 offset:6144
	v_mfma_f32_16x16x32_bf16 v[78:81], v[222:225], v[194:197], v[78:81]
	ds_read_b128 v[158:161], v240 offset:7168
	v_mfma_f32_16x16x32_bf16 v[82:85], v[210:213], v[198:201], v[82:85]
	global_load_lds_dwordx4 v226, s[54:55] offset:3072
	v_mfma_f32_16x16x32_bf16 v[86:89], v[214:217], v[198:201], v[86:89]
	v_mfma_f32_16x16x32_bf16 v[90:93], v[218:221], v[198:201], v[90:93]
	v_mfma_f32_16x16x32_bf16 v[94:97], v[222:225], v[198:201], v[94:97]
	v_mfma_f32_16x16x32_bf16 v[98:101], v[210:213], v[202:205], v[98:101]
	s_add_i32 m0, s60, s63
	v_mfma_f32_16x16x32_bf16 v[102:105], v[214:217], v[202:205], v[102:105]
	global_load_lds_dwordx4 v230, s[56:57]
	v_mfma_f32_16x16x32_bf16 v[106:109], v[218:221], v[202:205], v[106:109]
	v_mfma_f32_16x16x32_bf16 v[110:113], v[222:225], v[202:205], v[110:113]
	v_mfma_f32_16x16x32_bf16 v[114:117], v[210:213], v[206:209], v[114:117]
	v_mfma_f32_16x16x32_bf16 v[118:121], v[214:217], v[206:209], v[118:121]
	v_mfma_f32_16x16x32_bf16 v[122:125], v[218:221], v[206:209], v[122:125]
	global_load_lds_dwordx4 v231, s[56:57] offset:1024
	v_mfma_f32_16x16x32_bf16 v[126:129], v[222:225], v[206:209], v[126:129]
	s_setprio 0
	s_add_i32 s60, s60, 0x6000
	s_cmp_eq_u32 s60, 0x12000
	s_cselect_b32 s60, 0, s60
	s_add_u32 s54, s54, s72
	s_addc_u32 s55, s55, 0
	s_add_u32 s56, s56, s73
	s_addc_u32 s57, s57, 0
	s_add_i32 s61, s61, 0x6000
	s_cmp_eq_u32 s61, 0x12000
	s_cselect_b32 s61, 0, s61
	s_branch .Lup_main

.Lup_nn_b:
	s_waitcnt vmcnt(14) lgkmcnt(0)
	v_add_u32_e32 v240, s61, v238
	v_add_u32_e32 v241, s61, v239
	s_setprio 1
	v_mfma_f32_16x16x32_bf16 v[2:5], v[162:165], v[130:133], 0
	v_mfma_f32_16x16x32_bf16 v[6:9], v[166:169], v[130:133], 0
	v_mfma_f32_16x16x32_bf16 v[10:13], v[170:173], v[130:133], 0
	v_mfma_f32_16x16x32_bf16 v[14:17], v[174:177], v[130:133], 0
	s_barrier
	v_mfma_f32_16x16x32_bf16 v[18:21], v[162:165], v[134:137], 0
	s_add_i32 m0, s60, s62
	v_mfma_f32_16x16x32_bf16 v[22:25], v[166:169], v[134:137], 0
	global_load_lds_dwordx4 v226, s[54:55]
	v_mfma_f32_16x16x32_bf16 v[26:29], v[170:173], v[134:137], 0
	v_mfma_f32_16x16x32_bf16 v[30:33], v[174:177], v[134:137], 0
	v_mfma_f32_16x16x32_bf16 v[34:37], v[162:165], v[138:141], 0
	ds_read_b128 v[210:213], v241 offset:0
	v_mfma_f32_16x16x32_bf16 v[38:41], v[166:169], v[138:141], 0
	ds_read_b128 v[214:217], v241 offset:256
	v_mfma_f32_16x16x32_bf16 v[42:45], v[170:173], v[138:141], 0
	ds_read_b128 v[218:221], v241 offset:2048
	global_load_lds_dwordx4 v226, s[54:55] offset:1024
	v_mfma_f32_16x16x32_bf16 v[46:49], v[174:177], v[138:141], 0
	ds_read_b128 v[222:225], v241 offset:2304
	v_mfma_f32_16x16x32_bf16 v[50:53], v[162:165], v[142:145], 0
	ds_read_b128 v[178:181], v240 offset:0
	v_mfma_f32_16x16x32_bf16 v[54:57], v[166:169], v[142:145], 0
	ds_read_b128 v[182:185], v240 offset:1024
	v_mfma_f32_16x16x32_bf16 v[58:61], v[170:173], v[142:145], 0
	ds_read_b128 v[186:189], v240 offset:2048
	v_mfma_f32_16x16x32_bf16 v[62:65], v[174:177], v[142:145], 0
	ds_read_b128 v[190:193], v240 offset:3072
	global_load_lds_dwordx4 v226, s[54:55] offset:2048
	v_mfma_f32_16x16x32_bf16 v[66:69], v[162:165], v[146:149], 0
	ds_read_b128 v[194:197], v240 offset:4096
	v_mfma_f32_16x16x32_bf16 v[70:73], v[166:169], v[146:149], 0
	ds_read_b128 v[198:201], v240 offset:5120
	v_mfma_f32_16x16x32_bf16 v[74:77], v[170:173], v[146:149], 0
	ds_read_b128 v[202:205], v240 offset:6144
	v_mfma_f32_16x16x32_bf16 v[78:81], v[174:177], v[146:149], 0
	ds_read_b128 v[206:209], v240 offset:7168
	v_mfma_f32_16x16x32_bf16 v[82:85], v[162:165], v[150:153], 0
	global_load_lds_dwordx4 v226, s[54:55] offset:3072
	v_mfma_f32_16x16x32_bf16 v[86:89], v[166:169], v[150:153], 0
	v_mfma_f32_16x16x32_bf16 v[90:93], v[170:173], v[150:153], 0
	v_mfma_f32_16x16x32_bf16 v[94:97], v[174:177], v[150:153], 0
	v_mfma_f32_16x16x32_bf16 v[98:101], v[162:165], v[154:157], 0
	s_add_i32 m0, s60, s63
	v_mfma_f32_16x16x32_bf16 v[102:105], v[166:169], v[154:157], 0
	global_load_lds_dwordx4 v230, s[56:57]
	v_mfma_f32_16x16x32_bf16 v[106:109], v[170:173], v[154:157], 0
	v_mfma_f32_16x16x32_bf16 v[110:113], v[174:177], v[154:157], 0
	v_mfma_f32_16x16x32_bf16 v[114:117], v[162:165], v[158:161], 0
	v_mfma_f32_16x16x32_bf16 v[118:121], v[166:169], v[158:161], 0
	v_mfma_f32_16x16x32_bf16 v[122:125], v[170:173], v[158:161], 0
	global_load_lds_dwordx4 v231, s[56:57] offset:1024
	v_mfma_f32_16x16x32_bf16 v[126:129], v[174:177], v[158:161], 0
	s_setprio 0
	s_add_i32 s60, s60, 0x6000
	s_cmp_eq_u32 s60, 0x12000
	s_cselect_b32 s60, 0, s60
	s_add_u32 s54, s54, s72
	s_addc_u32 s55, s55, 0
	s_add_u32 s56, s56, s73
	s_addc_u32 s57, s57, 0
	s_add_i32 s61, s61, 0x6000
	s_cmp_eq_u32 s61, 0x12000
	s_cselect_b32 s61, 0, s61
	v_mbcnt_lo_u32_b32 v0, -1, 0
	v_lshlrev_b32_e32 v0, 4, v0
	s_lshl_b32 s26, s36, 1
	v_add_u32_e32 v0, s26, v0
	s_lshl_b32 s26, s41, 8
	s_add_i32 m0, s26, 0x13010
	s_mov_b64 exec, 0xffff
	global_load_lds_dwordx4 v0, s[82:83]
	s_mov_b64 exec, -1
	s_waitcnt vmcnt(14) lgkmcnt(0)
	v_add_u32_e32 v240, s61, v238
	v_add_u32_e32 v241, s61, v239
	s_setprio 1
	v_mfma_f32_16x16x32_bf16 v[2:5], v[210:213], v[178:181], v[2:5]
	v_mfma_f32_16x16x32_bf16 v[6:9], v[214:217], v[178:181], v[6:9]
	v_mfma_f32_16x16x32_bf16 v[10:13], v[218:221], v[178:181], v[10:13]
	v_mfma_f32_16x16x32_bf16 v[14:17], v[222:225], v[178:181], v[14:17]
	s_barrier
	v_mfma_f32_16x16x32_bf16 v[18:21], v[210:213], v[182:185], v[18:21]
	s_add_i32 m0, s60, s62
	v_mfma_f32_16x16x32_bf16 v[22:25], v[214:217], v[182:185], v[22:25]
	global_load_lds_dwordx4 v226, s[54:55]
	v_mfma_f32_16x16x32_bf16 v[26:29], v[218:221], v[182:185], v[26:29]
	v_mfma_f32_16x16x32_bf16 v[30:33], v[222:225], v[182:185], v[30:33]
	v_mfma_f32_16x16x32_bf16 v[34:37], v[210:213], v[186:189], v[34:37]
	ds_read_b128 v[162:165], v241 offset:0
	v_mfma_f32_16x16x32_bf16 v[38:41], v[214:217], v[186:189], v[38:41]
	ds_read_b128 v[166:169], v241 offset:256
	v_mfma_f32_16x16x32_bf16 v[42:45], v[218:221], v[186:189], v[42:45]
	ds_read_b128 v[170:173], v241 offset:2048
	global_load_lds_dwordx4 v226, s[54:55] offset:1024
	v_mfma_f32_16x16x32_bf16 v[46:49], v[222:225], v[186:189], v[46:49]
	ds_read_b128 v[174:177], v241 offset:2304
	v_mfma_f32_16x16x32_bf16 v[50:53], v[210:213], v[190:193], v[50:53]
	ds_read_b128 v[130:133], v240 offset:0
	v_mfma_f32_16x16x32_bf16 v[54:57], v[214:217], v[190:193], v[54:57]
	ds_read_b128 v[134:137], v240 offset:1024
	v_mfma_f32_16x16x32_bf16 v[58:61], v[218:221], v[190:193], v[58:61]
	ds_read_b128 v[138:141], v240 offset:2048
	v_mfma_f32_16x16x32_bf16 v[62:65], v[222:225], v[190:193], v[62:65]
	ds_read_b128 v[142:145], v240 offset:3072
	global_load_lds_dwordx4 v226, s[54:55] offset:2048
	v_mfma_f32_16x16x32_bf16 v[66:69], v[210:213], v[194:197], v[66:69]
	ds_read_b128 v[146:149], v240 offset:4096
	v_mfma_f32_16x16x32_bf16 v[70:73], v[214:217], v[194:197], v[70:73]
	ds_read_b128 v[150:153], v240 offset:5120
	v_mfma_f32_16x16x32_bf16 v[74:77], v[218:221], v[194:197], v[74:77]
	ds_read_b128 v[154:157], v240 offset:6144
	v_mfma_f32_16x16x32_bf16 v[78:81], v[222:225], v[194:197], v[78:81]
	ds_read_b128 v[158:161], v240 offset:7168
	v_mfma_f32_16x16x32_bf16 v[82:85], v[210:213], v[198:201], v[82:85]
	global_load_lds_dwordx4 v226, s[54:55] offset:3072
	v_mfma_f32_16x16x32_bf16 v[86:89], v[214:217], v[198:201], v[86:89]
	v_mfma_f32_16x16x32_bf16 v[90:93], v[218:221], v[198:201], v[90:93]
	v_mfma_f32_16x16x32_bf16 v[94:97], v[222:225], v[198:201], v[94:97]
	v_mfma_f32_16x16x32_bf16 v[98:101], v[210:213], v[202:205], v[98:101]
	s_add_i32 m0, s60, s63
	v_mfma_f32_16x16x32_bf16 v[102:105], v[214:217], v[202:205], v[102:105]
	global_load_lds_dwordx4 v230, s[56:57]
	v_mfma_f32_16x16x32_bf16 v[106:109], v[218:221], v[202:205], v[106:109]
	v_mfma_f32_16x16x32_bf16 v[110:113], v[222:225], v[202:205], v[110:113]
	v_mfma_f32_16x16x32_bf16 v[114:117], v[210:213], v[206:209], v[114:117]
	v_mfma_f32_16x16x32_bf16 v[118:121], v[214:217], v[206:209], v[118:121]
	v_mfma_f32_16x16x32_bf16 v[122:125], v[218:221], v[206:209], v[122:125]
	global_load_lds_dwordx4 v231, s[56:57] offset:1024
	v_mfma_f32_16x16x32_bf16 v[126:129], v[222:225], v[206:209], v[126:129]
	s_setprio 0
	s_add_i32 s60, s60, 0x6000
	s_cmp_eq_u32 s60, 0x12000
	s_cselect_b32 s60, 0, s60
	s_add_u32 s54, s54, s72
	s_addc_u32 s55, s55, 0
	s_add_u32 s56, s56, s73
	s_addc_u32 s57, s57, 0
	s_add_i32 s61, s61, 0x6000
	s_cmp_eq_u32 s61, 0x12000
	s_cselect_b32 s61, 0, s61

.Lup_kloop:
	s_waitcnt vmcnt(6) lgkmcnt(0)
	v_add_u32_e32 v240, s61, v238
	v_add_u32_e32 v241, s61, v239
	s_setprio 1
	v_mfma_f32_16x16x32_bf16 v[2:5], v[162:165], v[130:133], v[2:5]
	v_mfma_f32_16x16x32_bf16 v[6:9], v[166:169], v[130:133], v[6:9]
	v_mfma_f32_16x16x32_bf16 v[10:13], v[170:173], v[130:133], v[10:13]
	v_mfma_f32_16x16x32_bf16 v[14:17], v[174:177], v[130:133], v[14:17]
	s_barrier
	v_mfma_f32_16x16x32_bf16 v[18:21], v[162:165], v[134:137], v[18:21]
	s_add_i32 m0, s60, s62
	v_mfma_f32_16x16x32_bf16 v[22:25], v[166:169], v[134:137], v[22:25]
	global_load_lds_dwordx4 v226, s[54:55]
	v_mfma_f32_16x16x32_bf16 v[26:29], v[170:173], v[134:137], v[26:29]
	v_mfma_f32_16x16x32_bf16 v[30:33], v[174:177], v[134:137], v[30:33]
	v_mfma_f32_16x16x32_bf16 v[34:37], v[162:165], v[138:141], v[34:37]
	ds_read_b128 v[210:213], v241 offset:0
	v_mfma_f32_16x16x32_bf16 v[38:41], v[166:169], v[138:141], v[38:41]
	ds_read_b128 v[214:217], v241 offset:256
	v_mfma_f32_16x16x32_bf16 v[42:45], v[170:173], v[138:141], v[42:45]
	ds_read_b128 v[218:221], v241 offset:2048
	global_load_lds_dwordx4 v226, s[54:55] offset:1024
	v_mfma_f32_16x16x32_bf16 v[46:49], v[174:177], v[138:141], v[46:49]
	ds_read_b128 v[222:225], v241 offset:2304
	v_mfma_f32_16x16x32_bf16 v[50:53], v[162:165], v[142:145], v[50:53]
	ds_read_b128 v[178:181], v240 offset:0
	v_mfma_f32_16x16x32_bf16 v[54:57], v[166:169], v[142:145], v[54:57]
	ds_read_b128 v[182:185], v240 offset:1024
	v_mfma_f32_16x16x32_bf16 v[58:61], v[170:173], v[142:145], v[58:61]
	ds_read_b128 v[186:189], v240 offset:2048
	v_mfma_f32_16x16x32_bf16 v[62:65], v[174:177], v[142:145], v[62:65]
	ds_read_b128 v[190:193], v240 offset:3072
	global_load_lds_dwordx4 v226, s[54:55] offset:2048
	v_mfma_f32_16x16x32_bf16 v[66:69], v[162:165], v[146:149], v[66:69]
	ds_read_b128 v[194:197], v240 offset:4096
	v_mfma_f32_16x16x32_bf16 v[70:73], v[166:169], v[146:149], v[70:73]
	ds_read_b128 v[198:201], v240 offset:5120
	v_mfma_f32_16x16x32_bf16 v[74:77], v[170:173], v[146:149], v[74:77]
	ds_read_b128 v[202:205], v240 offset:6144
	v_mfma_f32_16x16x32_bf16 v[78:81], v[174:177], v[146:149], v[78:81]
	ds_read_b128 v[206:209], v240 offset:7168
	v_mfma_f32_16x16x32_bf16 v[82:85], v[162:165], v[150:153], v[82:85]
	global_load_lds_dwordx4 v226, s[54:55] offset:3072
	v_mfma_f32_16x16x32_bf16 v[86:89], v[166:169], v[150:153], v[86:89]
	v_mfma_f32_16x16x32_bf16 v[90:93], v[170:173], v[150:153], v[90:93]
	v_mfma_f32_16x16x32_bf16 v[94:97], v[174:177], v[150:153], v[94:97]
	v_mfma_f32_16x16x32_bf16 v[98:101], v[162:165], v[154:157], v[98:101]
	s_add_i32 m0, s60, s63
	v_mfma_f32_16x16x32_bf16 v[102:105], v[166:169], v[154:157], v[102:105]
	global_load_lds_dwordx4 v230, s[56:57]
	v_mfma_f32_16x16x32_bf16 v[106:109], v[170:173], v[154:157], v[106:109]
	v_mfma_f32_16x16x32_bf16 v[110:113], v[174:177], v[154:157], v[110:113]
	v_mfma_f32_16x16x32_bf16 v[114:117], v[162:165], v[158:161], v[114:117]
	v_mfma_f32_16x16x32_bf16 v[118:121], v[166:169], v[158:161], v[118:121]
	v_mfma_f32_16x16x32_bf16 v[122:125], v[170:173], v[158:161], v[122:125]
	global_load_lds_dwordx4 v231, s[56:57] offset:1024
	v_mfma_f32_16x16x32_bf16 v[126:129], v[174:177], v[158:161], v[126:129]
	s_setprio 0
	s_add_i32 s60, s60, 0x6000
	s_cmp_eq_u32 s60, 0x12000
	s_cselect_b32 s60, 0, s60
	s_add_u32 s54, s54, s72
	s_addc_u32 s55, s55, 0
	s_add_u32 s56, s56, s73
	s_addc_u32 s57, s57, 0
	s_add_i32 s61, s61, 0x6000
	s_cmp_eq_u32 s61, 0x12000
	s_cselect_b32 s61, 0, s61
	s_waitcnt vmcnt(6) lgkmcnt(0)
	v_add_u32_e32 v240, s61, v238
	v_add_u32_e32 v241, s61, v239
	s_setprio 1
	v_mfma_f32_16x16x32_bf16 v[2:5], v[210:213], v[178:181], v[2:5]
	v_mfma_f32_16x16x32_bf16 v[6:9], v[214:217], v[178:181], v[6:9]
	v_mfma_f32_16x16x32_bf16 v[10:13], v[218:221], v[178:181], v[10:13]
	v_mfma_f32_16x16x32_bf16 v[14:17], v[222:225], v[178:181], v[14:17]
	s_barrier
	v_mfma_f32_16x16x32_bf16 v[18:21], v[210:213], v[182:185], v[18:21]
	s_add_i32 m0, s60, s62
	v_mfma_f32_16x16x32_bf16 v[22:25], v[214:217], v[182:185], v[22:25]
	global_load_lds_dwordx4 v226, s[54:55]
	v_mfma_f32_16x16x32_bf16 v[26:29], v[218:221], v[182:185], v[26:29]
	v_mfma_f32_16x16x32_bf16 v[30:33], v[222:225], v[182:185], v[30:33]
	v_mfma_f32_16x16x32_bf16 v[34:37], v[210:213], v[186:189], v[34:37]
	ds_read_b128 v[162:165], v241 offset:0
	v_mfma_f32_16x16x32_bf16 v[38:41], v[214:217], v[186:189], v[38:41]
	ds_read_b128 v[166:169], v241 offset:256
	v_mfma_f32_16x16x32_bf16 v[42:45], v[218:221], v[186:189], v[42:45]
	ds_read_b128 v[170:173], v241 offset:2048
	global_load_lds_dwordx4 v226, s[54:55] offset:1024
	v_mfma_f32_16x16x32_bf16 v[46:49], v[222:225], v[186:189], v[46:49]
	ds_read_b128 v[174:177], v241 offset:2304
	v_mfma_f32_16x16x32_bf16 v[50:53], v[210:213], v[190:193], v[50:53]
	ds_read_b128 v[130:133], v240 offset:0
	v_mfma_f32_16x16x32_bf16 v[54:57], v[214:217], v[190:193], v[54:57]
	ds_read_b128 v[134:137], v240 offset:1024
	v_mfma_f32_16x16x32_bf16 v[58:61], v[218:221], v[190:193], v[58:61]
	ds_read_b128 v[138:141], v240 offset:2048
	v_mfma_f32_16x16x32_bf16 v[62:65], v[222:225], v[190:193], v[62:65]
	ds_read_b128 v[142:145], v240 offset:3072
	global_load_lds_dwordx4 v226, s[54:55] offset:2048
	v_mfma_f32_16x16x32_bf16 v[66:69], v[210:213], v[194:197], v[66:69]
	ds_read_b128 v[146:149], v240 offset:4096
	v_mfma_f32_16x16x32_bf16 v[70:73], v[214:217], v[194:197], v[70:73]
	ds_read_b128 v[150:153], v240 offset:5120
	v_mfma_f32_16x16x32_bf16 v[74:77], v[218:221], v[194:197], v[74:77]
	ds_read_b128 v[154:157], v240 offset:6144
	v_mfma_f32_16x16x32_bf16 v[78:81], v[222:225], v[194:197], v[78:81]
	ds_read_b128 v[158:161], v240 offset:7168
	v_mfma_f32_16x16x32_bf16 v[82:85], v[210:213], v[198:201], v[82:85]
	global_load_lds_dwordx4 v226, s[54:55] offset:3072
	v_mfma_f32_16x16x32_bf16 v[86:89], v[214:217], v[198:201], v[86:89]
	v_mfma_f32_16x16x32_bf16 v[90:93], v[218:221], v[198:201], v[90:93]
	v_mfma_f32_16x16x32_bf16 v[94:97], v[222:225], v[198:201], v[94:97]
	v_mfma_f32_16x16x32_bf16 v[98:101], v[210:213], v[202:205], v[98:101]
	s_add_i32 m0, s60, s63
	v_mfma_f32_16x16x32_bf16 v[102:105], v[214:217], v[202:205], v[102:105]
	global_load_lds_dwordx4 v230, s[56:57]
	v_mfma_f32_16x16x32_bf16 v[106:109], v[218:221], v[202:205], v[106:109]
	v_mfma_f32_16x16x32_bf16 v[110:113], v[222:225], v[202:205], v[110:113]
	v_mfma_f32_16x16x32_bf16 v[114:117], v[210:213], v[206:209], v[114:117]
	v_mfma_f32_16x16x32_bf16 v[118:121], v[214:217], v[206:209], v[118:121]
	v_mfma_f32_16x16x32_bf16 v[122:125], v[218:221], v[206:209], v[122:125]
	global_load_lds_dwordx4 v231, s[56:57] offset:1024
	v_mfma_f32_16x16x32_bf16 v[126:129], v[222:225], v[206:209], v[126:129]
	s_setprio 0
	s_add_i32 s60, s60, 0x6000
	s_cmp_eq_u32 s60, 0x12000
	s_cselect_b32 s60, 0, s60
	s_add_u32 s54, s54, s72
	s_addc_u32 s55, s55, 0
	s_add_u32 s56, s56, s73
	s_addc_u32 s57, s57, 0
	s_add_i32 s61, s61, 0x6000
	s_cmp_eq_u32 s61, 0x12000
	s_cselect_b32 s61, 0, s61
	s_add_i32 s40, s40, -1
	s_cmp_lg_u32 s40, 0
	s_cbranch_scc1 .Lup_kloop
.Lup_kdone:
	s_cmp_eq_u32 s37, 0
	s_cbranch_scc1 .Lup_tail_last
	s_waitcnt vmcnt(6) lgkmcnt(0)
	v_add_u32_e32 v240, s61, v238
	v_add_u32_e32 v241, s61, v239
	s_setprio 1
	v_mfma_f32_16x16x32_bf16 v[2:5], v[162:165], v[130:133], v[2:5]
	v_mfma_f32_16x16x32_bf16 v[6:9], v[166:169], v[130:133], v[6:9]
	v_mfma_f32_16x16x32_bf16 v[10:13], v[170:173], v[130:133], v[10:13]
	v_mfma_f32_16x16x32_bf16 v[14:17], v[174:177], v[130:133], v[14:17]
	s_barrier
	v_mfma_f32_16x16x32_bf16 v[18:21], v[162:165], v[134:137], v[18:21]
	s_add_i32 m0, s60, s62
	v_mfma_f32_16x16x32_bf16 v[22:25], v[166:169], v[134:137], v[22:25]
	global_load_lds_dwordx4 v226, s[54:55]
	v_mfma_f32_16x16x32_bf16 v[26:29], v[170:173], v[134:137], v[26:29]
	v_mfma_f32_16x16x32_bf16 v[30:33], v[174:177], v[134:137], v[30:33]
	v_mfma_f32_16x16x32_bf16 v[34:37], v[162:165], v[138:141], v[34:37]
	ds_read_b128 v[210:213], v241 offset:0
	v_mfma_f32_16x16x32_bf16 v[38:41], v[166:169], v[138:141], v[38:41]
	ds_read_b128 v[214:217], v241 offset:256
	v_mfma_f32_16x16x32_bf16 v[42:45], v[170:173], v[138:141], v[42:45]
	ds_read_b128 v[218:221], v241 offset:2048
	global_load_lds_dwordx4 v226, s[54:55] offset:1024
	v_mfma_f32_16x16x32_bf16 v[46:49], v[174:177], v[138:141], v[46:49]
	ds_read_b128 v[222:225], v241 offset:2304
	v_mfma_f32_16x16x32_bf16 v[50:53], v[162:165], v[142:145], v[50:53]
	ds_read_b128 v[178:181], v240 offset:0
	v_mfma_f32_16x16x32_bf16 v[54:57], v[166:169], v[142:145], v[54:57]
	ds_read_b128 v[182:185], v240 offset:1024
	v_mfma_f32_16x16x32_bf16 v[58:61], v[170:173], v[142:145], v[58:61]
	ds_read_b128 v[186:189], v240 offset:2048
	v_mfma_f32_16x16x32_bf16 v[62:65], v[174:177], v[142:145], v[62:65]
	ds_read_b128 v[190:193], v240 offset:3072
	global_load_lds_dwordx4 v226, s[54:55] offset:2048
	v_mfma_f32_16x16x32_bf16 v[66:69], v[162:165], v[146:149], v[66:69]
	ds_read_b128 v[194:197], v240 offset:4096
	v_mfma_f32_16x16x32_bf16 v[70:73], v[166:169], v[146:149], v[70:73]
	ds_read_b128 v[198:201], v240 offset:5120
	v_mfma_f32_16x16x32_bf16 v[74:77], v[170:173], v[146:149], v[74:77]
	ds_read_b128 v[202:205], v240 offset:6144
	v_mfma_f32_16x16x32_bf16 v[78:81], v[174:177], v[146:149], v[78:81]
	ds_read_b128 v[206:209], v240 offset:7168
	v_mfma_f32_16x16x32_bf16 v[82:85], v[162:165], v[150:153], v[82:85]
	global_load_lds_dwordx4 v226, s[54:55] offset:3072
	v_mfma_f32_16x16x32_bf16 v[86:89], v[166:169], v[150:153], v[86:89]
	v_mfma_f32_16x16x32_bf16 v[90:93], v[170:173], v[150:153], v[90:93]
	v_mfma_f32_16x16x32_bf16 v[94:97], v[174:177], v[150:153], v[94:97]
	v_mfma_f32_16x16x32_bf16 v[98:101], v[162:165], v[154:157], v[98:101]
	s_add_i32 m0, s60, s63
	v_mfma_f32_16x16x32_bf16 v[102:105], v[166:169], v[154:157], v[102:105]
	global_load_lds_dwordx4 v230, s[56:57]
	v_mfma_f32_16x16x32_bf16 v[106:109], v[170:173], v[154:157], v[106:109]
	v_mfma_f32_16x16x32_bf16 v[110:113], v[174:177], v[154:157], v[110:113]
	v_mfma_f32_16x16x32_bf16 v[114:117], v[162:165], v[158:161], v[114:117]
	v_mfma_f32_16x16x32_bf16 v[118:121], v[166:169], v[158:161], v[118:121]
	v_mfma_f32_16x16x32_bf16 v[122:125], v[170:173], v[158:161], v[122:125]
	global_load_lds_dwordx4 v231, s[56:57] offset:1024
	v_mfma_f32_16x16x32_bf16 v[126:129], v[174:177], v[158:161], v[126:129]
	s_setprio 0
	s_add_i32 s60, s60, 0x6000
	s_cmp_eq_u32 s60, 0x12000
	s_cselect_b32 s60, 0, s60
	s_add_u32 s54, s54, s72
	s_addc_u32 s55, s55, 0
	s_add_u32 s56, s56, s73
	s_addc_u32 s57, s57, 0
	s_add_i32 s61, s61, 0x6000
	s_cmp_eq_u32 s61, 0x12000
	s_cselect_b32 s61, 0, s61
	v_mov_b32_e32 v226, v232
	v_mov_b32_e32 v230, v236
	v_mov_b32_e32 v231, v237
	s_mov_b64 s[54:55], s[48:49]
	s_mov_b64 s[56:57], s[50:51]
	s_waitcnt vmcnt(6) lgkmcnt(0)
	v_add_u32_e32 v240, s61, v238
	v_add_u32_e32 v241, s61, v239
	s_setprio 1
	v_mfma_f32_16x16x32_bf16 v[2:5], v[210:213], v[178:181], v[2:5]
	v_mfma_f32_16x16x32_bf16 v[6:9], v[214:217], v[178:181], v[6:9]
	v_mfma_f32_16x16x32_bf16 v[10:13], v[218:221], v[178:181], v[10:13]
	v_mfma_f32_16x16x32_bf16 v[14:17], v[222:225], v[178:181], v[14:17]
	s_barrier
	v_mfma_f32_16x16x32_bf16 v[18:21], v[210:213], v[182:185], v[18:21]
	s_add_i32 m0, s60, s62
	v_mfma_f32_16x16x32_bf16 v[22:25], v[214:217], v[182:185], v[22:25]
	global_load_lds_dwordx4 v226, s[54:55]
	v_mfma_f32_16x16x32_bf16 v[26:29], v[218:221], v[182:185], v[26:29]
	v_mfma_f32_16x16x32_bf16 v[30:33], v[222:225], v[182:185], v[30:33]
	v_mfma_f32_16x16x32_bf16 v[34:37], v[210:213], v[186:189], v[34:37]
	ds_read_b128 v[162:165], v241 offset:0
	v_mfma_f32_16x16x32_bf16 v[38:41], v[214:217], v[186:189], v[38:41]
	ds_read_b128 v[166:169], v241 offset:256
	v_mfma_f32_16x16x32_bf16 v[42:45], v[218:221], v[186:189], v[42:45]
	ds_read_b128 v[170:173], v241 offset:2048
	global_load_lds_dwordx4 v226, s[54:55] offset:1024
	v_mfma_f32_16x16x32_bf16 v[46:49], v[222:225], v[186:189], v[46:49]
	ds_read_b128 v[174:177], v241 offset:2304
	v_mfma_f32_16x16x32_bf16 v[50:53], v[210:213], v[190:193], v[50:53]
	ds_read_b128 v[130:133], v240 offset:0
	v_mfma_f32_16x16x32_bf16 v[54:57], v[214:217], v[190:193], v[54:57]
	ds_read_b128 v[134:137], v240 offset:1024
	v_mfma_f32_16x16x32_bf16 v[58:61], v[218:221], v[190:193], v[58:61]
	ds_read_b128 v[138:141], v240 offset:2048
	v_mfma_f32_16x16x32_bf16 v[62:65], v[222:225], v[190:193], v[62:65]
	ds_read_b128 v[142:145], v240 offset:3072
	global_load_lds_dwordx4 v226, s[54:55] offset:2048
	v_mfma_f32_16x16x32_bf16 v[66:69], v[210:213], v[194:197], v[66:69]
	ds_read_b128 v[146:149], v240 offset:4096
	v_mfma_f32_16x16x32_bf16 v[70:73], v[214:217], v[194:197], v[70:73]
	ds_read_b128 v[150:153], v240 offset:5120
	v_mfma_f32_16x16x32_bf16 v[74:77], v[218:221], v[194:197], v[74:77]
	ds_read_b128 v[154:157], v240 offset:6144
	v_mfma_f32_16x16x32_bf16 v[78:81], v[222:225], v[194:197], v[78:81]
	ds_read_b128 v[158:161], v240 offset:7168
	v_mfma_f32_16x16x32_bf16 v[82:85], v[210:213], v[198:201], v[82:85]
	global_load_lds_dwordx4 v226, s[54:55] offset:3072
	v_mfma_f32_16x16x32_bf16 v[86:89], v[214:217], v[198:201], v[86:89]
	v_mfma_f32_16x16x32_bf16 v[90:93], v[218:221], v[198:201], v[90:93]
	v_mfma_f32_16x16x32_bf16 v[94:97], v[222:225], v[198:201], v[94:97]
	v_mfma_f32_16x16x32_bf16 v[98:101], v[210:213], v[202:205], v[98:101]
	s_add_i32 m0, s60, s63
	v_mfma_f32_16x16x32_bf16 v[102:105], v[214:217], v[202:205], v[102:105]
	global_load_lds_dwordx4 v230, s[56:57]
	v_mfma_f32_16x16x32_bf16 v[106:109], v[218:221], v[202:205], v[106:109]
	v_mfma_f32_16x16x32_bf16 v[110:113], v[222:225], v[202:205], v[110:113]
	v_mfma_f32_16x16x32_bf16 v[114:117], v[210:213], v[206:209], v[114:117]
	v_mfma_f32_16x16x32_bf16 v[118:121], v[214:217], v[206:209], v[118:121]
	v_mfma_f32_16x16x32_bf16 v[122:125], v[218:221], v[206:209], v[122:125]
	global_load_lds_dwordx4 v231, s[56:57] offset:1024
	v_mfma_f32_16x16x32_bf16 v[126:129], v[222:225], v[206:209], v[126:129]
	s_setprio 0
	s_add_i32 s60, s60, 0x6000
	s_cmp_eq_u32 s60, 0x12000
	s_cselect_b32 s60, 0, s60
	s_add_u32 s54, s54, s72
	s_addc_u32 s55, s55, 0
	s_add_u32 s56, s56, s73
	s_addc_u32 s57, s57, 0
	s_add_i32 s61, s61, 0x6000
	s_cmp_eq_u32 s61, 0x12000
	s_cselect_b32 s61, 0, s61
	s_waitcnt vmcnt(6) lgkmcnt(0)
	v_add_u32_e32 v240, s61, v238
	v_add_u32_e32 v241, s61, v239
	s_setprio 1
	v_mfma_f32_16x16x32_bf16 v[2:5], v[162:165], v[130:133], v[2:5]
	v_mfma_f32_16x16x32_bf16 v[6:9], v[166:169], v[130:133], v[6:9]
	v_mfma_f32_16x16x32_bf16 v[10:13], v[170:173], v[130:133], v[10:13]
	v_mfma_f32_16x16x32_bf16 v[14:17], v[174:177], v[130:133], v[14:17]
	s_barrier
	v_mfma_f32_16x16x32_bf16 v[18:21], v[162:165], v[134:137], v[18:21]
	s_add_i32 m0, s60, s62
	v_mfma_f32_16x16x32_bf16 v[22:25], v[166:169], v[134:137], v[22:25]
	global_load_lds_dwordx4 v226, s[54:55]
	v_mfma_f32_16x16x32_bf16 v[26:29], v[170:173], v[134:137], v[26:29]
	v_mfma_f32_16x16x32_bf16 v[30:33], v[174:177], v[134:137], v[30:33]
	v_mfma_f32_16x16x32_bf16 v[34:37], v[162:165], v[138:141], v[34:37]
	ds_read_b128 v[210:213], v241 offset:0
	v_mfma_f32_16x16x32_bf16 v[38:41], v[166:169], v[138:141], v[38:41]
	ds_read_b128 v[214:217], v241 offset:256
	v_mfma_f32_16x16x32_bf16 v[42:45], v[170:173], v[138:141], v[42:45]
	ds_read_b128 v[218:221], v241 offset:2048
	global_load_lds_dwordx4 v226, s[54:55] offset:1024
	v_mfma_f32_16x16x32_bf16 v[46:49], v[174:177], v[138:141], v[46:49]
	ds_read_b128 v[222:225], v241 offset:2304
	v_mfma_f32_16x16x32_bf16 v[50:53], v[162:165], v[142:145], v[50:53]
	ds_read_b128 v[178:181], v240 offset:0
	v_mfma_f32_16x16x32_bf16 v[54:57], v[166:169], v[142:145], v[54:57]
	ds_read_b128 v[182:185], v240 offset:1024
	v_mfma_f32_16x16x32_bf16 v[58:61], v[170:173], v[142:145], v[58:61]
	ds_read_b128 v[186:189], v240 offset:2048
	v_mfma_f32_16x16x32_bf16 v[62:65], v[174:177], v[142:145], v[62:65]
	ds_read_b128 v[190:193], v240 offset:3072
	global_load_lds_dwordx4 v226, s[54:55] offset:2048
	v_mfma_f32_16x16x32_bf16 v[66:69], v[162:165], v[146:149], v[66:69]
	ds_read_b128 v[194:197], v240 offset:4096
	v_mfma_f32_16x16x32_bf16 v[70:73], v[166:169], v[146:149], v[70:73]
	ds_read_b128 v[198:201], v240 offset:5120
	v_mfma_f32_16x16x32_bf16 v[74:77], v[170:173], v[146:149], v[74:77]
	ds_read_b128 v[202:205], v240 offset:6144
	v_mfma_f32_16x16x32_bf16 v[78:81], v[174:177], v[146:149], v[78:81]
	ds_read_b128 v[206:209], v240 offset:7168
	v_mfma_f32_16x16x32_bf16 v[82:85], v[162:165], v[150:153], v[82:85]
	global_load_lds_dwordx4 v226, s[54:55] offset:3072
	v_mfma_f32_16x16x32_bf16 v[86:89], v[166:169], v[150:153], v[86:89]
	v_mfma_f32_16x16x32_bf16 v[90:93], v[170:173], v[150:153], v[90:93]
	v_mfma_f32_16x16x32_bf16 v[94:97], v[174:177], v[150:153], v[94:97]
	v_mfma_f32_16x16x32_bf16 v[98:101], v[162:165], v[154:157], v[98:101]
	s_add_i32 m0, s60, s63
	v_mfma_f32_16x16x32_bf16 v[102:105], v[166:169], v[154:157], v[102:105]
	global_load_lds_dwordx4 v230, s[56:57]
	v_mfma_f32_16x16x32_bf16 v[106:109], v[170:173], v[154:157], v[106:109]
	v_mfma_f32_16x16x32_bf16 v[110:113], v[174:177], v[154:157], v[110:113]
	v_mfma_f32_16x16x32_bf16 v[114:117], v[162:165], v[158:161], v[114:117]
	v_mfma_f32_16x16x32_bf16 v[118:121], v[166:169], v[158:161], v[118:121]
	v_mfma_f32_16x16x32_bf16 v[122:125], v[170:173], v[158:161], v[122:125]
	global_load_lds_dwordx4 v231, s[56:57] offset:1024
	v_mfma_f32_16x16x32_bf16 v[126:129], v[174:177], v[158:161], v[126:129]
	s_setprio 0
	s_add_i32 s60, s60, 0x6000
	s_cmp_eq_u32 s60, 0x12000
	s_cselect_b32 s60, 0, s60
	s_add_u32 s54, s54, s72
	s_addc_u32 s55, s55, 0
	s_add_u32 s56, s56, s73
	s_addc_u32 s57, s57, 0
	s_add_i32 s61, s61, 0x6000
	s_cmp_eq_u32 s61, 0x12000
	s_cselect_b32 s61, 0, s61
	s_waitcnt vmcnt(6) lgkmcnt(0)
	v_add_u32_e32 v240, s61, v238
	v_add_u32_e32 v241, s61, v239
	s_setprio 1
	v_mfma_f32_16x16x32_bf16 v[2:5], v[210:213], v[178:181], v[2:5]
	v_mfma_f32_16x16x32_bf16 v[6:9], v[214:217], v[178:181], v[6:9]
	v_mfma_f32_16x16x32_bf16 v[10:13], v[218:221], v[178:181], v[10:13]
	v_mfma_f32_16x16x32_bf16 v[14:17], v[222:225], v[178:181], v[14:17]
	s_barrier
	v_mfma_f32_16x16x32_bf16 v[18:21], v[210:213], v[182:185], v[18:21]
	s_add_i32 m0, s60, s62
	v_mfma_f32_16x16x32_bf16 v[22:25], v[214:217], v[182:185], v[22:25]
	global_load_lds_dwordx4 v226, s[54:55]
	v_mfma_f32_16x16x32_bf16 v[26:29], v[218:221], v[182:185], v[26:29]
	v_mfma_f32_16x16x32_bf16 v[30:33], v[222:225], v[182:185], v[30:33]
	v_mfma_f32_16x16x32_bf16 v[34:37], v[210:213], v[186:189], v[34:37]
	ds_read_b128 v[162:165], v241 offset:0
	v_mfma_f32_16x16x32_bf16 v[38:41], v[214:217], v[186:189], v[38:41]
	ds_read_b128 v[166:169], v241 offset:256
	v_mfma_f32_16x16x32_bf16 v[42:45], v[218:221], v[186:189], v[42:45]
	ds_read_b128 v[170:173], v241 offset:2048
	global_load_lds_dwordx4 v226, s[54:55] offset:1024
	v_mfma_f32_16x16x32_bf16 v[46:49], v[222:225], v[186:189], v[46:49]
	ds_read_b128 v[174:177], v241 offset:2304
	v_mfma_f32_16x16x32_bf16 v[50:53], v[210:213], v[190:193], v[50:53]
	ds_read_b128 v[130:133], v240 offset:0
	v_mfma_f32_16x16x32_bf16 v[54:57], v[214:217], v[190:193], v[54:57]
	ds_read_b128 v[134:137], v240 offset:1024
	v_mfma_f32_16x16x32_bf16 v[58:61], v[218:221], v[190:193], v[58:61]
	ds_read_b128 v[138:141], v240 offset:2048
	v_mfma_f32_16x16x32_bf16 v[62:65], v[222:225], v[190:193], v[62:65]
	ds_read_b128 v[142:145], v240 offset:3072
	global_load_lds_dwordx4 v226, s[54:55] offset:2048
	v_mfma_f32_16x16x32_bf16 v[66:69], v[210:213], v[194:197], v[66:69]
	ds_read_b128 v[146:149], v240 offset:4096
	v_mfma_f32_16x16x32_bf16 v[70:73], v[214:217], v[194:197], v[70:73]
	ds_read_b128 v[150:153], v240 offset:5120
	v_mfma_f32_16x16x32_bf16 v[74:77], v[218:221], v[194:197], v[74:77]
	ds_read_b128 v[154:157], v240 offset:6144
	v_mfma_f32_16x16x32_bf16 v[78:81], v[222:225], v[194:197], v[78:81]
	ds_read_b128 v[158:161], v240 offset:7168
	v_mfma_f32_16x16x32_bf16 v[82:85], v[210:213], v[198:201], v[82:85]
	global_load_lds_dwordx4 v226, s[54:55] offset:3072
	v_mfma_f32_16x16x32_bf16 v[86:89], v[214:217], v[198:201], v[86:89]
	v_mfma_f32_16x16x32_bf16 v[90:93], v[218:221], v[198:201], v[90:93]
	v_mfma_f32_16x16x32_bf16 v[94:97], v[222:225], v[198:201], v[94:97]
	v_mfma_f32_16x16x32_bf16 v[98:101], v[210:213], v[202:205], v[98:101]
	s_add_i32 m0, s60, s63
	v_mfma_f32_16x16x32_bf16 v[102:105], v[214:217], v[202:205], v[102:105]
	global_load_lds_dwordx4 v230, s[56:57]
	v_mfma_f32_16x16x32_bf16 v[106:109], v[218:221], v[202:205], v[106:109]
	v_mfma_f32_16x16x32_bf16 v[110:113], v[222:225], v[202:205], v[110:113]
	v_mfma_f32_16x16x32_bf16 v[114:117], v[210:213], v[206:209], v[114:117]
	v_mfma_f32_16x16x32_bf16 v[118:121], v[214:217], v[206:209], v[118:121]
	v_mfma_f32_16x16x32_bf16 v[122:125], v[218:221], v[206:209], v[122:125]
	global_load_lds_dwordx4 v231, s[56:57] offset:1024
	v_mfma_f32_16x16x32_bf16 v[126:129], v[222:225], v[206:209], v[126:129]
	s_setprio 0
	s_add_i32 s60, s60, 0x6000
	s_cmp_eq_u32 s60, 0x12000
	s_cselect_b32 s60, 0, s60
	s_add_u32 s54, s54, s72
	s_addc_u32 s55, s55, 0
	s_add_u32 s56, s56, s73
	s_addc_u32 s57, s57, 0
	s_add_i32 s61, s61, 0x6000
	s_cmp_eq_u32 s61, 0x12000
	s_cselect_b32 s61, 0, s61
	s_and_b32 s39, s35, 0xfff
	s_lshr_b32 s21, s36, 7
	s_waitcnt vmcnt(18)
	v_mbcnt_lo_u32_b32 v217, -1, 0
	v_mbcnt_hi_u32_b32 v217, -1, v217
	v_lshlrev_b32_e32 v217, 5, v217
	s_lshl_b32 s26, s43, 11
	v_add_u32_e32 v248, s26, v217
	s_add_i32 s26, s26, 0x12010
	v_add_u32_e32 v217, s26, v217
	s_cmp_eq_u32 s42, 0
	s_cbranch_scc0 .Lup_en_nowr
	ds_write_b128 v217, v[114:117]
	ds_write_b128 v217, v[118:121] offset:16
	s_branch .Lup_en_wrd

.Lup_tail_last:
	s_waitcnt vmcnt(6) lgkmcnt(0)
	v_add_u32_e32 v240, s61, v238
	v_add_u32_e32 v241, s61, v239
	s_setprio 1
	v_mfma_f32_16x16x32_bf16 v[2:5], v[162:165], v[130:133], v[2:5]
	v_mfma_f32_16x16x32_bf16 v[6:9], v[166:169], v[130:133], v[6:9]
	v_mfma_f32_16x16x32_bf16 v[10:13], v[170:173], v[130:133], v[10:13]
	v_mfma_f32_16x16x32_bf16 v[14:17], v[174:177], v[130:133], v[14:17]
	s_barrier
	v_mfma_f32_16x16x32_bf16 v[18:21], v[162:165], v[134:137], v[18:21]
	s_add_i32 m0, s60, s62
	v_mfma_f32_16x16x32_bf16 v[22:25], v[166:169], v[134:137], v[22:25]
	global_load_lds_dwordx4 v226, s[54:55]
	v_mfma_f32_16x16x32_bf16 v[26:29], v[170:173], v[134:137], v[26:29]
	v_mfma_f32_16x16x32_bf16 v[30:33], v[174:177], v[134:137], v[30:33]
	v_mfma_f32_16x16x32_bf16 v[34:37], v[162:165], v[138:141], v[34:37]
	ds_read_b128 v[210:213], v241 offset:0
	v_mfma_f32_16x16x32_bf16 v[38:41], v[166:169], v[138:141], v[38:41]
	ds_read_b128 v[214:217], v241 offset:256
	v_mfma_f32_16x16x32_bf16 v[42:45], v[170:173], v[138:141], v[42:45]
	ds_read_b128 v[218:221], v241 offset:2048
	global_load_lds_dwordx4 v226, s[54:55] offset:1024
	v_mfma_f32_16x16x32_bf16 v[46:49], v[174:177], v[138:141], v[46:49]
	ds_read_b128 v[222:225], v241 offset:2304
	v_mfma_f32_16x16x32_bf16 v[50:53], v[162:165], v[142:145], v[50:53]
	ds_read_b128 v[178:181], v240 offset:0
	v_mfma_f32_16x16x32_bf16 v[54:57], v[166:169], v[142:145], v[54:57]
	ds_read_b128 v[182:185], v240 offset:1024
	v_mfma_f32_16x16x32_bf16 v[58:61], v[170:173], v[142:145], v[58:61]
	ds_read_b128 v[186:189], v240 offset:2048
	v_mfma_f32_16x16x32_bf16 v[62:65], v[174:177], v[142:145], v[62:65]
	ds_read_b128 v[190:193], v240 offset:3072
	global_load_lds_dwordx4 v226, s[54:55] offset:2048
	v_mfma_f32_16x16x32_bf16 v[66:69], v[162:165], v[146:149], v[66:69]
	ds_read_b128 v[194:197], v240 offset:4096
	v_mfma_f32_16x16x32_bf16 v[70:73], v[166:169], v[146:149], v[70:73]
	ds_read_b128 v[198:201], v240 offset:5120
	v_mfma_f32_16x16x32_bf16 v[74:77], v[170:173], v[146:149], v[74:77]
	ds_read_b128 v[202:205], v240 offset:6144
	v_mfma_f32_16x16x32_bf16 v[78:81], v[174:177], v[146:149], v[78:81]
	ds_read_b128 v[206:209], v240 offset:7168
	v_mfma_f32_16x16x32_bf16 v[82:85], v[162:165], v[150:153], v[82:85]
	global_load_lds_dwordx4 v226, s[54:55] offset:3072
	v_mfma_f32_16x16x32_bf16 v[86:89], v[166:169], v[150:153], v[86:89]
	v_mfma_f32_16x16x32_bf16 v[90:93], v[170:173], v[150:153], v[90:93]
	v_mfma_f32_16x16x32_bf16 v[94:97], v[174:177], v[150:153], v[94:97]
	v_mfma_f32_16x16x32_bf16 v[98:101], v[162:165], v[154:157], v[98:101]
	s_add_i32 m0, s60, s63
	v_mfma_f32_16x16x32_bf16 v[102:105], v[166:169], v[154:157], v[102:105]
	global_load_lds_dwordx4 v230, s[56:57]
	v_mfma_f32_16x16x32_bf16 v[106:109], v[170:173], v[154:157], v[106:109]
	v_mfma_f32_16x16x32_bf16 v[110:113], v[174:177], v[154:157], v[110:113]
	v_mfma_f32_16x16x32_bf16 v[114:117], v[162:165], v[158:161], v[114:117]
	v_mfma_f32_16x16x32_bf16 v[118:121], v[166:169], v[158:161], v[118:121]
	v_mfma_f32_16x16x32_bf16 v[122:125], v[170:173], v[158:161], v[122:125]
	global_load_lds_dwordx4 v231, s[56:57] offset:1024
	v_mfma_f32_16x16x32_bf16 v[126:129], v[174:177], v[158:161], v[126:129]
	s_setprio 0
	s_add_i32 s60, s60, 0x6000
	s_cmp_eq_u32 s60, 0x12000
	s_cselect_b32 s60, 0, s60
	s_add_u32 s54, s54, s72
	s_addc_u32 s55, s55, 0
	s_add_u32 s56, s56, s73
	s_addc_u32 s57, s57, 0
	s_add_i32 s61, s61, 0x6000
	s_cmp_eq_u32 s61, 0x12000
	s_cselect_b32 s61, 0, s61
	s_waitcnt vmcnt(6) lgkmcnt(0)
	v_add_u32_e32 v240, s61, v238
	v_add_u32_e32 v241, s61, v239
	s_setprio 1
	v_mfma_f32_16x16x32_bf16 v[2:5], v[210:213], v[178:181], v[2:5]
	v_mfma_f32_16x16x32_bf16 v[6:9], v[214:217], v[178:181], v[6:9]
	v_mfma_f32_16x16x32_bf16 v[10:13], v[218:221], v[178:181], v[10:13]
	v_mfma_f32_16x16x32_bf16 v[14:17], v[222:225], v[178:181], v[14:17]
	s_barrier
	v_mfma_f32_16x16x32_bf16 v[18:21], v[210:213], v[182:185], v[18:21]
	v_mfma_f32_16x16x32_bf16 v[22:25], v[214:217], v[182:185], v[22:25]
	v_mfma_f32_16x16x32_bf16 v[26:29], v[218:221], v[182:185], v[26:29]
	v_mfma_f32_16x16x32_bf16 v[30:33], v[222:225], v[182:185], v[30:33]
	v_mfma_f32_16x16x32_bf16 v[34:37], v[210:213], v[186:189], v[34:37]
	ds_read_b128 v[162:165], v241 offset:0
	v_mfma_f32_16x16x32_bf16 v[38:41], v[214:217], v[186:189], v[38:41]
	ds_read_b128 v[166:169], v241 offset:256
	v_mfma_f32_16x16x32_bf16 v[42:45], v[218:221], v[186:189], v[42:45]
	ds_read_b128 v[170:173], v241 offset:2048
	v_mfma_f32_16x16x32_bf16 v[46:49], v[222:225], v[186:189], v[46:49]
	ds_read_b128 v[174:177], v241 offset:2304
	v_mfma_f32_16x16x32_bf16 v[50:53], v[210:213], v[190:193], v[50:53]
	ds_read_b128 v[130:133], v240 offset:0
	v_mfma_f32_16x16x32_bf16 v[54:57], v[214:217], v[190:193], v[54:57]
	ds_read_b128 v[134:137], v240 offset:1024
	v_mfma_f32_16x16x32_bf16 v[58:61], v[218:221], v[190:193], v[58:61]
	ds_read_b128 v[138:141], v240 offset:2048
	v_mfma_f32_16x16x32_bf16 v[62:65], v[222:225], v[190:193], v[62:65]
	ds_read_b128 v[142:145], v240 offset:3072
	v_mfma_f32_16x16x32_bf16 v[66:69], v[210:213], v[194:197], v[66:69]
	ds_read_b128 v[146:149], v240 offset:4096
	v_mfma_f32_16x16x32_bf16 v[70:73], v[214:217], v[194:197], v[70:73]
	ds_read_b128 v[150:153], v240 offset:5120
	v_mfma_f32_16x16x32_bf16 v[74:77], v[218:221], v[194:197], v[74:77]
	ds_read_b128 v[154:157], v240 offset:6144
	v_mfma_f32_16x16x32_bf16 v[78:81], v[222:225], v[194:197], v[78:81]
	ds_read_b128 v[158:161], v240 offset:7168
	v_mfma_f32_16x16x32_bf16 v[82:85], v[210:213], v[198:201], v[82:85]
	v_mfma_f32_16x16x32_bf16 v[86:89], v[214:217], v[198:201], v[86:89]
	v_mfma_f32_16x16x32_bf16 v[90:93], v[218:221], v[198:201], v[90:93]
	v_mfma_f32_16x16x32_bf16 v[94:97], v[222:225], v[198:201], v[94:97]
	v_mfma_f32_16x16x32_bf16 v[98:101], v[210:213], v[202:205], v[98:101]
	v_mfma_f32_16x16x32_bf16 v[102:105], v[214:217], v[202:205], v[102:105]
	v_mfma_f32_16x16x32_bf16 v[106:109], v[218:221], v[202:205], v[106:109]
	v_mfma_f32_16x16x32_bf16 v[110:113], v[222:225], v[202:205], v[110:113]
	v_mfma_f32_16x16x32_bf16 v[114:117], v[210:213], v[206:209], v[114:117]
	v_mfma_f32_16x16x32_bf16 v[118:121], v[214:217], v[206:209], v[118:121]
	v_mfma_f32_16x16x32_bf16 v[122:125], v[218:221], v[206:209], v[122:125]
	v_mfma_f32_16x16x32_bf16 v[126:129], v[222:225], v[206:209], v[126:129]
	s_setprio 0
	s_add_i32 s61, s61, 0x6000
	s_cmp_eq_u32 s61, 0x12000
	s_cselect_b32 s61, 0, s61
	s_waitcnt vmcnt(0) lgkmcnt(0)
	v_add_u32_e32 v240, s61, v238
	v_add_u32_e32 v241, s61, v239
	s_setprio 1
	v_mfma_f32_16x16x32_bf16 v[2:5], v[162:165], v[130:133], v[2:5]
	v_mfma_f32_16x16x32_bf16 v[6:9], v[166:169], v[130:133], v[6:9]
	v_mfma_f32_16x16x32_bf16 v[10:13], v[170:173], v[130:133], v[10:13]
	v_mfma_f32_16x16x32_bf16 v[14:17], v[174:177], v[130:133], v[14:17]
	s_barrier
	v_mfma_f32_16x16x32_bf16 v[18:21], v[162:165], v[134:137], v[18:21]
	v_mfma_f32_16x16x32_bf16 v[22:25], v[166:169], v[134:137], v[22:25]
	v_mfma_f32_16x16x32_bf16 v[26:29], v[170:173], v[134:137], v[26:29]
	v_mfma_f32_16x16x32_bf16 v[30:33], v[174:177], v[134:137], v[30:33]
	v_mfma_f32_16x16x32_bf16 v[34:37], v[162:165], v[138:141], v[34:37]
	ds_read_b128 v[210:213], v241 offset:0
	v_mfma_f32_16x16x32_bf16 v[38:41], v[166:169], v[138:141], v[38:41]
	ds_read_b128 v[214:217], v241 offset:256
	v_mfma_f32_16x16x32_bf16 v[42:45], v[170:173], v[138:141], v[42:45]
	ds_read_b128 v[218:221], v241 offset:2048
	v_mfma_f32_16x16x32_bf16 v[46:49], v[174:177], v[138:141], v[46:49]
	ds_read_b128 v[222:225], v241 offset:2304
	v_mfma_f32_16x16x32_bf16 v[50:53], v[162:165], v[142:145], v[50:53]
	ds_read_b128 v[178:181], v240 offset:0
	v_mfma_f32_16x16x32_bf16 v[54:57], v[166:169], v[142:145], v[54:57]
	ds_read_b128 v[182:185], v240 offset:1024
	v_mfma_f32_16x16x32_bf16 v[58:61], v[170:173], v[142:145], v[58:61]
	ds_read_b128 v[186:189], v240 offset:2048
	v_mfma_f32_16x16x32_bf16 v[62:65], v[174:177], v[142:145], v[62:65]
	ds_read_b128 v[190:193], v240 offset:3072
	v_mfma_f32_16x16x32_bf16 v[66:69], v[162:165], v[146:149], v[66:69]
	ds_read_b128 v[194:197], v240 offset:4096
	v_mfma_f32_16x16x32_bf16 v[70:73], v[166:169], v[146:149], v[70:73]
	ds_read_b128 v[198:201], v240 offset:5120
	v_mfma_f32_16x16x32_bf16 v[74:77], v[170:173], v[146:149], v[74:77]
	ds_read_b128 v[202:205], v240 offset:6144
	v_mfma_f32_16x16x32_bf16 v[78:81], v[174:177], v[146:149], v[78:81]
	ds_read_b128 v[206:209], v240 offset:7168
	v_mfma_f32_16x16x32_bf16 v[82:85], v[162:165], v[150:153], v[82:85]
	v_mfma_f32_16x16x32_bf16 v[86:89], v[166:169], v[150:153], v[86:89]
	v_mfma_f32_16x16x32_bf16 v[90:93], v[170:173], v[150:153], v[90:93]
	v_mfma_f32_16x16x32_bf16 v[94:97], v[174:177], v[150:153], v[94:97]
	v_mfma_f32_16x16x32_bf16 v[98:101], v[162:165], v[154:157], v[98:101]
	v_mfma_f32_16x16x32_bf16 v[102:105], v[166:169], v[154:157], v[102:105]
	v_mfma_f32_16x16x32_bf16 v[106:109], v[170:173], v[154:157], v[106:109]
	v_mfma_f32_16x16x32_bf16 v[110:113], v[174:177], v[154:157], v[110:113]
	v_mfma_f32_16x16x32_bf16 v[114:117], v[162:165], v[158:161], v[114:117]
	v_mfma_f32_16x16x32_bf16 v[118:121], v[166:169], v[158:161], v[118:121]
	v_mfma_f32_16x16x32_bf16 v[122:125], v[170:173], v[158:161], v[122:125]
	v_mfma_f32_16x16x32_bf16 v[126:129], v[174:177], v[158:161], v[126:129]
	s_setprio 0
	s_add_i32 s61, s61, 0x6000
	s_cmp_eq_u32 s61, 0x12000
	s_cselect_b32 s61, 0, s61
	s_waitcnt lgkmcnt(0)
	s_setprio 1
	v_mfma_f32_16x16x32_bf16 v[2:5], v[210:213], v[178:181], v[2:5]
	v_mfma_f32_16x16x32_bf16 v[6:9], v[214:217], v[178:181], v[6:9]
	v_mfma_f32_16x16x32_bf16 v[10:13], v[218:221], v[178:181], v[10:13]
	v_mfma_f32_16x16x32_bf16 v[14:17], v[222:225], v[178:181], v[14:17]
	s_barrier
	v_mfma_f32_16x16x32_bf16 v[18:21], v[210:213], v[182:185], v[18:21]
	v_mfma_f32_16x16x32_bf16 v[22:25], v[214:217], v[182:185], v[22:25]
	v_mfma_f32_16x16x32_bf16 v[26:29], v[218:221], v[182:185], v[26:29]
	v_mfma_f32_16x16x32_bf16 v[30:33], v[222:225], v[182:185], v[30:33]
	v_mfma_f32_16x16x32_bf16 v[34:37], v[210:213], v[186:189], v[34:37]
	v_mfma_f32_16x16x32_bf16 v[38:41], v[214:217], v[186:189], v[38:41]
	v_mfma_f32_16x16x32_bf16 v[42:45], v[218:221], v[186:189], v[42:45]
	v_mfma_f32_16x16x32_bf16 v[46:49], v[222:225], v[186:189], v[46:49]
	v_mfma_f32_16x16x32_bf16 v[50:53], v[210:213], v[190:193], v[50:53]
	v_mfma_f32_16x16x32_bf16 v[54:57], v[214:217], v[190:193], v[54:57]
	v_mfma_f32_16x16x32_bf16 v[58:61], v[218:221], v[190:193], v[58:61]
	v_mfma_f32_16x16x32_bf16 v[62:65], v[222:225], v[190:193], v[62:65]
	v_mfma_f32_16x16x32_bf16 v[66:69], v[210:213], v[194:197], v[66:69]
	v_mfma_f32_16x16x32_bf16 v[70:73], v[214:217], v[194:197], v[70:73]
	v_mfma_f32_16x16x32_bf16 v[74:77], v[218:221], v[194:197], v[74:77]
	v_mfma_f32_16x16x32_bf16 v[78:81], v[222:225], v[194:197], v[78:81]
	v_mfma_f32_16x16x32_bf16 v[82:85], v[210:213], v[198:201], v[82:85]
	v_mfma_f32_16x16x32_bf16 v[86:89], v[214:217], v[198:201], v[86:89]
	v_mfma_f32_16x16x32_bf16 v[90:93], v[218:221], v[198:201], v[90:93]
	v_mfma_f32_16x16x32_bf16 v[94:97], v[222:225], v[198:201], v[94:97]
	v_mfma_f32_16x16x32_bf16 v[98:101], v[210:213], v[202:205], v[98:101]
	v_mfma_f32_16x16x32_bf16 v[102:105], v[214:217], v[202:205], v[102:105]
	v_mfma_f32_16x16x32_bf16 v[106:109], v[218:221], v[202:205], v[106:109]
	v_mfma_f32_16x16x32_bf16 v[110:113], v[222:225], v[202:205], v[110:113]
	v_mfma_f32_16x16x32_bf16 v[114:117], v[210:213], v[206:209], v[114:117]
	v_mfma_f32_16x16x32_bf16 v[118:121], v[214:217], v[206:209], v[118:121]
	v_mfma_f32_16x16x32_bf16 v[122:125], v[218:221], v[206:209], v[122:125]
	v_mfma_f32_16x16x32_bf16 v[126:129], v[222:225], v[206:209], v[126:129]
	s_setprio 0
	s_and_b32 s39, s35, 0xfff
	s_lshr_b32 s21, s36, 7
	s_waitcnt vmcnt(0)
	v_mbcnt_lo_u32_b32 v217, -1, 0
	v_mbcnt_hi_u32_b32 v217, -1, v217
	v_lshlrev_b32_e32 v217, 5, v217
	s_lshl_b32 s26, s43, 11
	v_add_u32_e32 v248, s26, v217
	s_add_i32 s26, s26, 0x12010
	v_add_u32_e32 v217, s26, v217
	s_cmp_eq_u32 s42, 0
	s_cbranch_scc0 .Lup_el_nowr
	ds_write_b128 v217, v[114:117]
	ds_write_b128 v217, v[118:121] offset:16
	s_branch .Lup_el_wrd

.Lpj_nn_a:
	s_waitcnt vmcnt(6) lgkmcnt(0)
	v_add_u32_e32 v240, s61, v238
	v_add_u32_e32 v241, s61, v239
	s_setprio 1
	v_mfma_f32_16x16x32_bf16 v[2:5], v[162:165], v[130:133], 0
	v_mfma_f32_16x16x32_bf16 v[6:9], v[166:169], v[130:133], 0
	v_mfma_f32_16x16x32_bf16 v[10:13], v[170:173], v[130:133], 0
	v_mfma_f32_16x16x32_bf16 v[14:17], v[174:177], v[130:133], 0
	s_barrier
	v_mfma_f32_16x16x32_bf16 v[18:21], v[162:165], v[134:137], 0
	s_add_i32 m0, s60, s62
	v_mfma_f32_16x16x32_bf16 v[22:25], v[166:169], v[134:137], 0
	global_load_lds_dwordx4 v226, s[54:55]
	v_mfma_f32_16x16x32_bf16 v[26:29], v[170:173], v[134:137], 0
	v_mfma_f32_16x16x32_bf16 v[30:33], v[174:177], v[134:137], 0
	v_mfma_f32_16x16x32_bf16 v[34:37], v[162:165], v[138:141], 0
	ds_read_b128 v[210:213], v241 offset:0
	v_mfma_f32_16x16x32_bf16 v[38:41], v[166:169], v[138:141], 0
	ds_read_b128 v[214:217], v241 offset:256
	v_mfma_f32_16x16x32_bf16 v[42:45], v[170:173], v[138:141], 0
	ds_read_b128 v[218:221], v241 offset:2048
	global_load_lds_dwordx4 v226, s[54:55] offset:1024
	v_mfma_f32_16x16x32_bf16 v[46:49], v[174:177], v[138:141], 0
	ds_read_b128 v[222:225], v241 offset:2304
	v_mfma_f32_16x16x32_bf16 v[50:53], v[162:165], v[142:145], 0
	ds_read_b128 v[178:181], v240 offset:0
	v_mfma_f32_16x16x32_bf16 v[54:57], v[166:169], v[142:145], 0
	ds_read_b128 v[182:185], v240 offset:1024
	v_mfma_f32_16x16x32_bf16 v[58:61], v[170:173], v[142:145], 0
	ds_read_b128 v[186:189], v240 offset:2048
	v_mfma_f32_16x16x32_bf16 v[62:65], v[174:177], v[142:145], 0
	ds_read_b128 v[190:193], v240 offset:3072
	global_load_lds_dwordx4 v226, s[54:55] offset:2048
	v_mfma_f32_16x16x32_bf16 v[66:69], v[162:165], v[146:149], 0
	ds_read_b128 v[194:197], v240 offset:4096
	v_mfma_f32_16x16x32_bf16 v[70:73], v[166:169], v[146:149], 0
	ds_read_b128 v[198:201], v240 offset:5120
	v_mfma_f32_16x16x32_bf16 v[74:77], v[170:173], v[146:149], 0
	ds_read_b128 v[202:205], v240 offset:6144
	v_mfma_f32_16x16x32_bf16 v[78:81], v[174:177], v[146:149], 0
	ds_read_b128 v[206:209], v240 offset:7168
	v_mfma_f32_16x16x32_bf16 v[82:85], v[162:165], v[150:153], 0
	global_load_lds_dwordx4 v226, s[54:55] offset:3072
	v_mfma_f32_16x16x32_bf16 v[86:89], v[166:169], v[150:153], 0
	v_mfma_f32_16x16x32_bf16 v[90:93], v[170:173], v[150:153], 0
	v_mfma_f32_16x16x32_bf16 v[94:97], v[174:177], v[150:153], 0
	v_mfma_f32_16x16x32_bf16 v[98:101], v[162:165], v[154:157], 0
	s_add_i32 m0, s60, s63
	v_mfma_f32_16x16x32_bf16 v[102:105], v[166:169], v[154:157], 0
	global_load_lds_dwordx4 v230, s[56:57]
	v_mfma_f32_16x16x32_bf16 v[106:109], v[170:173], v[154:157], 0
	v_mfma_f32_16x16x32_bf16 v[110:113], v[174:177], v[154:157], 0
	v_mfma_f32_16x16x32_bf16 v[114:117], v[162:165], v[158:161], 0
	v_mfma_f32_16x16x32_bf16 v[118:121], v[166:169], v[158:161], 0
	v_mfma_f32_16x16x32_bf16 v[122:125], v[170:173], v[158:161], 0
	global_load_lds_dwordx4 v231, s[56:57] offset:1024
	v_mfma_f32_16x16x32_bf16 v[126:129], v[174:177], v[158:161], 0
	s_setprio 0
	s_add_i32 s60, s60, 0x6000
	s_cmp_eq_u32 s60, 0x12000
	s_cselect_b32 s60, 0, s60
	s_add_u32 s54, s54, s72
	s_addc_u32 s55, s55, 0
	s_add_u32 s56, s56, s73
	s_addc_u32 s57, s57, 0
	s_add_i32 s61, s61, 0x6000
	s_cmp_eq_u32 s61, 0x12000
	s_cselect_b32 s61, 0, s61
	s_waitcnt vmcnt(6) lgkmcnt(0)
	v_add_u32_e32 v240, s61, v238
	v_add_u32_e32 v241, s61, v239
	s_setprio 1
	v_mfma_f32_16x16x32_bf16 v[2:5], v[210:213], v[178:181], v[2:5]
	v_mfma_f32_16x16x32_bf16 v[6:9], v[214:217], v[178:181], v[6:9]
	v_mfma_f32_16x16x32_bf16 v[10:13], v[218:221], v[178:181], v[10:13]
	v_mfma_f32_16x16x32_bf16 v[14:17], v[222:225], v[178:181], v[14:17]
	s_barrier
	v_mfma_f32_16x16x32_bf16 v[18:21], v[210:213], v[182:185], v[18:21]
	s_add_i32 m0, s60, s62
	v_mfma_f32_16x16x32_bf16 v[22:25], v[214:217], v[182:185], v[22:25]
	global_load_lds_dwordx4 v226, s[54:55]
	v_mfma_f32_16x16x32_bf16 v[26:29], v[218:221], v[182:185], v[26:29]
	v_mfma_f32_16x16x32_bf16 v[30:33], v[222:225], v[182:185], v[30:33]
	v_mfma_f32_16x16x32_bf16 v[34:37], v[210:213], v[186:189], v[34:37]
	ds_read_b128 v[162:165], v241 offset:0
	v_mfma_f32_16x16x32_bf16 v[38:41], v[214:217], v[186:189], v[38:41]
	ds_read_b128 v[166:169], v241 offset:256
	v_mfma_f32_16x16x32_bf16 v[42:45], v[218:221], v[186:189], v[42:45]
	ds_read_b128 v[170:173], v241 offset:2048
	global_load_lds_dwordx4 v226, s[54:55] offset:1024
	v_mfma_f32_16x16x32_bf16 v[46:49], v[222:225], v[186:189], v[46:49]
	ds_read_b128 v[174:177], v241 offset:2304
	v_mfma_f32_16x16x32_bf16 v[50:53], v[210:213], v[190:193], v[50:53]
	ds_read_b128 v[130:133], v240 offset:0
	v_mfma_f32_16x16x32_bf16 v[54:57], v[214:217], v[190:193], v[54:57]
	ds_read_b128 v[134:137], v240 offset:1024
	v_mfma_f32_16x16x32_bf16 v[58:61], v[218:221], v[190:193], v[58:61]
	ds_read_b128 v[138:141], v240 offset:2048
	v_mfma_f32_16x16x32_bf16 v[62:65], v[222:225], v[190:193], v[62:65]
	ds_read_b128 v[142:145], v240 offset:3072
	global_load_lds_dwordx4 v226, s[54:55] offset:2048
	v_mfma_f32_16x16x32_bf16 v[66:69], v[210:213], v[194:197], v[66:69]
	ds_read_b128 v[146:149], v240 offset:4096
	v_mfma_f32_16x16x32_bf16 v[70:73], v[214:217], v[194:197], v[70:73]
	ds_read_b128 v[150:153], v240 offset:5120
	v_mfma_f32_16x16x32_bf16 v[74:77], v[218:221], v[194:197], v[74:77]
	ds_read_b128 v[154:157], v240 offset:6144
	v_mfma_f32_16x16x32_bf16 v[78:81], v[222:225], v[194:197], v[78:81]
	ds_read_b128 v[158:161], v240 offset:7168
	v_mfma_f32_16x16x32_bf16 v[82:85], v[210:213], v[198:201], v[82:85]
	global_load_lds_dwordx4 v226, s[54:55] offset:3072
	v_mfma_f32_16x16x32_bf16 v[86:89], v[214:217], v[198:201], v[86:89]
	v_mfma_f32_16x16x32_bf16 v[90:93], v[218:221], v[198:201], v[90:93]
	v_mfma_f32_16x16x32_bf16 v[94:97], v[222:225], v[198:201], v[94:97]
	v_mfma_f32_16x16x32_bf16 v[98:101], v[210:213], v[202:205], v[98:101]
	s_add_i32 m0, s60, s63
	v_mfma_f32_16x16x32_bf16 v[102:105], v[214:217], v[202:205], v[102:105]
	global_load_lds_dwordx4 v230, s[56:57]
	v_mfma_f32_16x16x32_bf16 v[106:109], v[218:221], v[202:205], v[106:109]
	v_mfma_f32_16x16x32_bf16 v[110:113], v[222:225], v[202:205], v[110:113]
	v_mfma_f32_16x16x32_bf16 v[114:117], v[210:213], v[206:209], v[114:117]
	v_mfma_f32_16x16x32_bf16 v[118:121], v[214:217], v[206:209], v[118:121]
	v_mfma_f32_16x16x32_bf16 v[122:125], v[218:221], v[206:209], v[122:125]
	global_load_lds_dwordx4 v231, s[56:57] offset:1024
	v_mfma_f32_16x16x32_bf16 v[126:129], v[222:225], v[206:209], v[126:129]
	s_setprio 0
	s_add_i32 s60, s60, 0x6000
	s_cmp_eq_u32 s60, 0x12000
	s_cselect_b32 s60, 0, s60
	s_add_u32 s54, s54, s72
	s_addc_u32 s55, s55, 0
	s_add_u32 s56, s56, s73
	s_addc_u32 s57, s57, 0
	s_add_i32 s61, s61, 0x6000
	s_cmp_eq_u32 s61, 0x12000
	s_cselect_b32 s61, 0, s61
	s_branch .Lpj_main

.Lpj_nn_b:
	s_waitcnt vmcnt(63) lgkmcnt(0)
	v_add_u32_e32 v240, s61, v238
	v_add_u32_e32 v241, s61, v239
	s_setprio 1
	v_mfma_f32_16x16x32_bf16 v[2:5], v[162:165], v[130:133], 0
	v_mfma_f32_16x16x32_bf16 v[6:9], v[166:169], v[130:133], 0
	v_mfma_f32_16x16x32_bf16 v[10:13], v[170:173], v[130:133], 0
	v_mfma_f32_16x16x32_bf16 v[14:17], v[174:177], v[130:133], 0
	s_barrier
	v_mfma_f32_16x16x32_bf16 v[18:21], v[162:165], v[134:137], 0
	s_add_i32 m0, s60, s62
	v_mfma_f32_16x16x32_bf16 v[22:25], v[166:169], v[134:137], 0
	global_load_lds_dwordx4 v226, s[54:55]
	v_mfma_f32_16x16x32_bf16 v[26:29], v[170:173], v[134:137], 0
	v_mfma_f32_16x16x32_bf16 v[30:33], v[174:177], v[134:137], 0
	v_mfma_f32_16x16x32_bf16 v[34:37], v[162:165], v[138:141], 0
	ds_read_b128 v[210:213], v241 offset:0
	v_mfma_f32_16x16x32_bf16 v[38:41], v[166:169], v[138:141], 0
	ds_read_b128 v[214:217], v241 offset:256
	v_mfma_f32_16x16x32_bf16 v[42:45], v[170:173], v[138:141], 0
	ds_read_b128 v[218:221], v241 offset:2048
	global_load_lds_dwordx4 v226, s[54:55] offset:1024
	v_mfma_f32_16x16x32_bf16 v[46:49], v[174:177], v[138:141], 0
	ds_read_b128 v[222:225], v241 offset:2304
	v_mfma_f32_16x16x32_bf16 v[50:53], v[162:165], v[142:145], 0
	ds_read_b128 v[178:181], v240 offset:0
	v_mfma_f32_16x16x32_bf16 v[54:57], v[166:169], v[142:145], 0
	ds_read_b128 v[182:185], v240 offset:1024
	v_mfma_f32_16x16x32_bf16 v[58:61], v[170:173], v[142:145], 0
	ds_read_b128 v[186:189], v240 offset:2048
	v_mfma_f32_16x16x32_bf16 v[62:65], v[174:177], v[142:145], 0
	ds_read_b128 v[190:193], v240 offset:3072
	global_load_lds_dwordx4 v226, s[54:55] offset:2048
	v_mfma_f32_16x16x32_bf16 v[66:69], v[162:165], v[146:149], 0
	ds_read_b128 v[194:197], v240 offset:4096
	v_mfma_f32_16x16x32_bf16 v[70:73], v[166:169], v[146:149], 0
	ds_read_b128 v[198:201], v240 offset:5120
	v_mfma_f32_16x16x32_bf16 v[74:77], v[170:173], v[146:149], 0
	ds_read_b128 v[202:205], v240 offset:6144
	v_mfma_f32_16x16x32_bf16 v[78:81], v[174:177], v[146:149], 0
	ds_read_b128 v[206:209], v240 offset:7168
	v_mfma_f32_16x16x32_bf16 v[82:85], v[162:165], v[150:153], 0
	global_load_lds_dwordx4 v226, s[54:55] offset:3072
	v_mfma_f32_16x16x32_bf16 v[86:89], v[166:169], v[150:153], 0
	v_mfma_f32_16x16x32_bf16 v[90:93], v[170:173], v[150:153], 0
	v_mfma_f32_16x16x32_bf16 v[94:97], v[174:177], v[150:153], 0
	v_mfma_f32_16x16x32_bf16 v[98:101], v[162:165], v[154:157], 0
	s_add_i32 m0, s60, s63
	v_mfma_f32_16x16x32_bf16 v[102:105], v[166:169], v[154:157], 0
	global_load_lds_dwordx4 v230, s[56:57]
	v_mfma_f32_16x16x32_bf16 v[106:109], v[170:173], v[154:157], 0
	v_mfma_f32_16x16x32_bf16 v[110:113], v[174:177], v[154:157], 0
	v_mfma_f32_16x16x32_bf16 v[114:117], v[162:165], v[158:161], 0
	v_mfma_f32_16x16x32_bf16 v[118:121], v[166:169], v[158:161], 0
	v_mfma_f32_16x16x32_bf16 v[122:125], v[170:173], v[158:161], 0
	global_load_lds_dwordx4 v231, s[56:57] offset:1024
	v_mfma_f32_16x16x32_bf16 v[126:129], v[174:177], v[158:161], 0
	s_setprio 0
	s_add_i32 s60, s60, 0x6000
	s_cmp_eq_u32 s60, 0x12000
	s_cselect_b32 s60, 0, s60
	s_add_u32 s54, s54, s72
	s_addc_u32 s55, s55, 0
	s_add_u32 s56, s56, s73
	s_addc_u32 s57, s57, 0
	s_add_i32 s61, s61, 0x6000
	s_cmp_eq_u32 s61, 0x12000
	s_cselect_b32 s61, 0, s61
	s_waitcnt vmcnt(63) lgkmcnt(0)
	v_add_u32_e32 v240, s61, v238
	v_add_u32_e32 v241, s61, v239
	s_setprio 1
	v_mfma_f32_16x16x32_bf16 v[2:5], v[210:213], v[178:181], v[2:5]
	v_mfma_f32_16x16x32_bf16 v[6:9], v[214:217], v[178:181], v[6:9]
	v_mfma_f32_16x16x32_bf16 v[10:13], v[218:221], v[178:181], v[10:13]
	v_mfma_f32_16x16x32_bf16 v[14:17], v[222:225], v[178:181], v[14:17]
	s_barrier
	v_mfma_f32_16x16x32_bf16 v[18:21], v[210:213], v[182:185], v[18:21]
	s_add_i32 m0, s60, s62
	v_mfma_f32_16x16x32_bf16 v[22:25], v[214:217], v[182:185], v[22:25]
	global_load_lds_dwordx4 v226, s[54:55]
	v_mfma_f32_16x16x32_bf16 v[26:29], v[218:221], v[182:185], v[26:29]
	v_mfma_f32_16x16x32_bf16 v[30:33], v[222:225], v[182:185], v[30:33]
	v_mfma_f32_16x16x32_bf16 v[34:37], v[210:213], v[186:189], v[34:37]
	ds_read_b128 v[162:165], v241 offset:0
	v_mfma_f32_16x16x32_bf16 v[38:41], v[214:217], v[186:189], v[38:41]
	ds_read_b128 v[166:169], v241 offset:256
	v_mfma_f32_16x16x32_bf16 v[42:45], v[218:221], v[186:189], v[42:45]
	ds_read_b128 v[170:173], v241 offset:2048
	global_load_lds_dwordx4 v226, s[54:55] offset:1024
	v_mfma_f32_16x16x32_bf16 v[46:49], v[222:225], v[186:189], v[46:49]
	ds_read_b128 v[174:177], v241 offset:2304
	v_mfma_f32_16x16x32_bf16 v[50:53], v[210:213], v[190:193], v[50:53]
	ds_read_b128 v[130:133], v240 offset:0
	v_mfma_f32_16x16x32_bf16 v[54:57], v[214:217], v[190:193], v[54:57]
	ds_read_b128 v[134:137], v240 offset:1024
	v_mfma_f32_16x16x32_bf16 v[58:61], v[218:221], v[190:193], v[58:61]
	ds_read_b128 v[138:141], v240 offset:2048
	v_mfma_f32_16x16x32_bf16 v[62:65], v[222:225], v[190:193], v[62:65]
	ds_read_b128 v[142:145], v240 offset:3072
	global_load_lds_dwordx4 v226, s[54:55] offset:2048
	v_mfma_f32_16x16x32_bf16 v[66:69], v[210:213], v[194:197], v[66:69]
	ds_read_b128 v[146:149], v240 offset:4096
	v_mfma_f32_16x16x32_bf16 v[70:73], v[214:217], v[194:197], v[70:73]
	ds_read_b128 v[150:153], v240 offset:5120
	v_mfma_f32_16x16x32_bf16 v[74:77], v[218:221], v[194:197], v[74:77]
	ds_read_b128 v[154:157], v240 offset:6144
	v_mfma_f32_16x16x32_bf16 v[78:81], v[222:225], v[194:197], v[78:81]
	ds_read_b128 v[158:161], v240 offset:7168
	v_mfma_f32_16x16x32_bf16 v[82:85], v[210:213], v[198:201], v[82:85]
	global_load_lds_dwordx4 v226, s[54:55] offset:3072
	v_mfma_f32_16x16x32_bf16 v[86:89], v[214:217], v[198:201], v[86:89]
	v_mfma_f32_16x16x32_bf16 v[90:93], v[218:221], v[198:201], v[90:93]
	v_mfma_f32_16x16x32_bf16 v[94:97], v[222:225], v[198:201], v[94:97]
	v_mfma_f32_16x16x32_bf16 v[98:101], v[210:213], v[202:205], v[98:101]
	s_add_i32 m0, s60, s63
	v_mfma_f32_16x16x32_bf16 v[102:105], v[214:217], v[202:205], v[102:105]
	global_load_lds_dwordx4 v230, s[56:57]
	v_mfma_f32_16x16x32_bf16 v[106:109], v[218:221], v[202:205], v[106:109]
	v_mfma_f32_16x16x32_bf16 v[110:113], v[222:225], v[202:205], v[110:113]
	v_mfma_f32_16x16x32_bf16 v[114:117], v[210:213], v[206:209], v[114:117]
	v_mfma_f32_16x16x32_bf16 v[118:121], v[214:217], v[206:209], v[118:121]
	v_mfma_f32_16x16x32_bf16 v[122:125], v[218:221], v[206:209], v[122:125]
	global_load_lds_dwordx4 v231, s[56:57] offset:1024
	v_mfma_f32_16x16x32_bf16 v[126:129], v[222:225], v[206:209], v[126:129]
	s_setprio 0
	s_add_i32 s60, s60, 0x6000
	s_cmp_eq_u32 s60, 0x12000
	s_cselect_b32 s60, 0, s60
	s_add_u32 s54, s54, s72
	s_addc_u32 s55, s55, 0
	s_add_u32 s56, s56, s73
	s_addc_u32 s57, s57, 0
	s_add_i32 s61, s61, 0x6000
	s_cmp_eq_u32 s61, 0x12000
	s_cselect_b32 s61, 0, s61

.Lpj_kdone:
	s_cmp_eq_u32 s37, 0
	s_cbranch_scc1 .Lpj_tail_last
	s_waitcnt vmcnt(6) lgkmcnt(0)
	v_add_u32_e32 v240, s61, v238
	v_add_u32_e32 v241, s61, v239
	s_setprio 1
	v_mfma_f32_16x16x32_bf16 v[2:5], v[162:165], v[130:133], v[2:5]
	v_mfma_f32_16x16x32_bf16 v[6:9], v[166:169], v[130:133], v[6:9]
	v_mfma_f32_16x16x32_bf16 v[10:13], v[170:173], v[130:133], v[10:13]
	v_mfma_f32_16x16x32_bf16 v[14:17], v[174:177], v[130:133], v[14:17]
	s_barrier
	v_mfma_f32_16x16x32_bf16 v[18:21], v[162:165], v[134:137], v[18:21]
	s_add_i32 m0, s60, s62
	v_mfma_f32_16x16x32_bf16 v[22:25], v[166:169], v[134:137], v[22:25]
	global_load_lds_dwordx4 v226, s[54:55]
	v_mfma_f32_16x16x32_bf16 v[26:29], v[170:173], v[134:137], v[26:29]
	v_mfma_f32_16x16x32_bf16 v[30:33], v[174:177], v[134:137], v[30:33]
	v_mfma_f32_16x16x32_bf16 v[34:37], v[162:165], v[138:141], v[34:37]
	ds_read_b128 v[210:213], v241 offset:0
	v_mfma_f32_16x16x32_bf16 v[38:41], v[166:169], v[138:141], v[38:41]
	ds_read_b128 v[214:217], v241 offset:256
	v_mfma_f32_16x16x32_bf16 v[42:45], v[170:173], v[138:141], v[42:45]
	ds_read_b128 v[218:221], v241 offset:2048
	global_load_lds_dwordx4 v226, s[54:55] offset:1024
	v_mfma_f32_16x16x32_bf16 v[46:49], v[174:177], v[138:141], v[46:49]
	ds_read_b128 v[222:225], v241 offset:2304
	v_mfma_f32_16x16x32_bf16 v[50:53], v[162:165], v[142:145], v[50:53]
	ds_read_b128 v[178:181], v240 offset:0
	v_mfma_f32_16x16x32_bf16 v[54:57], v[166:169], v[142:145], v[54:57]
	ds_read_b128 v[182:185], v240 offset:1024
	v_mfma_f32_16x16x32_bf16 v[58:61], v[170:173], v[142:145], v[58:61]
	ds_read_b128 v[186:189], v240 offset:2048
	v_mfma_f32_16x16x32_bf16 v[62:65], v[174:177], v[142:145], v[62:65]
	ds_read_b128 v[190:193], v240 offset:3072
	global_load_lds_dwordx4 v226, s[54:55] offset:2048
	v_mfma_f32_16x16x32_bf16 v[66:69], v[162:165], v[146:149], v[66:69]
	ds_read_b128 v[194:197], v240 offset:4096
	v_mfma_f32_16x16x32_bf16 v[70:73], v[166:169], v[146:149], v[70:73]
	ds_read_b128 v[198:201], v240 offset:5120
	v_mfma_f32_16x16x32_bf16 v[74:77], v[170:173], v[146:149], v[74:77]
	ds_read_b128 v[202:205], v240 offset:6144
	v_mfma_f32_16x16x32_bf16 v[78:81], v[174:177], v[146:149], v[78:81]
	ds_read_b128 v[206:209], v240 offset:7168
	v_mfma_f32_16x16x32_bf16 v[82:85], v[162:165], v[150:153], v[82:85]
	global_load_lds_dwordx4 v226, s[54:55] offset:3072
	v_mfma_f32_16x16x32_bf16 v[86:89], v[166:169], v[150:153], v[86:89]
	v_mfma_f32_16x16x32_bf16 v[90:93], v[170:173], v[150:153], v[90:93]
	v_mfma_f32_16x16x32_bf16 v[94:97], v[174:177], v[150:153], v[94:97]
	v_mfma_f32_16x16x32_bf16 v[98:101], v[162:165], v[154:157], v[98:101]
	s_add_i32 m0, s60, s63
	v_mfma_f32_16x16x32_bf16 v[102:105], v[166:169], v[154:157], v[102:105]
	global_load_lds_dwordx4 v230, s[56:57]
	v_mfma_f32_16x16x32_bf16 v[106:109], v[170:173], v[154:157], v[106:109]
	v_mfma_f32_16x16x32_bf16 v[110:113], v[174:177], v[154:157], v[110:113]
	v_mfma_f32_16x16x32_bf16 v[114:117], v[162:165], v[158:161], v[114:117]
	v_mfma_f32_16x16x32_bf16 v[118:121], v[166:169], v[158:161], v[118:121]
	v_mfma_f32_16x16x32_bf16 v[122:125], v[170:173], v[158:161], v[122:125]
	global_load_lds_dwordx4 v231, s[56:57] offset:1024
	v_mfma_f32_16x16x32_bf16 v[126:129], v[174:177], v[158:161], v[126:129]
	s_setprio 0
	s_add_i32 s60, s60, 0x6000
	s_cmp_eq_u32 s60, 0x12000
	s_cselect_b32 s60, 0, s60
	s_add_u32 s54, s54, s72
	s_addc_u32 s55, s55, 0
	s_add_u32 s56, s56, s73
	s_addc_u32 s57, s57, 0
	s_add_i32 s61, s61, 0x6000
	s_cmp_eq_u32 s61, 0x12000
	s_cselect_b32 s61, 0, s61
	v_mov_b32_e32 v226, v232
	v_mov_b32_e32 v230, v236
	v_mov_b32_e32 v231, v237
	s_mov_b64 s[54:55], s[48:49]
	s_mov_b64 s[56:57], s[50:51]
	s_waitcnt vmcnt(6) lgkmcnt(0)
	v_add_u32_e32 v240, s61, v238
	v_add_u32_e32 v241, s61, v239
	s_setprio 1
	v_mfma_f32_16x16x32_bf16 v[2:5], v[210:213], v[178:181], v[2:5]
	v_mfma_f32_16x16x32_bf16 v[6:9], v[214:217], v[178:181], v[6:9]
	v_mfma_f32_16x16x32_bf16 v[10:13], v[218:221], v[178:181], v[10:13]
	v_mfma_f32_16x16x32_bf16 v[14:17], v[222:225], v[178:181], v[14:17]
	s_barrier
	v_mfma_f32_16x16x32_bf16 v[18:21], v[210:213], v[182:185], v[18:21]
	s_add_i32 m0, s60, s62
	v_mfma_f32_16x16x32_bf16 v[22:25], v[214:217], v[182:185], v[22:25]
	global_load_lds_dwordx4 v226, s[54:55]
	v_mfma_f32_16x16x32_bf16 v[26:29], v[218:221], v[182:185], v[26:29]
	v_mfma_f32_16x16x32_bf16 v[30:33], v[222:225], v[182:185], v[30:33]
	v_mfma_f32_16x16x32_bf16 v[34:37], v[210:213], v[186:189], v[34:37]
	ds_read_b128 v[162:165], v241 offset:0
	v_mfma_f32_16x16x32_bf16 v[38:41], v[214:217], v[186:189], v[38:41]
	ds_read_b128 v[166:169], v241 offset:256
	v_mfma_f32_16x16x32_bf16 v[42:45], v[218:221], v[186:189], v[42:45]
	ds_read_b128 v[170:173], v241 offset:2048
	global_load_lds_dwordx4 v226, s[54:55] offset:1024
	v_mfma_f32_16x16x32_bf16 v[46:49], v[222:225], v[186:189], v[46:49]
	ds_read_b128 v[174:177], v241 offset:2304
	v_mfma_f32_16x16x32_bf16 v[50:53], v[210:213], v[190:193], v[50:53]
	ds_read_b128 v[130:133], v240 offset:0
	v_mfma_f32_16x16x32_bf16 v[54:57], v[214:217], v[190:193], v[54:57]
	ds_read_b128 v[134:137], v240 offset:1024
	v_mfma_f32_16x16x32_bf16 v[58:61], v[218:221], v[190:193], v[58:61]
	ds_read_b128 v[138:141], v240 offset:2048
	v_mfma_f32_16x16x32_bf16 v[62:65], v[222:225], v[190:193], v[62:65]
	ds_read_b128 v[142:145], v240 offset:3072
	global_load_lds_dwordx4 v226, s[54:55] offset:2048
	v_mfma_f32_16x16x32_bf16 v[66:69], v[210:213], v[194:197], v[66:69]
	ds_read_b128 v[146:149], v240 offset:4096
	v_mfma_f32_16x16x32_bf16 v[70:73], v[214:217], v[194:197], v[70:73]
	ds_read_b128 v[150:153], v240 offset:5120
	v_mfma_f32_16x16x32_bf16 v[74:77], v[218:221], v[194:197], v[74:77]
	ds_read_b128 v[154:157], v240 offset:6144
	v_mfma_f32_16x16x32_bf16 v[78:81], v[222:225], v[194:197], v[78:81]
	ds_read_b128 v[158:161], v240 offset:7168
	v_mfma_f32_16x16x32_bf16 v[82:85], v[210:213], v[198:201], v[82:85]
	global_load_lds_dwordx4 v226, s[54:55] offset:3072
	v_mfma_f32_16x16x32_bf16 v[86:89], v[214:217], v[198:201], v[86:89]
	v_mfma_f32_16x16x32_bf16 v[90:93], v[218:221], v[198:201], v[90:93]
	v_mfma_f32_16x16x32_bf16 v[94:97], v[222:225], v[198:201], v[94:97]
	v_mfma_f32_16x16x32_bf16 v[98:101], v[210:213], v[202:205], v[98:101]
	s_add_i32 m0, s60, s63
	v_mfma_f32_16x16x32_bf16 v[102:105], v[214:217], v[202:205], v[102:105]
	global_load_lds_dwordx4 v230, s[56:57]
	v_mfma_f32_16x16x32_bf16 v[106:109], v[218:221], v[202:205], v[106:109]
	v_mfma_f32_16x16x32_bf16 v[110:113], v[222:225], v[202:205], v[110:113]
	v_mfma_f32_16x16x32_bf16 v[114:117], v[210:213], v[206:209], v[114:117]
	v_mfma_f32_16x16x32_bf16 v[118:121], v[214:217], v[206:209], v[118:121]
	v_mfma_f32_16x16x32_bf16 v[122:125], v[218:221], v[206:209], v[122:125]
	global_load_lds_dwordx4 v231, s[56:57] offset:1024
	v_mfma_f32_16x16x32_bf16 v[126:129], v[222:225], v[206:209], v[126:129]
	s_setprio 0
	s_add_i32 s60, s60, 0x6000
	s_cmp_eq_u32 s60, 0x12000
	s_cselect_b32 s60, 0, s60
	s_add_u32 s54, s54, s72
	s_addc_u32 s55, s55, 0
	s_add_u32 s56, s56, s73
	s_addc_u32 s57, s57, 0
	s_add_i32 s61, s61, 0x6000
	s_cmp_eq_u32 s61, 0x12000
	s_cselect_b32 s61, 0, s61
	s_waitcnt vmcnt(6) lgkmcnt(0)
	v_add_u32_e32 v240, s61, v238
	v_add_u32_e32 v241, s61, v239
	s_setprio 1
	v_mfma_f32_16x16x32_bf16 v[2:5], v[162:165], v[130:133], v[2:5]
	v_mfma_f32_16x16x32_bf16 v[6:9], v[166:169], v[130:133], v[6:9]
	v_mfma_f32_16x16x32_bf16 v[10:13], v[170:173], v[130:133], v[10:13]
	v_mfma_f32_16x16x32_bf16 v[14:17], v[174:177], v[130:133], v[14:17]
	s_barrier
	v_mfma_f32_16x16x32_bf16 v[18:21], v[162:165], v[134:137], v[18:21]
	s_add_i32 m0, s60, s62
	v_mfma_f32_16x16x32_bf16 v[22:25], v[166:169], v[134:137], v[22:25]
	global_load_lds_dwordx4 v226, s[54:55]
	v_mfma_f32_16x16x32_bf16 v[26:29], v[170:173], v[134:137], v[26:29]
	v_mfma_f32_16x16x32_bf16 v[30:33], v[174:177], v[134:137], v[30:33]
	v_mfma_f32_16x16x32_bf16 v[34:37], v[162:165], v[138:141], v[34:37]
	ds_read_b128 v[210:213], v241 offset:0
	v_mfma_f32_16x16x32_bf16 v[38:41], v[166:169], v[138:141], v[38:41]
	ds_read_b128 v[214:217], v241 offset:256
	v_mfma_f32_16x16x32_bf16 v[42:45], v[170:173], v[138:141], v[42:45]
	ds_read_b128 v[218:221], v241 offset:2048
	global_load_lds_dwordx4 v226, s[54:55] offset:1024
	v_mfma_f32_16x16x32_bf16 v[46:49], v[174:177], v[138:141], v[46:49]
	ds_read_b128 v[222:225], v241 offset:2304
	v_mfma_f32_16x16x32_bf16 v[50:53], v[162:165], v[142:145], v[50:53]
	ds_read_b128 v[178:181], v240 offset:0
	v_mfma_f32_16x16x32_bf16 v[54:57], v[166:169], v[142:145], v[54:57]
	ds_read_b128 v[182:185], v240 offset:1024
	v_mfma_f32_16x16x32_bf16 v[58:61], v[170:173], v[142:145], v[58:61]
	ds_read_b128 v[186:189], v240 offset:2048
	v_mfma_f32_16x16x32_bf16 v[62:65], v[174:177], v[142:145], v[62:65]
	ds_read_b128 v[190:193], v240 offset:3072
	global_load_lds_dwordx4 v226, s[54:55] offset:2048
	v_mfma_f32_16x16x32_bf16 v[66:69], v[162:165], v[146:149], v[66:69]
	ds_read_b128 v[194:197], v240 offset:4096
	v_mfma_f32_16x16x32_bf16 v[70:73], v[166:169], v[146:149], v[70:73]
	ds_read_b128 v[198:201], v240 offset:5120
	v_mfma_f32_16x16x32_bf16 v[74:77], v[170:173], v[146:149], v[74:77]
	ds_read_b128 v[202:205], v240 offset:6144
	v_mfma_f32_16x16x32_bf16 v[78:81], v[174:177], v[146:149], v[78:81]
	ds_read_b128 v[206:209], v240 offset:7168
	v_mfma_f32_16x16x32_bf16 v[82:85], v[162:165], v[150:153], v[82:85]
	global_load_lds_dwordx4 v226, s[54:55] offset:3072
	v_mfma_f32_16x16x32_bf16 v[86:89], v[166:169], v[150:153], v[86:89]
	v_mfma_f32_16x16x32_bf16 v[90:93], v[170:173], v[150:153], v[90:93]
	v_mfma_f32_16x16x32_bf16 v[94:97], v[174:177], v[150:153], v[94:97]
	v_mfma_f32_16x16x32_bf16 v[98:101], v[162:165], v[154:157], v[98:101]
	s_add_i32 m0, s60, s63
	v_mfma_f32_16x16x32_bf16 v[102:105], v[166:169], v[154:157], v[102:105]
	global_load_lds_dwordx4 v230, s[56:57]
	v_mfma_f32_16x16x32_bf16 v[106:109], v[170:173], v[154:157], v[106:109]
	v_mfma_f32_16x16x32_bf16 v[110:113], v[174:177], v[154:157], v[110:113]
	v_mfma_f32_16x16x32_bf16 v[114:117], v[162:165], v[158:161], v[114:117]
	v_mfma_f32_16x16x32_bf16 v[118:121], v[166:169], v[158:161], v[118:121]
	v_mfma_f32_16x16x32_bf16 v[122:125], v[170:173], v[158:161], v[122:125]
	global_load_lds_dwordx4 v231, s[56:57] offset:1024
	v_mfma_f32_16x16x32_bf16 v[126:129], v[174:177], v[158:161], v[126:129]
	s_setprio 0
	s_add_i32 s60, s60, 0x6000
	s_cmp_eq_u32 s60, 0x12000
	s_cselect_b32 s60, 0, s60
	s_add_u32 s54, s54, s72
	s_addc_u32 s55, s55, 0
	s_add_u32 s56, s56, s73
	s_addc_u32 s57, s57, 0
	s_add_i32 s61, s61, 0x6000
	s_cmp_eq_u32 s61, 0x12000
	s_cselect_b32 s61, 0, s61
	s_waitcnt vmcnt(6) lgkmcnt(0)
	v_add_u32_e32 v240, s61, v238
	v_add_u32_e32 v241, s61, v239
	s_setprio 1
	v_mfma_f32_16x16x32_bf16 v[2:5], v[210:213], v[178:181], v[2:5]
	v_mfma_f32_16x16x32_bf16 v[6:9], v[214:217], v[178:181], v[6:9]
	v_mfma_f32_16x16x32_bf16 v[10:13], v[218:221], v[178:181], v[10:13]
	v_mfma_f32_16x16x32_bf16 v[14:17], v[222:225], v[178:181], v[14:17]
	s_barrier
	v_mfma_f32_16x16x32_bf16 v[18:21], v[210:213], v[182:185], v[18:21]
	s_add_i32 m0, s60, s62
	v_mfma_f32_16x16x32_bf16 v[22:25], v[214:217], v[182:185], v[22:25]
	global_load_lds_dwordx4 v226, s[54:55]
	v_mfma_f32_16x16x32_bf16 v[26:29], v[218:221], v[182:185], v[26:29]
	v_mfma_f32_16x16x32_bf16 v[30:33], v[222:225], v[182:185], v[30:33]
	v_mfma_f32_16x16x32_bf16 v[34:37], v[210:213], v[186:189], v[34:37]
	ds_read_b128 v[162:165], v241 offset:0
	v_mfma_f32_16x16x32_bf16 v[38:41], v[214:217], v[186:189], v[38:41]
	ds_read_b128 v[166:169], v241 offset:256
	v_mfma_f32_16x16x32_bf16 v[42:45], v[218:221], v[186:189], v[42:45]
	ds_read_b128 v[170:173], v241 offset:2048
	global_load_lds_dwordx4 v226, s[54:55] offset:1024
	v_mfma_f32_16x16x32_bf16 v[46:49], v[222:225], v[186:189], v[46:49]
	ds_read_b128 v[174:177], v241 offset:2304
	v_mfma_f32_16x16x32_bf16 v[50:53], v[210:213], v[190:193], v[50:53]
	ds_read_b128 v[130:133], v240 offset:0
	v_mfma_f32_16x16x32_bf16 v[54:57], v[214:217], v[190:193], v[54:57]
	ds_read_b128 v[134:137], v240 offset:1024
	v_mfma_f32_16x16x32_bf16 v[58:61], v[218:221], v[190:193], v[58:61]
	ds_read_b128 v[138:141], v240 offset:2048
	v_mfma_f32_16x16x32_bf16 v[62:65], v[222:225], v[190:193], v[62:65]
	ds_read_b128 v[142:145], v240 offset:3072
	global_load_lds_dwordx4 v226, s[54:55] offset:2048
	v_mfma_f32_16x16x32_bf16 v[66:69], v[210:213], v[194:197], v[66:69]
	ds_read_b128 v[146:149], v240 offset:4096
	v_mfma_f32_16x16x32_bf16 v[70:73], v[214:217], v[194:197], v[70:73]
	ds_read_b128 v[150:153], v240 offset:5120
	v_mfma_f32_16x16x32_bf16 v[74:77], v[218:221], v[194:197], v[74:77]
	ds_read_b128 v[154:157], v240 offset:6144
	v_mfma_f32_16x16x32_bf16 v[78:81], v[222:225], v[194:197], v[78:81]
	ds_read_b128 v[158:161], v240 offset:7168
	v_mfma_f32_16x16x32_bf16 v[82:85], v[210:213], v[198:201], v[82:85]
	global_load_lds_dwordx4 v226, s[54:55] offset:3072
	v_mfma_f32_16x16x32_bf16 v[86:89], v[214:217], v[198:201], v[86:89]
	v_mfma_f32_16x16x32_bf16 v[90:93], v[218:221], v[198:201], v[90:93]
	v_mfma_f32_16x16x32_bf16 v[94:97], v[222:225], v[198:201], v[94:97]
	v_mfma_f32_16x16x32_bf16 v[98:101], v[210:213], v[202:205], v[98:101]
	s_add_i32 m0, s60, s63
	v_mfma_f32_16x16x32_bf16 v[102:105], v[214:217], v[202:205], v[102:105]
	global_load_lds_dwordx4 v230, s[56:57]
	v_mfma_f32_16x16x32_bf16 v[106:109], v[218:221], v[202:205], v[106:109]
	v_mfma_f32_16x16x32_bf16 v[110:113], v[222:225], v[202:205], v[110:113]
	v_mfma_f32_16x16x32_bf16 v[114:117], v[210:213], v[206:209], v[114:117]
	v_mfma_f32_16x16x32_bf16 v[118:121], v[214:217], v[206:209], v[118:121]
	v_mfma_f32_16x16x32_bf16 v[122:125], v[218:221], v[206:209], v[122:125]
	global_load_lds_dwordx4 v231, s[56:57] offset:1024
	v_mfma_f32_16x16x32_bf16 v[126:129], v[222:225], v[206:209], v[126:129]
	s_setprio 0
	s_add_i32 s60, s60, 0x6000
	s_cmp_eq_u32 s60, 0x12000
	s_cselect_b32 s60, 0, s60
	s_add_u32 s54, s54, s72
	s_addc_u32 s55, s55, 0
	s_add_u32 s56, s56, s73
	s_addc_u32 s57, s57, 0
	s_add_i32 s61, s61, 0x6000
	s_cmp_eq_u32 s61, 0x12000
	s_cselect_b32 s61, 0, s61
	s_branch .Lpj_epi

.Lpj_tail_last:
	s_waitcnt vmcnt(6) lgkmcnt(0)
	v_add_u32_e32 v240, s61, v238
	v_add_u32_e32 v241, s61, v239
	s_setprio 1
	v_mfma_f32_16x16x32_bf16 v[2:5], v[162:165], v[130:133], v[2:5]
	v_mfma_f32_16x16x32_bf16 v[6:9], v[166:169], v[130:133], v[6:9]
	v_mfma_f32_16x16x32_bf16 v[10:13], v[170:173], v[130:133], v[10:13]
	v_mfma_f32_16x16x32_bf16 v[14:17], v[174:177], v[130:133], v[14:17]
	s_barrier
	v_mfma_f32_16x16x32_bf16 v[18:21], v[162:165], v[134:137], v[18:21]
	s_add_i32 m0, s60, s62
	v_mfma_f32_16x16x32_bf16 v[22:25], v[166:169], v[134:137], v[22:25]
	global_load_lds_dwordx4 v226, s[54:55]
	v_mfma_f32_16x16x32_bf16 v[26:29], v[170:173], v[134:137], v[26:29]
	v_mfma_f32_16x16x32_bf16 v[30:33], v[174:177], v[134:137], v[30:33]
	v_mfma_f32_16x16x32_bf16 v[34:37], v[162:165], v[138:141], v[34:37]
	ds_read_b128 v[210:213], v241 offset:0
	v_mfma_f32_16x16x32_bf16 v[38:41], v[166:169], v[138:141], v[38:41]
	ds_read_b128 v[214:217], v241 offset:256
	v_mfma_f32_16x16x32_bf16 v[42:45], v[170:173], v[138:141], v[42:45]
	ds_read_b128 v[218:221], v241 offset:2048
	global_load_lds_dwordx4 v226, s[54:55] offset:1024
	v_mfma_f32_16x16x32_bf16 v[46:49], v[174:177], v[138:141], v[46:49]
	ds_read_b128 v[222:225], v241 offset:2304
	v_mfma_f32_16x16x32_bf16 v[50:53], v[162:165], v[142:145], v[50:53]
	ds_read_b128 v[178:181], v240 offset:0
	v_mfma_f32_16x16x32_bf16 v[54:57], v[166:169], v[142:145], v[54:57]
	ds_read_b128 v[182:185], v240 offset:1024
	v_mfma_f32_16x16x32_bf16 v[58:61], v[170:173], v[142:145], v[58:61]
	ds_read_b128 v[186:189], v240 offset:2048
	v_mfma_f32_16x16x32_bf16 v[62:65], v[174:177], v[142:145], v[62:65]
	ds_read_b128 v[190:193], v240 offset:3072
	global_load_lds_dwordx4 v226, s[54:55] offset:2048
	v_mfma_f32_16x16x32_bf16 v[66:69], v[162:165], v[146:149], v[66:69]
	ds_read_b128 v[194:197], v240 offset:4096
	v_mfma_f32_16x16x32_bf16 v[70:73], v[166:169], v[146:149], v[70:73]
	ds_read_b128 v[198:201], v240 offset:5120
	v_mfma_f32_16x16x32_bf16 v[74:77], v[170:173], v[146:149], v[74:77]
	ds_read_b128 v[202:205], v240 offset:6144
	v_mfma_f32_16x16x32_bf16 v[78:81], v[174:177], v[146:149], v[78:81]
	ds_read_b128 v[206:209], v240 offset:7168
	v_mfma_f32_16x16x32_bf16 v[82:85], v[162:165], v[150:153], v[82:85]
	global_load_lds_dwordx4 v226, s[54:55] offset:3072
	v_mfma_f32_16x16x32_bf16 v[86:89], v[166:169], v[150:153], v[86:89]
	v_mfma_f32_16x16x32_bf16 v[90:93], v[170:173], v[150:153], v[90:93]
	v_mfma_f32_16x16x32_bf16 v[94:97], v[174:177], v[150:153], v[94:97]
	v_mfma_f32_16x16x32_bf16 v[98:101], v[162:165], v[154:157], v[98:101]
	s_add_i32 m0, s60, s63
	v_mfma_f32_16x16x32_bf16 v[102:105], v[166:169], v[154:157], v[102:105]
	global_load_lds_dwordx4 v230, s[56:57]
	v_mfma_f32_16x16x32_bf16 v[106:109], v[170:173], v[154:157], v[106:109]
	v_mfma_f32_16x16x32_bf16 v[110:113], v[174:177], v[154:157], v[110:113]
	v_mfma_f32_16x16x32_bf16 v[114:117], v[162:165], v[158:161], v[114:117]
	v_mfma_f32_16x16x32_bf16 v[118:121], v[166:169], v[158:161], v[118:121]
	v_mfma_f32_16x16x32_bf16 v[122:125], v[170:173], v[158:161], v[122:125]
	global_load_lds_dwordx4 v231, s[56:57] offset:1024
	v_mfma_f32_16x16x32_bf16 v[126:129], v[174:177], v[158:161], v[126:129]
	s_setprio 0
	s_add_i32 s60, s60, 0x6000
	s_cmp_eq_u32 s60, 0x12000
	s_cselect_b32 s60, 0, s60
	s_add_u32 s54, s54, s72
	s_addc_u32 s55, s55, 0
	s_add_u32 s56, s56, s73
	s_addc_u32 s57, s57, 0
	s_add_i32 s61, s61, 0x6000
	s_cmp_eq_u32 s61, 0x12000
	s_cselect_b32 s61, 0, s61
	s_waitcnt vmcnt(6) lgkmcnt(0)
	v_add_u32_e32 v240, s61, v238
	v_add_u32_e32 v241, s61, v239
	s_setprio 1
	v_mfma_f32_16x16x32_bf16 v[2:5], v[210:213], v[178:181], v[2:5]
	v_mfma_f32_16x16x32_bf16 v[6:9], v[214:217], v[178:181], v[6:9]
	v_mfma_f32_16x16x32_bf16 v[10:13], v[218:221], v[178:181], v[10:13]
	v_mfma_f32_16x16x32_bf16 v[14:17], v[222:225], v[178:181], v[14:17]
	s_barrier
	v_mfma_f32_16x16x32_bf16 v[18:21], v[210:213], v[182:185], v[18:21]
	v_mfma_f32_16x16x32_bf16 v[22:25], v[214:217], v[182:185], v[22:25]
	v_mfma_f32_16x16x32_bf16 v[26:29], v[218:221], v[182:185], v[26:29]
	v_mfma_f32_16x16x32_bf16 v[30:33], v[222:225], v[182:185], v[30:33]
	v_mfma_f32_16x16x32_bf16 v[34:37], v[210:213], v[186:189], v[34:37]
	ds_read_b128 v[162:165], v241 offset:0
	v_mfma_f32_16x16x32_bf16 v[38:41], v[214:217], v[186:189], v[38:41]
	ds_read_b128 v[166:169], v241 offset:256
	v_mfma_f32_16x16x32_bf16 v[42:45], v[218:221], v[186:189], v[42:45]
	ds_read_b128 v[170:173], v241 offset:2048
	v_mfma_f32_16x16x32_bf16 v[46:49], v[222:225], v[186:189], v[46:49]
	ds_read_b128 v[174:177], v241 offset:2304
	v_mfma_f32_16x16x32_bf16 v[50:53], v[210:213], v[190:193], v[50:53]
	ds_read_b128 v[130:133], v240 offset:0
	v_mfma_f32_16x16x32_bf16 v[54:57], v[214:217], v[190:193], v[54:57]
	ds_read_b128 v[134:137], v240 offset:1024
	v_mfma_f32_16x16x32_bf16 v[58:61], v[218:221], v[190:193], v[58:61]
	ds_read_b128 v[138:141], v240 offset:2048
	v_mfma_f32_16x16x32_bf16 v[62:65], v[222:225], v[190:193], v[62:65]
	ds_read_b128 v[142:145], v240 offset:3072
	v_mfma_f32_16x16x32_bf16 v[66:69], v[210:213], v[194:197], v[66:69]
	ds_read_b128 v[146:149], v240 offset:4096
	v_mfma_f32_16x16x32_bf16 v[70:73], v[214:217], v[194:197], v[70:73]
	ds_read_b128 v[150:153], v240 offset:5120
	v_mfma_f32_16x16x32_bf16 v[74:77], v[218:221], v[194:197], v[74:77]
	ds_read_b128 v[154:157], v240 offset:6144
	v_mfma_f32_16x16x32_bf16 v[78:81], v[222:225], v[194:197], v[78:81]
	ds_read_b128 v[158:161], v240 offset:7168
	v_mfma_f32_16x16x32_bf16 v[82:85], v[210:213], v[198:201], v[82:85]
	v_mfma_f32_16x16x32_bf16 v[86:89], v[214:217], v[198:201], v[86:89]
	v_mfma_f32_16x16x32_bf16 v[90:93], v[218:221], v[198:201], v[90:93]
	v_mfma_f32_16x16x32_bf16 v[94:97], v[222:225], v[198:201], v[94:97]
	v_mfma_f32_16x16x32_bf16 v[98:101], v[210:213], v[202:205], v[98:101]
	v_mfma_f32_16x16x32_bf16 v[102:105], v[214:217], v[202:205], v[102:105]
	v_mfma_f32_16x16x32_bf16 v[106:109], v[218:221], v[202:205], v[106:109]
	v_mfma_f32_16x16x32_bf16 v[110:113], v[222:225], v[202:205], v[110:113]
	v_mfma_f32_16x16x32_bf16 v[114:117], v[210:213], v[206:209], v[114:117]
	v_mfma_f32_16x16x32_bf16 v[118:121], v[214:217], v[206:209], v[118:121]
	v_mfma_f32_16x16x32_bf16 v[122:125], v[218:221], v[206:209], v[122:125]
	v_mfma_f32_16x16x32_bf16 v[126:129], v[222:225], v[206:209], v[126:129]
	s_setprio 0
	s_add_i32 s61, s61, 0x6000
	s_cmp_eq_u32 s61, 0x12000
	s_cselect_b32 s61, 0, s61
	s_waitcnt vmcnt(0) lgkmcnt(0)
	v_add_u32_e32 v240, s61, v238
	v_add_u32_e32 v241, s61, v239
	s_setprio 1
	v_mfma_f32_16x16x32_bf16 v[2:5], v[162:165], v[130:133], v[2:5]
	v_mfma_f32_16x16x32_bf16 v[6:9], v[166:169], v[130:133], v[6:9]
	v_mfma_f32_16x16x32_bf16 v[10:13], v[170:173], v[130:133], v[10:13]
	v_mfma_f32_16x16x32_bf16 v[14:17], v[174:177], v[130:133], v[14:17]
	s_barrier
	v_mfma_f32_16x16x32_bf16 v[18:21], v[162:165], v[134:137], v[18:21]
	v_mfma_f32_16x16x32_bf16 v[22:25], v[166:169], v[134:137], v[22:25]
	v_mfma_f32_16x16x32_bf16 v[26:29], v[170:173], v[134:137], v[26:29]
	v_mfma_f32_16x16x32_bf16 v[30:33], v[174:177], v[134:137], v[30:33]
	v_mfma_f32_16x16x32_bf16 v[34:37], v[162:165], v[138:141], v[34:37]
	ds_read_b128 v[210:213], v241 offset:0
	v_mfma_f32_16x16x32_bf16 v[38:41], v[166:169], v[138:141], v[38:41]
	ds_read_b128 v[214:217], v241 offset:256
	v_mfma_f32_16x16x32_bf16 v[42:45], v[170:173], v[138:141], v[42:45]
	ds_read_b128 v[218:221], v241 offset:2048
	v_mfma_f32_16x16x32_bf16 v[46:49], v[174:177], v[138:141], v[46:49]
	ds_read_b128 v[222:225], v241 offset:2304
	v_mfma_f32_16x16x32_bf16 v[50:53], v[162:165], v[142:145], v[50:53]
	ds_read_b128 v[178:181], v240 offset:0
	v_mfma_f32_16x16x32_bf16 v[54:57], v[166:169], v[142:145], v[54:57]
	ds_read_b128 v[182:185], v240 offset:1024
	v_mfma_f32_16x16x32_bf16 v[58:61], v[170:173], v[142:145], v[58:61]
	ds_read_b128 v[186:189], v240 offset:2048
	v_mfma_f32_16x16x32_bf16 v[62:65], v[174:177], v[142:145], v[62:65]
	ds_read_b128 v[190:193], v240 offset:3072
	v_mfma_f32_16x16x32_bf16 v[66:69], v[162:165], v[146:149], v[66:69]
	ds_read_b128 v[194:197], v240 offset:4096
	v_mfma_f32_16x16x32_bf16 v[70:73], v[166:169], v[146:149], v[70:73]
	ds_read_b128 v[198:201], v240 offset:5120
	v_mfma_f32_16x16x32_bf16 v[74:77], v[170:173], v[146:149], v[74:77]
	ds_read_b128 v[202:205], v240 offset:6144
	v_mfma_f32_16x16x32_bf16 v[78:81], v[174:177], v[146:149], v[78:81]
	ds_read_b128 v[206:209], v240 offset:7168
	v_mfma_f32_16x16x32_bf16 v[82:85], v[162:165], v[150:153], v[82:85]
	v_mfma_f32_16x16x32_bf16 v[86:89], v[166:169], v[150:153], v[86:89]
	v_mfma_f32_16x16x32_bf16 v[90:93], v[170:173], v[150:153], v[90:93]
	v_mfma_f32_16x16x32_bf16 v[94:97], v[174:177], v[150:153], v[94:97]
	v_mfma_f32_16x16x32_bf16 v[98:101], v[162:165], v[154:157], v[98:101]
	v_mfma_f32_16x16x32_bf16 v[102:105], v[166:169], v[154:157], v[102:105]
	v_mfma_f32_16x16x32_bf16 v[106:109], v[170:173], v[154:157], v[106:109]
	v_mfma_f32_16x16x32_bf16 v[110:113], v[174:177], v[154:157], v[110:113]
	v_mfma_f32_16x16x32_bf16 v[114:117], v[162:165], v[158:161], v[114:117]
	v_mfma_f32_16x16x32_bf16 v[118:121], v[166:169], v[158:161], v[118:121]
	v_mfma_f32_16x16x32_bf16 v[122:125], v[170:173], v[158:161], v[122:125]
	v_mfma_f32_16x16x32_bf16 v[126:129], v[174:177], v[158:161], v[126:129]
	s_setprio 0
	s_add_i32 s61, s61, 0x6000
	s_cmp_eq_u32 s61, 0x12000
	s_cselect_b32 s61, 0, s61
	s_waitcnt lgkmcnt(0)
	s_setprio 1
	v_mfma_f32_16x16x32_bf16 v[2:5], v[210:213], v[178:181], v[2:5]
	v_mfma_f32_16x16x32_bf16 v[6:9], v[214:217], v[178:181], v[6:9]
	v_mfma_f32_16x16x32_bf16 v[10:13], v[218:221], v[178:181], v[10:13]
	v_mfma_f32_16x16x32_bf16 v[14:17], v[222:225], v[178:181], v[14:17]
	s_barrier
	v_mfma_f32_16x16x32_bf16 v[18:21], v[210:213], v[182:185], v[18:21]
	v_mfma_f32_16x16x32_bf16 v[22:25], v[214:217], v[182:185], v[22:25]
	v_mfma_f32_16x16x32_bf16 v[26:29], v[218:221], v[182:185], v[26:29]
	v_mfma_f32_16x16x32_bf16 v[30:33], v[222:225], v[182:185], v[30:33]
	v_mfma_f32_16x16x32_bf16 v[34:37], v[210:213], v[186:189], v[34:37]
	v_mfma_f32_16x16x32_bf16 v[38:41], v[214:217], v[186:189], v[38:41]
	v_mfma_f32_16x16x32_bf16 v[42:45], v[218:221], v[186:189], v[42:45]
	v_mfma_f32_16x16x32_bf16 v[46:49], v[222:225], v[186:189], v[46:49]
	v_mfma_f32_16x16x32_bf16 v[50:53], v[210:213], v[190:193], v[50:53]
	v_mfma_f32_16x16x32_bf16 v[54:57], v[214:217], v[190:193], v[54:57]
	v_mfma_f32_16x16x32_bf16 v[58:61], v[218:221], v[190:193], v[58:61]
	v_mfma_f32_16x16x32_bf16 v[62:65], v[222:225], v[190:193], v[62:65]
	v_mfma_f32_16x16x32_bf16 v[66:69], v[210:213], v[194:197], v[66:69]
	v_mfma_f32_16x16x32_bf16 v[70:73], v[214:217], v[194:197], v[70:73]
	v_mfma_f32_16x16x32_bf16 v[74:77], v[218:221], v[194:197], v[74:77]
	v_mfma_f32_16x16x32_bf16 v[78:81], v[222:225], v[194:197], v[78:81]
	v_mfma_f32_16x16x32_bf16 v[82:85], v[210:213], v[198:201], v[82:85]
	v_mfma_f32_16x16x32_bf16 v[86:89], v[214:217], v[198:201], v[86:89]
	v_mfma_f32_16x16x32_bf16 v[90:93], v[218:221], v[198:201], v[90:93]
	v_mfma_f32_16x16x32_bf16 v[94:97], v[222:225], v[198:201], v[94:97]
	v_mfma_f32_16x16x32_bf16 v[98:101], v[210:213], v[202:205], v[98:101]
	v_mfma_f32_16x16x32_bf16 v[102:105], v[214:217], v[202:205], v[102:105]
	v_mfma_f32_16x16x32_bf16 v[106:109], v[218:221], v[202:205], v[106:109]
	v_mfma_f32_16x16x32_bf16 v[110:113], v[222:225], v[202:205], v[110:113]
	v_mfma_f32_16x16x32_bf16 v[114:117], v[210:213], v[206:209], v[114:117]
	v_mfma_f32_16x16x32_bf16 v[118:121], v[214:217], v[206:209], v[118:121]
	v_mfma_f32_16x16x32_bf16 v[122:125], v[218:221], v[206:209], v[122:125]
	v_mfma_f32_16x16x32_bf16 v[126:129], v[222:225], v[206:209], v[126:129]
	s_setprio 0
